# MLA loop pipelined + batched gla_scan + f32 v_rcp instead of IEEE division sequences in sigmoid/silu epilogues (in-proj gates, conv, gla_out)
# speedup vs baseline: 1.0391x; 1.0113x over previous
; __device__ __forceinline__ u32x4 pack8(const float* v) { u32x4 w; w.x = pk2(v[0], v[1]); w.y = pk2(v[2], v[3]); w.z = pk2(v[4], v[5]); w.w = pk2(v[6], v[7]); return w; }
; __device__ __forceinline__ void unpack8(u32x4 w, float* v) { v[0] = bflo(w.x); v[1] = bfhi(w.x); v[2] = bflo(w.y); v[3] = bfhi(w.y); v[4] = bflo(w.z); v[5] = bfhi(w.z); v[6] = bflo(w.w); v[7] = bfhi(w.w); }
; __device__ __forceinline__ float siluf_(float x) { return x / (1.f + __expf(-x)); }
; __global__ void __launch_bounds__(NTHR, 2) mk_fwd(Args args) {
;     ...
;                     for (int r = 0; r < 16; ++r) {
;                         u32x4 gn_ = (u32x4){0u, 0u, 0u, 0u}, vn_ = (u32x4){0u, 0u, 0u, 0u};
;                         const int ii = i0 + r;
;                         if (ii != LC - 1 && ii != TB - 1) { gn_ = *(const u32x4*)(up + (size_t)(r + 1) * FF2); vn_ = *(const u32x4*)(up + (size_t)(r + 1) * FF2 + FF); }
;                         float gm[8], gc[8], gn[8], vm[8], vc[8], vn[8], o[8];
;                         unpack8(gp_, gm); unpack8(gc_, gc); unpack8(gn_, gn); unpack8(vp_, vm); unpack8(vc_, vc); unpack8(vn_, vn);
; #pragma unroll
;                         for (int e = 0; e < 8; ++e) {
;                             const float a = wg0[e] * gm[e] + wg1[e] * gc[e] + wg2[e] * gn[e] + bg[e];
;                             const float v = wv0[e] * vm[e] + wv1[e] * vc[e] + wv2[e] * vn[e] + bv[e];
;                             o[e] = siluf_(a) * v;
;                         }
;                         *(u32x4*)(ACT + (size_t)(t0 + r) * FF + j0) = pack8(o);
;                         gp_ = gc_; vp_ = vc_; gc_ = gn_; vc_ = vn_;
;                     }
.LBB0_90:
	s_or_b64 exec, exec, s[0:1]
	v_pk_mul_f32 v[104:105], v[32:33], v[124:125]
	s_waitcnt vmcnt(1)
	v_lshlrev_b32_e32 v38, 16, v88
	v_and_b32_e32 v39, 0xffff0000, v88
	v_pk_fma_f32 v[98:99], v[4:5], v[98:99], v[104:105]
	v_pk_mul_f32 v[122:123], v[60:61], v[122:123]
	v_pk_fma_f32 v[38:39], v[48:49], v[38:39], v[98:99]
	s_waitcnt vmcnt(0)
	v_lshlrev_b32_e32 v104, 16, v84
	v_pk_add_f32 v[38:39], v[12:13], v[38:39]
	v_and_b32_e32 v105, 0xffff0000, v84
	v_mul_f32_e32 v37, 0xbfb8aa3b, v38
	v_exp_f32_e32 v98, v37
	v_mul_f32_e32 v37, 0xbfb8aa3b, v39
	v_exp_f32_e32 v99, v37
	v_pk_fma_f32 v[94:95], v[16:17], v[94:95], v[122:123]
	v_pk_mul_f32 v[106:107], v[62:63], v[106:107]
	v_pk_fma_f32 v[94:95], v[64:65], v[104:105], v[94:95]
	v_pk_add_f32 v[98:99], v[98:99], 1.0 op_sel_hi:[1,0]
	v_pk_add_f32 v[94:95], v[24:25], v[94:95]
	v_pk_fma_f32 v[106:107], v[18:19], v[110:111], v[106:107]
	v_pk_mul_f32 v[96:97], v[70:71], v[96:97]
	s_add_i32 s18, s18, 4
	v_rcp_f32_e32 v37, v99
	s_nop 0
	v_mul_f32_e32 v39, v39, v37
	v_pk_fma_f32 v[96:97], v[22:23], v[118:119], v[96:97]
	v_rcp_f32_e32 v37, v98
	s_nop 0
	v_mul_f32_e32 v38, v38, v37
	v_pk_mul_f32 v[98:99], v[34:35], v[126:127]
	v_pk_mul_f32 v[38:39], v[38:39], v[94:95]
	v_lshlrev_b32_e32 v94, 16, v89
	v_and_b32_e32 v95, 0xffff0000, v89
	v_pk_fma_f32 v[98:99], v[6:7], v[112:113], v[98:99]
	v_lshlrev_b32_e32 v104, 16, v85
	v_pk_fma_f32 v[94:95], v[50:51], v[94:95], v[98:99]
	v_and_b32_e32 v105, 0xffff0000, v85
	v_pk_add_f32 v[94:95], v[14:15], v[94:95]
	v_pk_fma_f32 v[104:105], v[66:67], v[104:105], v[106:107]
	v_mul_f32_e32 v37, 0xbfb8aa3b, v94
	v_exp_f32_e32 v98, v37
	v_mul_f32_e32 v37, 0xbfb8aa3b, v95
	v_exp_f32_e32 v99, v37
	v_pk_add_f32 v[104:105], v[26:27], v[104:105]
	s_cmp_eq_u32 s18, 16
	v_pk_add_f32 v[98:99], v[98:99], 1.0 op_sel_hi:[1,0]
	s_nop 0
	s_nop 0
	v_rcp_f32_e32 v37, v99
	s_nop 0
	v_mul_f32_e32 v95, v95, v37
	v_rcp_f32_e32 v37, v98
	s_nop 0
	v_mul_f32_e32 v94, v94, v37
	v_pk_mul_f32 v[98:99], v[94:95], v[104:105]
	v_pk_mul_f32 v[104:105], v[52:53], v[130:131]
	v_lshlrev_b32_e32 v94, 16, v90
	v_and_b32_e32 v95, 0xffff0000, v90
	v_pk_fma_f32 v[104:105], v[0:1], v[116:117], v[104:105]
	v_pk_mul_f32 v[110:111], v[68:69], v[128:129]
	v_pk_fma_f32 v[94:95], v[56:57], v[94:95], v[104:105]
	v_lshlrev_b32_e32 v106, 16, v86
	v_pk_add_f32 v[94:95], v[8:9], v[94:95]
	v_and_b32_e32 v107, 0xffff0000, v86
	v_mul_f32_e32 v37, 0xbfb8aa3b, v94
	v_exp_f32_e32 v104, v37
	v_mul_f32_e32 v37, 0xbfb8aa3b, v95
	v_exp_f32_e32 v105, v37
	v_pk_fma_f32 v[110:111], v[20:21], v[114:115], v[110:111]
	v_pk_add_f32 v[104:105], v[104:105], 1.0 op_sel_hi:[1,0]
	s_nop 0
	v_pk_fma_f32 v[106:107], v[72:73], v[106:107], v[110:111]
	v_rcp_f32_e32 v37, v105
	s_nop 0
	v_mul_f32_e32 v95, v95, v37
	v_pk_add_f32 v[106:107], v[28:29], v[106:107]
	v_rcp_f32_e32 v37, v104
	s_nop 0
	v_mul_f32_e32 v94, v94, v37
	v_pk_mul_f32 v[104:105], v[94:95], v[106:107]
	v_pk_mul_f32 v[106:107], v[54:55], v[108:109]
	v_lshlrev_b32_e32 v94, 16, v91
	v_and_b32_e32 v95, 0xffff0000, v91
	v_pk_fma_f32 v[106:107], v[2:3], v[120:121], v[106:107]
	v_lshlrev_b32_e32 v108, 16, v87
	v_pk_fma_f32 v[94:95], v[58:59], v[94:95], v[106:107]
	v_and_b32_e32 v109, 0xffff0000, v87
	v_pk_add_f32 v[94:95], v[10:11], v[94:95]
	v_pk_fma_f32 v[96:97], v[74:75], v[108:109], v[96:97]
	v_mul_f32_e32 v37, 0xbfb8aa3b, v94
	v_exp_f32_e32 v106, v37
	v_mul_f32_e32 v37, 0xbfb8aa3b, v95
	v_exp_f32_e32 v107, v37
	v_pk_add_f32 v[96:97], v[30:31], v[96:97]
	v_pk_add_f32 v[106:107], v[106:107], 1.0 op_sel_hi:[1,0]
	s_nop 0
	s_nop 0
	v_rcp_f32_e32 v37, v107
	s_nop 0
	v_mul_f32_e32 v95, v95, v37
	s_mov_b64 s[0:1], 0x5800
	v_rcp_f32_e32 v37, v106
	s_nop 0
	v_mul_f32_e32 v94, v94, v37
	v_pk_mul_f32 v[106:107], v[94:95], v[96:97]
	v_cvt_pk_bf16_f32 v94, v38, v39
	v_add_co_u32_e32 v38, vcc, 0x13f24000, v92
	v_lshl_add_u64 v[100:101], v[100:101], 0, s[0:1]
	s_mov_b64 s[0:1], 0xb000
	v_cvt_pk_bf16_f32 v95, v98, v99
	v_cvt_pk_bf16_f32 v96, v104, v105
	v_cvt_pk_bf16_f32 v97, v106, v107
	v_addc_co_u32_e32 v39, vcc, 0, v93, vcc
	v_lshl_add_u64 v[102:103], v[102:103], 0, s[0:1]
	global_store_dwordx4 v[38:39], v[94:97], off offset:512
	s_cbranch_scc1 .LBB0_86
.LBB0_91:
	v_lshl_add_u64 v[104:105], v[102:103], 0, v[42:43]
	v_add_co_u32_e32 v38, vcc, 0x89a2000, v104
	s_waitcnt vmcnt(0)
	v_lshlrev_b32_e32 v110, 16, v88
	v_addc_co_u32_e32 v39, vcc, 0, v105, vcc
	global_load_dwordx4 v[96:99], v[38:39], off offset:3072
	v_add_co_u32_e32 v38, vcc, 0x89a4000, v104
	v_and_b32_e32 v111, 0xffff0000, v88
	s_nop 0
	v_addc_co_u32_e32 v39, vcc, 0, v105, vcc
	global_load_dwordx4 v[92:95], v[38:39], off offset:512
	v_lshlrev_b32_e32 v108, 16, v80
	v_and_b32_e32 v109, 0xffff0000, v80
	v_pk_mul_f32 v[116:117], v[32:33], v[110:111]
	v_lshlrev_b32_e32 v114, 16, v76
	v_pk_fma_f32 v[108:109], v[4:5], v[108:109], v[116:117]
	v_and_b32_e32 v115, 0xffff0000, v76
	v_lshlrev_b32_e32 v112, 16, v84
	v_and_b32_e32 v113, 0xffff0000, v84
	v_pk_mul_f32 v[118:119], v[60:61], v[112:113]
	v_lshlrev_b32_e32 v120, 16, v90
	v_pk_fma_f32 v[114:115], v[16:17], v[114:115], v[118:119]
	v_lshlrev_b32_e32 v118, 16, v85
	v_and_b32_e32 v119, 0xffff0000, v85
	v_and_b32_e32 v121, 0xffff0000, v90
	v_pk_mul_f32 v[124:125], v[52:53], v[120:121]
	v_lshlrev_b32_e32 v122, 16, v86
	v_and_b32_e32 v123, 0xffff0000, v86
	v_pk_mul_f32 v[126:127], v[68:69], v[122:123]
	s_waitcnt vmcnt(1)
	v_lshlrev_b32_e32 v38, 16, v96
	v_and_b32_e32 v39, 0xffff0000, v96
	v_pk_fma_f32 v[108:109], v[48:49], v[38:39], v[108:109]
	v_lshlrev_b32_e32 v96, 16, v77
	v_pk_add_f32 v[108:109], v[12:13], v[108:109]
	s_waitcnt vmcnt(0)
; __device__ __forceinline__ u32x4 pack8(const float* v) { u32x4 w; w.x = pk2(v[0], v[1]); w.y = pk2(v[2], v[3]); w.z = pk2(v[4], v[5]); w.w = pk2(v[6], v[7]); return w; }
; __device__ __forceinline__ void unpack8(u32x4 w, float* v) { v[0] = bflo(w.x); v[1] = bfhi(w.x); v[2] = bflo(w.y); v[3] = bfhi(w.y); v[4] = bflo(w.z); v[5] = bfhi(w.z); v[6] = bflo(w.w); v[7] = bfhi(w.w); }
; __device__ __forceinline__ float siluf_(float x) { return x / (1.f + __expf(-x)); }
; __global__ void __launch_bounds__(NTHR, 2) mk_fwd(Args args) {
;     ...
;                     for (int r = 0; r < 16; ++r) {
;                         u32x4 gn_ = (u32x4){0u, 0u, 0u, 0u}, vn_ = (u32x4){0u, 0u, 0u, 0u};
;                         const int ii = i0 + r;
;                         if (ii != LC - 1 && ii != TB - 1) { gn_ = *(const u32x4*)(up + (size_t)(r + 1) * FF2); vn_ = *(const u32x4*)(up + (size_t)(r + 1) * FF2 + FF); }
;                         float gm[8], gc[8], gn[8], vm[8], vc[8], vn[8], o[8];
;                         unpack8(gp_, gm); unpack8(gc_, gc); unpack8(gn_, gn); unpack8(vp_, vm); unpack8(vc_, vc); unpack8(vn_, vn);
; #pragma unroll
;                         for (int e = 0; e < 8; ++e) {
;                             const float a = wg0[e] * gm[e] + wg1[e] * gc[e] + wg2[e] * gn[e] + bg[e];
;                             const float v = wv0[e] * vm[e] + wv1[e] * vc[e] + wv2[e] * vn[e] + bv[e];
;                             o[e] = siluf_(a) * v;
;                         }
;                         *(u32x4*)(ACT + (size_t)(t0 + r) * FF + j0) = pack8(o);
;                         gp_ = gc_; vp_ = vc_; gc_ = gn_; vc_ = vn_;
;                     }
	v_lshlrev_b32_e32 v106, 16, v92
	v_mul_f32_e32 v37, 0xbfb8aa3b, v108
	v_exp_f32_e32 v116, v37
	v_mul_f32_e32 v37, 0xbfb8aa3b, v109
	v_exp_f32_e32 v117, v37
	v_and_b32_e32 v107, 0xffff0000, v92
	v_and_b32_e32 v85, 0xffff0000, v93
	v_pk_fma_f32 v[114:115], v[64:65], v[106:107], v[114:115]
	v_pk_add_f32 v[116:117], v[116:117], 1.0 op_sel_hi:[1,0]
	v_pk_add_f32 v[114:115], v[24:25], v[114:115]
	v_pk_mul_f32 v[128:129], v[60:61], v[106:107]
	v_rcp_f32_e32 v37, v117
	s_nop 0
	v_mul_f32_e32 v109, v109, v37
	v_and_b32_e32 v117, 0xffff0000, v89
	v_pk_fma_f32 v[112:113], v[16:17], v[112:113], v[128:129]
	v_rcp_f32_e32 v37, v116
	s_nop 0
	v_mul_f32_e32 v108, v108, v37
	v_lshlrev_b32_e32 v116, 16, v89
	v_lshlrev_b32_e32 v80, 16, v81
	v_and_b32_e32 v81, 0xffff0000, v81
	v_lshlrev_b32_e32 v88, 16, v97
	v_and_b32_e32 v89, 0xffff0000, v97
	v_and_b32_e32 v97, 0xffff0000, v77
	v_pk_mul_f32 v[76:77], v[34:35], v[116:117]
	v_lshlrev_b32_e32 v84, 16, v93
	v_pk_fma_f32 v[76:77], v[6:7], v[80:81], v[76:77]
	v_pk_mul_f32 v[80:81], v[62:63], v[118:119]
	v_pk_fma_f32 v[76:77], v[50:51], v[88:89], v[76:77]
	v_pk_fma_f32 v[80:81], v[18:19], v[96:97], v[80:81]
	v_pk_add_f32 v[76:77], v[14:15], v[76:77]
	v_pk_mul_f32 v[114:115], v[108:109], v[114:115]
	v_mul_f32_e32 v37, 0xbfb8aa3b, v76
	v_exp_f32_e32 v92, v37
	v_mul_f32_e32 v37, 0xbfb8aa3b, v77
	v_exp_f32_e32 v93, v37
	v_pk_fma_f32 v[80:81], v[66:67], v[84:85], v[80:81]
	v_pk_add_f32 v[92:93], v[92:93], 1.0 op_sel_hi:[1,0]
	s_nop 0
	v_pk_add_f32 v[80:81], v[26:27], v[80:81]
	v_rcp_f32_e32 v37, v93
	s_nop 0
	v_mul_f32_e32 v77, v77, v37
	v_and_b32_e32 v109, 0xffff0000, v94
	v_rcp_f32_e32 v37, v92
	s_nop 0
	v_mul_f32_e32 v76, v76, v37
	v_pk_mul_f32 v[76:77], v[76:77], v[80:81]
	v_lshlrev_b32_e32 v80, 16, v82
	v_and_b32_e32 v81, 0xffff0000, v82
	v_lshlrev_b32_e32 v96, 16, v98
	v_and_b32_e32 v97, 0xffff0000, v98
	v_pk_fma_f32 v[80:81], v[0:1], v[80:81], v[124:125]
	v_lshlrev_b32_e32 v92, 16, v78
	v_pk_fma_f32 v[80:81], v[56:57], v[96:97], v[80:81]
	v_and_b32_e32 v93, 0xffff0000, v78
	v_pk_add_f32 v[80:81], v[8:9], v[80:81]
	v_lshlrev_b32_e32 v108, 16, v94
	v_mul_f32_e32 v37, 0xbfb8aa3b, v80
	v_exp_f32_e32 v124, v37
	v_mul_f32_e32 v37, 0xbfb8aa3b, v81
	v_exp_f32_e32 v125, v37
	v_pk_fma_f32 v[92:93], v[20:21], v[92:93], v[126:127]
	v_lshlrev_b32_e32 v126, 16, v87
	v_pk_fma_f32 v[92:93], v[72:73], v[108:109], v[92:93]
	v_pk_add_f32 v[124:125], v[124:125], 1.0 op_sel_hi:[1,0]
	v_pk_add_f32 v[92:93], v[28:29], v[92:93]
	v_and_b32_e32 v127, 0xffff0000, v87
	v_and_b32_e32 v87, 0xffff0000, v95
	v_rcp_f32_e32 v37, v125
	s_nop 0
	v_mul_f32_e32 v81, v81, v37
	v_and_b32_e32 v125, 0xffff0000, v91
	v_rcp_f32_e32 v37, v124
	s_nop 0
	v_mul_f32_e32 v80, v80, v37
	v_lshlrev_b32_e32 v124, 16, v91
	v_pk_mul_f32 v[80:81], v[80:81], v[92:93]
	v_lshlrev_b32_e32 v82, 16, v83
	v_and_b32_e32 v83, 0xffff0000, v83
	v_pk_mul_f32 v[92:93], v[54:55], v[124:125]
	v_lshlrev_b32_e32 v90, 16, v99
	v_and_b32_e32 v91, 0xffff0000, v99
	v_pk_fma_f32 v[82:83], v[2:3], v[82:83], v[92:93]
	v_lshlrev_b32_e32 v78, 16, v79
	v_pk_fma_f32 v[82:83], v[58:59], v[90:91], v[82:83]
	v_and_b32_e32 v79, 0xffff0000, v79
	v_pk_add_f32 v[82:83], v[10:11], v[82:83]
	v_lshlrev_b32_e32 v86, 16, v95
	v_mul_f32_e32 v37, 0xbfb8aa3b, v82
	v_exp_f32_e32 v92, v37
	v_mul_f32_e32 v37, 0xbfb8aa3b, v83
	v_exp_f32_e32 v93, v37
	v_pk_mul_f32 v[94:95], v[70:71], v[126:127]
	v_cvt_pk_bf16_f32 v80, v80, v81
	v_pk_fma_f32 v[78:79], v[22:23], v[78:79], v[94:95]
	v_pk_add_f32 v[92:93], v[92:93], 1.0 op_sel_hi:[1,0]
	v_pk_fma_f32 v[78:79], v[74:75], v[86:87], v[78:79]
	v_pk_add_f32 v[78:79], v[30:31], v[78:79]
	v_rcp_f32_e32 v37, v93
	s_nop 0
	v_mul_f32_e32 v83, v83, v37
	s_mov_b32 s0, 0x13f20000
	v_rcp_f32_e32 v37, v92
	s_nop 0
	v_mul_f32_e32 v82, v82, v37
	v_lshl_add_u64 v[92:93], v[100:101], 0, v[42:43]
	v_pk_mul_f32 v[82:83], v[82:83], v[78:79]
	v_cvt_pk_bf16_f32 v79, v76, v77
	v_add_co_u32_e32 v76, vcc, s0, v92
	v_cvt_pk_bf16_f32 v78, v114, v115
	v_cvt_pk_bf16_f32 v81, v82, v83
	v_addc_co_u32_e32 v77, vcc, 0, v93, vcc
	s_mov_b32 s0, 0x89a5000
	global_store_dwordx4 v[76:77], v[78:81], off
	v_add_co_u32_e32 v76, vcc, s0, v104
	s_mov_b32 s0, 0x89a6000
	s_nop 0
	v_addc_co_u32_e32 v77, vcc, 0, v105, vcc
	global_load_dwordx4 v[76:79], v[76:77], off offset:2048
	v_add_co_u32_e32 v80, vcc, s0, v104
	v_pk_mul_f32 v[114:115], v[32:33], v[38:39]
	s_nop 0
	v_addc_co_u32_e32 v81, vcc, 0, v105, vcc
	global_load_dwordx4 v[80:83], v[80:81], off offset:3584
	v_pk_fma_f32 v[110:111], v[4:5], v[110:111], v[114:115]
	s_waitcnt vmcnt(1)
	v_lshlrev_b32_e32 v98, 16, v76
	v_and_b32_e32 v99, 0xffff0000, v76
	v_pk_fma_f32 v[110:111], v[48:49], v[98:99], v[110:111]
	s_waitcnt vmcnt(0)
; __device__ __forceinline__ u32x4 pack8(const float* v) { u32x4 w; w.x = pk2(v[0], v[1]); w.y = pk2(v[2], v[3]); w.z = pk2(v[4], v[5]); w.w = pk2(v[6], v[7]); return w; }
; __device__ __forceinline__ void unpack8(u32x4 w, float* v) { v[0] = bflo(w.x); v[1] = bfhi(w.x); v[2] = bflo(w.y); v[3] = bfhi(w.y); v[4] = bflo(w.z); v[5] = bfhi(w.z); v[6] = bflo(w.w); v[7] = bfhi(w.w); }
; __device__ __forceinline__ float siluf_(float x) { return x / (1.f + __expf(-x)); }
; __global__ void __launch_bounds__(NTHR, 2) mk_fwd(Args args) {
;     ...
;                     for (int r = 0; r < 16; ++r) {
;                         u32x4 gn_ = (u32x4){0u, 0u, 0u, 0u}, vn_ = (u32x4){0u, 0u, 0u, 0u};
;                         const int ii = i0 + r;
;                         if (ii != LC - 1 && ii != TB - 1) { gn_ = *(const u32x4*)(up + (size_t)(r + 1) * FF2); vn_ = *(const u32x4*)(up + (size_t)(r + 1) * FF2 + FF); }
;                         float gm[8], gc[8], gn[8], vm[8], vc[8], vn[8], o[8];
;                         unpack8(gp_, gm); unpack8(gc_, gc); unpack8(gn_, gn); unpack8(vp_, vm); unpack8(vc_, vc); unpack8(vn_, vn);
; #pragma unroll
;                         for (int e = 0; e < 8; ++e) {
;                             const float a = wg0[e] * gm[e] + wg1[e] * gc[e] + wg2[e] * gn[e] + bg[e];
;                             const float v = wv0[e] * vm[e] + wv1[e] * vc[e] + wv2[e] * vn[e] + bv[e];
;                             o[e] = siluf_(a) * v;
;                         }
;                         *(u32x4*)(ACT + (size_t)(t0 + r) * FF + j0) = pack8(o);
;                         gp_ = gc_; vp_ = vc_; gc_ = gn_; vc_ = vn_;
;                     }
	v_lshlrev_b32_e32 v94, 16, v80
	v_pk_add_f32 v[110:111], v[12:13], v[110:111]
	v_and_b32_e32 v95, 0xffff0000, v80
	v_mul_f32_e32 v37, 0xbfb8aa3b, v110
	v_exp_f32_e32 v114, v37
	v_mul_f32_e32 v37, 0xbfb8aa3b, v111
	v_exp_f32_e32 v115, v37
	v_pk_fma_f32 v[112:113], v[64:65], v[94:95], v[112:113]
	v_pk_add_f32 v[114:115], v[114:115], 1.0 op_sel_hi:[1,0]
	s_nop 0
	v_pk_add_f32 v[112:113], v[24:25], v[112:113]
	v_rcp_f32_e32 v37, v115
	s_nop 0
	v_mul_f32_e32 v111, v111, v37
	s_nop 0
	v_rcp_f32_e32 v37, v114
	s_nop 0
	v_mul_f32_e32 v110, v110, v37
	v_pk_mul_f32 v[128:129], v[110:111], v[112:113]
	v_lshlrev_b32_e32 v112, 16, v77
	v_and_b32_e32 v113, 0xffff0000, v77
	v_pk_mul_f32 v[76:77], v[34:35], v[88:89]
	v_lshlrev_b32_e32 v110, 16, v81
	v_pk_fma_f32 v[76:77], v[6:7], v[116:117], v[76:77]
	v_and_b32_e32 v111, 0xffff0000, v81
	v_pk_fma_f32 v[76:77], v[50:51], v[112:113], v[76:77]
	v_pk_mul_f32 v[114:115], v[62:63], v[84:85]
	v_pk_add_f32 v[76:77], v[14:15], v[76:77]
	v_pk_fma_f32 v[114:115], v[18:19], v[118:119], v[114:115]
	v_mul_f32_e32 v37, 0xbfb8aa3b, v76
	v_exp_f32_e32 v80, v37
	v_mul_f32_e32 v37, 0xbfb8aa3b, v77
	v_exp_f32_e32 v81, v37
	v_pk_fma_f32 v[114:115], v[66:67], v[110:111], v[114:115]
	v_pk_add_f32 v[80:81], v[80:81], 1.0 op_sel_hi:[1,0]
	s_nop 0
	v_pk_add_f32 v[114:115], v[26:27], v[114:115]
	v_rcp_f32_e32 v37, v81
	s_nop 0
	v_mul_f32_e32 v77, v77, v37
	s_nop 0
	v_rcp_f32_e32 v37, v80
	s_nop 0
	v_mul_f32_e32 v76, v76, v37
	v_pk_mul_f32 v[80:81], v[52:53], v[96:97]
	v_lshlrev_b32_e32 v116, 16, v78
	v_and_b32_e32 v117, 0xffff0000, v78
	v_pk_fma_f32 v[80:81], v[0:1], v[120:121], v[80:81]
	v_pk_mul_f32 v[76:77], v[76:77], v[114:115]
	v_pk_fma_f32 v[80:81], v[56:57], v[116:117], v[80:81]
	v_lshlrev_b32_e32 v114, 16, v82
	v_pk_add_f32 v[80:81], v[8:9], v[80:81]
	v_and_b32_e32 v115, 0xffff0000, v82
	v_mul_f32_e32 v37, 0xbfb8aa3b, v80
	v_exp_f32_e32 v118, v37
	v_mul_f32_e32 v37, 0xbfb8aa3b, v81
	v_exp_f32_e32 v119, v37
	v_pk_mul_f32 v[120:121], v[68:69], v[108:109]
	v_pk_add_f32 v[118:119], v[118:119], 1.0 op_sel_hi:[1,0]
	s_nop 0
	v_pk_fma_f32 v[120:121], v[20:21], v[122:123], v[120:121]
	v_rcp_f32_e32 v37, v119
	s_nop 0
	v_mul_f32_e32 v81, v81, v37
	v_pk_fma_f32 v[120:121], v[72:73], v[114:115], v[120:121]
	v_pk_add_f32 v[120:121], v[28:29], v[120:121]
	v_rcp_f32_e32 v37, v118
	s_nop 0
	v_mul_f32_e32 v80, v80, v37
	v_pk_mul_f32 v[80:81], v[80:81], v[120:121]
	v_lshlrev_b32_e32 v120, 16, v79
	v_and_b32_e32 v121, 0xffff0000, v79
	v_pk_mul_f32 v[78:79], v[54:55], v[90:91]
	v_lshlrev_b32_e32 v118, 16, v83
	v_pk_fma_f32 v[78:79], v[2:3], v[124:125], v[78:79]
	v_and_b32_e32 v119, 0xffff0000, v83
	v_pk_fma_f32 v[78:79], v[58:59], v[120:121], v[78:79]
	v_pk_mul_f32 v[122:123], v[70:71], v[86:87]
	v_pk_add_f32 v[78:79], v[10:11], v[78:79]
	v_pk_fma_f32 v[122:123], v[22:23], v[126:127], v[122:123]
	v_mul_f32_e32 v37, 0xbfb8aa3b, v78
	v_exp_f32_e32 v82, v37
	v_mul_f32_e32 v37, 0xbfb8aa3b, v79
	v_exp_f32_e32 v83, v37
	v_pk_fma_f32 v[122:123], v[74:75], v[118:119], v[122:123]
	v_cvt_pk_bf16_f32 v80, v80, v81
	v_pk_add_f32 v[122:123], v[30:31], v[122:123]
	v_pk_add_f32 v[82:83], v[82:83], 1.0 op_sel_hi:[1,0]
	s_nop 0
	s_nop 0
	v_rcp_f32_e32 v37, v83
	s_nop 0
	v_mul_f32_e32 v79, v79, v37
	s_mov_b32 s0, 0x13f21000
	v_rcp_f32_e32 v37, v82
	s_nop 0
	v_mul_f32_e32 v78, v78, v37
	v_pk_mul_f32 v[82:83], v[78:79], v[122:123]
	v_cvt_pk_bf16_f32 v79, v76, v77
	v_add_co_u32_e32 v76, vcc, s0, v92
	v_cvt_pk_bf16_f32 v78, v128, v129
	v_cvt_pk_bf16_f32 v81, v82, v83
	v_addc_co_u32_e32 v77, vcc, 0, v93, vcc
	s_mov_b32 s0, 0x89a8000
	global_store_dwordx4 v[76:77], v[78:81], off offset:1536
	v_add_co_u32_e32 v76, vcc, s0, v104
	s_mov_b32 s0, 0x89a9000
	s_nop 0
	v_addc_co_u32_e32 v77, vcc, 0, v105, vcc
	global_load_dwordx4 v[80:83], v[76:77], off offset:1024
	v_add_co_u32_e32 v76, vcc, s0, v104
	v_pk_mul_f32 v[126:127], v[32:33], v[98:99]
	s_nop 0
	v_addc_co_u32_e32 v77, vcc, 0, v105, vcc
	global_load_dwordx4 v[76:79], v[76:77], off offset:2560
	v_pk_fma_f32 v[38:39], v[4:5], v[38:39], v[126:127]
	v_pk_mul_f32 v[128:129], v[60:61], v[94:95]
	s_waitcnt vmcnt(1)
	v_lshlrev_b32_e32 v124, 16, v80
	v_and_b32_e32 v125, 0xffff0000, v80
	v_pk_fma_f32 v[38:39], v[48:49], v[124:125], v[38:39]
	v_pk_fma_f32 v[106:107], v[16:17], v[106:107], v[128:129]
	v_pk_add_f32 v[38:39], v[12:13], v[38:39]
	s_waitcnt vmcnt(0)
; __device__ __forceinline__ u32x4 pack8(const float* v) { u32x4 w; w.x = pk2(v[0], v[1]); w.y = pk2(v[2], v[3]); w.z = pk2(v[4], v[5]); w.w = pk2(v[6], v[7]); return w; }
; __device__ __forceinline__ void unpack8(u32x4 w, float* v) { v[0] = bflo(w.x); v[1] = bfhi(w.x); v[2] = bflo(w.y); v[3] = bfhi(w.y); v[4] = bflo(w.z); v[5] = bfhi(w.z); v[6] = bflo(w.w); v[7] = bfhi(w.w); }
; __device__ __forceinline__ float siluf_(float x) { return x / (1.f + __expf(-x)); }
; __global__ void __launch_bounds__(NTHR, 2) mk_fwd(Args args) {
;     ...
;                     for (int r = 0; r < 16; ++r) {
;                         u32x4 gn_ = (u32x4){0u, 0u, 0u, 0u}, vn_ = (u32x4){0u, 0u, 0u, 0u};
;                         const int ii = i0 + r;
;                         if (ii != LC - 1 && ii != TB - 1) { gn_ = *(const u32x4*)(up + (size_t)(r + 1) * FF2); vn_ = *(const u32x4*)(up + (size_t)(r + 1) * FF2 + FF); }
;                         float gm[8], gc[8], gn[8], vm[8], vc[8], vn[8], o[8];
;                         unpack8(gp_, gm); unpack8(gc_, gc); unpack8(gn_, gn); unpack8(vp_, vm); unpack8(vc_, vc); unpack8(vn_, vn);
; #pragma unroll
;                         for (int e = 0; e < 8; ++e) {
;                             const float a = wg0[e] * gm[e] + wg1[e] * gc[e] + wg2[e] * gn[e] + bg[e];
;                             const float v = wv0[e] * vm[e] + wv1[e] * vc[e] + wv2[e] * vn[e] + bv[e];
;                             o[e] = siluf_(a) * v;
;                         }
;                         *(u32x4*)(ACT + (size_t)(t0 + r) * FF + j0) = pack8(o);
;                         gp_ = gc_; vp_ = vc_; gc_ = gn_; vc_ = vn_;
;                     }
	v_lshlrev_b32_e32 v122, 16, v76
	v_mul_f32_e32 v37, 0xbfb8aa3b, v38
	v_exp_f32_e32 v126, v37
	v_mul_f32_e32 v37, 0xbfb8aa3b, v39
	v_exp_f32_e32 v127, v37
	v_and_b32_e32 v123, 0xffff0000, v76
	v_pk_fma_f32 v[106:107], v[64:65], v[122:123], v[106:107]
	v_pk_add_f32 v[126:127], v[126:127], 1.0 op_sel_hi:[1,0]
	s_nop 0
	v_pk_add_f32 v[106:107], v[24:25], v[106:107]
	v_rcp_f32_e32 v37, v127
	s_nop 0
	v_mul_f32_e32 v39, v39, v37
	s_nop 0
	v_pk_mul_f32 v[128:129], v[34:35], v[112:113]
	v_rcp_f32_e32 v37, v126
	s_nop 0
	v_mul_f32_e32 v38, v38, v37
	v_lshlrev_b32_e32 v126, 16, v81
	v_and_b32_e32 v127, 0xffff0000, v81
	v_pk_fma_f32 v[88:89], v[6:7], v[88:89], v[128:129]
	v_pk_mul_f32 v[130:131], v[62:63], v[110:111]
	v_pk_fma_f32 v[88:89], v[50:51], v[126:127], v[88:89]
	v_pk_fma_f32 v[84:85], v[18:19], v[84:85], v[130:131]
	v_pk_add_f32 v[88:89], v[14:15], v[88:89]
	v_pk_mul_f32 v[38:39], v[38:39], v[106:107]
	v_mul_f32_e32 v37, 0xbfb8aa3b, v88
	v_exp_f32_e32 v128, v37
	v_mul_f32_e32 v37, 0xbfb8aa3b, v89
	v_exp_f32_e32 v129, v37
	v_lshlrev_b32_e32 v106, 16, v77
	v_and_b32_e32 v107, 0xffff0000, v77
	v_pk_fma_f32 v[84:85], v[66:67], v[106:107], v[84:85]
	v_pk_add_f32 v[128:129], v[128:129], 1.0 op_sel_hi:[1,0]
	v_pk_add_f32 v[84:85], v[26:27], v[84:85]
	s_nop 0
	v_rcp_f32_e32 v37, v129
	s_nop 0
	v_mul_f32_e32 v89, v89, v37
	v_pk_mul_f32 v[134:135], v[68:69], v[114:115]
	v_rcp_f32_e32 v37, v128
	s_nop 0
	v_mul_f32_e32 v88, v88, v37
	v_pk_mul_f32 v[84:85], v[88:89], v[84:85]
	v_pk_mul_f32 v[88:89], v[52:53], v[116:117]
	v_lshlrev_b32_e32 v130, 16, v82
	v_and_b32_e32 v131, 0xffff0000, v82
	v_pk_fma_f32 v[88:89], v[0:1], v[96:97], v[88:89]
	v_pk_fma_f32 v[108:109], v[20:21], v[108:109], v[134:135]
	v_pk_fma_f32 v[88:89], v[56:57], v[130:131], v[88:89]
	v_lshlrev_b32_e32 v128, 16, v78
	v_pk_add_f32 v[88:89], v[8:9], v[88:89]
	v_and_b32_e32 v129, 0xffff0000, v78
	v_mul_f32_e32 v37, 0xbfb8aa3b, v88
	v_exp_f32_e32 v96, v37
	v_mul_f32_e32 v37, 0xbfb8aa3b, v89
	v_exp_f32_e32 v97, v37
	v_pk_fma_f32 v[108:109], v[72:73], v[128:129], v[108:109]
	v_pk_add_f32 v[96:97], v[96:97], 1.0 op_sel_hi:[1,0]
	s_nop 0
	v_pk_add_f32 v[108:109], v[28:29], v[108:109]
	v_rcp_f32_e32 v37, v97
	s_nop 0
	v_mul_f32_e32 v89, v89, v37
	v_pk_mul_f32 v[136:137], v[70:71], v[118:119]
	v_rcp_f32_e32 v37, v96
	s_nop 0
	v_mul_f32_e32 v88, v88, v37
	v_pk_mul_f32 v[134:135], v[54:55], v[120:121]
	v_pk_mul_f32 v[88:89], v[88:89], v[108:109]
	v_lshlrev_b32_e32 v108, 16, v83
	v_and_b32_e32 v109, 0xffff0000, v83
	v_pk_fma_f32 v[90:91], v[2:3], v[90:91], v[134:135]
	v_pk_fma_f32 v[86:87], v[22:23], v[86:87], v[136:137]
	v_pk_fma_f32 v[90:91], v[58:59], v[108:109], v[90:91]
	v_lshlrev_b32_e32 v96, 16, v79
	v_pk_add_f32 v[90:91], v[10:11], v[90:91]
	v_and_b32_e32 v97, 0xffff0000, v79
	v_mul_f32_e32 v37, 0xbfb8aa3b, v90
	v_exp_f32_e32 v134, v37
	v_mul_f32_e32 v37, 0xbfb8aa3b, v91
	v_exp_f32_e32 v135, v37
	v_pk_fma_f32 v[86:87], v[74:75], v[96:97], v[86:87]
	v_cvt_pk_bf16_f32 v88, v88, v89
	v_pk_add_f32 v[86:87], v[30:31], v[86:87]
	v_pk_add_f32 v[134:135], v[134:135], 1.0 op_sel_hi:[1,0]
	s_nop 0
	s_nop 0
	v_rcp_f32_e32 v37, v135
	s_nop 0
	v_mul_f32_e32 v91, v91, v37
	s_nop 0
	v_rcp_f32_e32 v37, v134
	s_nop 0
	v_mul_f32_e32 v90, v90, v37
	v_pk_mul_f32 v[90:91], v[90:91], v[86:87]
	v_cvt_pk_bf16_f32 v86, v38, v39
	v_add_co_u32_e32 v38, vcc, 0x13f22000, v92
	v_cvt_pk_bf16_f32 v87, v84, v85
	v_cvt_pk_bf16_f32 v89, v90, v91
	v_addc_co_u32_e32 v39, vcc, 0, v93, vcc
	global_store_dwordx4 v[38:39], v[86:89], off offset:3072
	v_mov_b32_e32 v38, v36
	v_mov_b32_e32 v39, v36
	v_mov_b32_e32 v37, v36
	v_mov_b64_e32 v[90:91], v[38:39]
	v_mov_b64_e32 v[86:87], v[38:39]
	v_cmp_ne_u32_e32 vcc, s18, v132
	v_mov_b64_e32 v[88:89], v[36:37]
	v_mov_b64_e32 v[84:85], v[36:37]
	s_and_saveexec_b64 s[0:1], vcc
	s_cbranch_execz .LBB0_90
	v_add_co_u32_e32 v38, vcc, 0x89ab000, v104
	s_nop 1
	v_addc_co_u32_e32 v39, vcc, 0, v105, vcc
	v_add_co_u32_e32 v84, vcc, 0x89ac000, v104
	s_nop 1
	v_addc_co_u32_e32 v85, vcc, 0, v105, vcc
	global_load_dwordx4 v[88:91], v[38:39], off
	s_nop 0
	global_load_dwordx4 v[84:87], v[84:85], off offset:1536
	s_branch .LBB0_90

; __device__ __forceinline__ void gla_decay(unsigned char* lds, const float* glow_t0, const float* Wg  , const float* bg  , int dir) {
;     float* Bs = (float*)(lds + GL_BS); float* Tot = (float*)(lds + GL_TOT); float* GLs = (float*)(lds + GL_O);
;     int tid_ = threadIdx.x; asm volatile("" : "+v"(tid_)); const int tid = tid_;
;     { const int s = tid >> 3, q = tid & 7;
;       const float* gp = glow_t0 + (size_t)s * 32 + dir * 16 + q * 2;
;       GLs[s * 16 + q * 2] = gp[0]; GLs[s * 16 + q * 2 + 1] = gp[1]; }
;     const int d = tid & 63, seg = tid >> 6;
;     float w[16];
; #pragma unroll
;     for (int r = 0; r < 16; ++r) w[r] = Wg[r * 256 + d];
;     const float bias = bg[d];
;     __syncthreads();
; __device__ __forceinline__ void gla_out_item(unsigned char* lds, unsigned char* ws, const float* wgate, const float* bgate, const float* hnorm, int l, int item, bool dowrite = true) {
;     ...
;     const u32x4 qraw = *(const u32x4*)((const bf16_t*)(ws + O_CQ) + (size_t)(t0 + (tid >> 3)) * 256 + h * 64 + (tid & 7) * 8);
;     const u32x4 kraw = *(const u32x4*)((const bf16_t*)(ws + O_CK) + (size_t)(t0 + (tid >> 3)) * 256 + h * 64 + (tid & 7) * 8);
;     bf16x8 sfr[2][2];
; #pragma unroll
;     for (int dd = 0; dd < 2; ++dd)
; #pragma unroll
;         for (int kk = 0; kk < 2; ++kk) sfr[dd][kk] = *(const bf16x8*)((const bf16_t*)(ws + O_ST) + (size_t)(((b * 4 + h) * 2 + dd) * 132 + c) * 8192 + (wid * 16 + ql) * 64 + kk * 32 + g * 8);
;     const u32x4 rraw0 = *(const u32x4*)((const bf16_t*)(ws + O_CR) + (size_t)(t0 + (tid >> 3)) * 512 + h * 128 + (tid & 7) * 16);
;     const u32x4 rraw1 = *(const u32x4*)((const bf16_t*)(ws + O_CR) + (size_t)(t0 + (tid >> 3)) * 512 + h * 128 + (tid & 7) * 16 + 8);
;     gla_load_vt(lds, (const bf16_t*)(ws + O_CV) + (size_t)t0 * 512 + h * 128);
.LBB0_394:
	s_mul_hi_i32 s0, s51, 0x3e0f83e1
	s_ashr_i32 s1, s0, 5
	s_lshr_b32 s18, s0, 31
	s_ashr_i32 s0, s0, 7
	s_add_i32 s1, s1, s18
	s_add_i32 s18, s0, s18
	s_waitcnt vmcnt(0)
	v_mov_b32_e32 v68, v203
	s_mul_i32 s38, s18, 0x2100
	s_mul_i32 s19, s1, 0x84
	v_ashrrev_i32_e32 v37, 3, v68
	s_and_b32 s52, s1, 3
	s_mulk_i32 s1, 0x2100
	v_add_u32_e32 v0, s38, v37
	v_subrev_u32_e32 v0, s1, v0
	v_add_u32_e32 v0, s37, v0
	v_ashrrev_i32_e32 v1, 31, v0
	v_lshlrev_b64 v[2:3], 9, v[0:1]
	s_sub_i32 s0, s38, s1
	v_lshl_add_u64 v[4:5], s[2:3], 0, v[2:3]
	s_lshl_b32 s60, s52, 7
	v_and_b32_e32 v41, 7, v68
	v_lshl_add_u64 v[2:3], s[10:11], 0, v[2:3]
	s_mul_i32 s1, s18, 0x420
	s_mul_i32 s18, s52, 0x108
	v_lshl_add_u64 v[4:5], v[4:5], 0, s[60:61]
	v_lshlrev_b32_e32 v34, 4, v41
	v_mov_b32_e32 v35, v36
	v_lshl_add_u64 v[2:3], v[2:3], 0, s[60:61]
	s_add_i32 s1, s1, s18
	v_and_b32_e32 v69, 15, v68
	v_lshl_add_u64 v[4:5], v[4:5], 0, v[34:35]
	v_lshl_add_u64 v[2:3], v[2:3], 0, v[34:35]
	s_sub_i32 s1, s1, s19
	v_ashrrev_i32_e32 v55, 6, v68
	global_load_dwordx4 v[24:27], v[4:5], off
	global_load_dwordx4 v[20:23], v[2:3], off
	v_lshlrev_b32_e32 v2, 6, v69
	s_add_i32 s18, s51, s1
	v_lshl_or_b32 v2, v55, 10, v2
	s_ashr_i32 s19, s18, 31
	v_bfe_u32 v70, v68, 4, 2
	v_ashrrev_i32_e32 v3, 31, v2
	s_lshl_b64 s[38:39], s[18:19], 14
	s_addk_i32 s18, 0x84
	s_add_i32 s0, s37, s0
	v_lshl_add_u64 v[2:3], v[2:3], 1, s[20:21]
	v_lshlrev_b32_e32 v38, 4, v70
	v_mov_b32_e32 v39, v36
	s_ashr_i32 s19, s18, 31
	v_lshl_add_u64 v[2:3], v[2:3], 0, v[38:39]
	s_lshl_b64 s[18:19], s[18:19], 14
	v_lshlrev_b64 v[0:1], 10, v[0:1]
	s_ashr_i32 s1, s0, 31
	v_lshl_add_u64 v[4:5], v[2:3], 0, s[38:39]
	v_lshl_add_u64 v[2:3], v[2:3], 0, s[18:19]
	v_lshl_add_u64 v[0:1], s[14:15], 0, v[0:1]
	s_lshl_b32 s60, s52, 8
	s_lshl_b64 s[18:19], s[0:1], 10
	v_lshl_add_u64 v[0:1], v[0:1], 0, s[60:61]
	v_lshlrev_b32_e32 v42, 5, v41
	v_mov_b32_e32 v43, v36
	s_add_u32 s18, s13, s18
	v_lshl_add_u64 v[32:33], v[0:1], 0, v[42:43]
	s_addc_u32 s19, s24, s19
	v_mov_b32_e32 v35, v203
	global_load_dwordx4 v[16:19], v[4:5], off
	global_load_dwordx4 v[28:31], v[4:5], off offset:64
	global_load_dwordx4 v[12:15], v[2:3], off
	global_load_dwordx4 v[8:11], v[2:3], off offset:64
	s_nop 0
	global_load_dwordx4 v[0:3], v[32:33], off offset:16
	global_load_dwordx4 v[4:7], v[32:33], off
	s_add_u32 s18, s18, s60
	s_addc_u32 s19, s19, 0
	v_and_b32_e32 v39, 63, v35
	v_lshlrev_b32_e32 v48, 10, v39
	v_mov_b32_e32 v49, v36
	v_lshl_add_u32 v54, v39, 1, 0
	v_ashrrev_i32_e32 v39, 3, v35
	v_lshl_add_u64 v[52:53], s[18:19], 0, v[48:49]
	v_and_b32_e32 v48, -8, v39
	v_ashrrev_i32_e32 v49, 31, v48
	v_lshl_add_u64 v[50:51], v[48:49], 1, v[52:53]
	v_mad_u64_u32 v[56:57], s[18:19], v48, s76, v[54:55]
	global_load_dwordx4 v[48:51], v[50:51], off
	v_add_u32_e32 v35, 0x200, v35
	v_ashrrev_i32_e32 v35, 3, v35
	s_lshl_b64 s[0:1], s[0:1], 7
	s_add_u32 s42, s25, s0
	v_add_u32_e32 v42, 0, v42
	s_addc_u32 s43, s26, s1
	v_sub_u32_e32 v34, v42, v34
	v_add_u32_e32 v66, 0, v38
	s_add_u32 s48, s44, s60
	s_addc_u32 s49, s45, 0
	s_add_u32 s53, s46, s60
	s_addc_u32 s54, s47, 0
	s_waitcnt vmcnt(0)
	ds_write_b16 v56, v48 offset:46336
	ds_write_b16_d16_hi v56, v48 offset:46480
	ds_write_b16 v56, v49 offset:46624
	ds_write_b16_d16_hi v56, v49 offset:46768
	ds_write_b16 v56, v50 offset:46912
	ds_write_b16_d16_hi v56, v50 offset:47056
	ds_write_b16 v56, v51 offset:47200
	ds_write_b16_d16_hi v56, v51 offset:47344
	v_and_b32_e32 v48, -8, v35
	v_ashrrev_i32_e32 v49, 31, v48
	v_lshl_add_u64 v[50:51], v[48:49], 1, v[52:53]
	v_mad_u64_u32 v[52:53], s[18:19], v48, s76, v[54:55]
	global_load_dwordx4 v[48:51], v[50:51], off
	s_add_u32 s18, s48, s16
	s_addc_u32 s19, s49, s17
	s_waitcnt vmcnt(0)
	ds_write_b16 v52, v48 offset:46336
	ds_write_b16_d16_hi v52, v48 offset:46480
	ds_write_b16 v52, v49 offset:46624
	ds_write_b16_d16_hi v52, v49 offset:46768
	ds_write_b16 v52, v50 offset:46912
	ds_write_b16_d16_hi v52, v50 offset:47056
	ds_write_b16 v52, v51 offset:47200
	ds_write_b16_d16_hi v52, v51 offset:47344
	v_mad_u64_u32 v[48:49], s[0:1], v37, s56, v[42:43]
	v_mov_b32_e32 v49, v203
	v_mad_u64_u32 v[42:43], s[0:1], v37, s76, v[34:35]
	v_ashrrev_i32_e32 v50, 3, v49
	v_bfi_b32 v35, -16, v37, v68
	v_ashrrev_i32_e32 v51, 31, v50
	v_and_b32_e32 v34, -16, v37
	v_mad_u64_u32 v[38:39], s[0:1], v35, s76, v[66:67]
	v_lshlrev_b64 v[52:53], 7, v[50:51]
	v_lshlrev_b32_e32 v51, 3, v49
	v_lshlrev_b32_e32 v43, 5, v55
	v_lshl_or_b32 v39, v70, 2, v34
	v_lshl_or_b32 v34, v55, 4, v69
	v_lshl_add_u64 v[52:53], s[42:43], 0, v[52:53]
	v_and_b32_e32 v54, 56, v51
	v_mov_b32_e32 v55, v36
	v_lshl_add_u64 v[52:53], v[52:53], 0, v[54:55]
	v_lshlrev_b32_e32 v50, 6, v50
	v_add3_u32 v54, 0, v50, v54
	global_load_dwordx2 v[50:51], v[52:53], off
	v_lshlrev_b32_e32 v64, 2, v49
	v_mad_u64_u32 v[34:35], s[0:1], v34, s76, v[66:67]
	s_add_u32 s0, s53, s30
	s_addc_u32 s1, s54, s31
	v_ashrrev_i32_e32 v49, 6, v49
	v_lshl_add_u32 v72, v49, 9, 0
	v_mul_u32_u24_e32 v35, 0x48, v69
	v_lshl_add_u32 v35, v35, 1, v66
	s_waitcnt vmcnt(0)
	ds_write_b64 v54, v[50:51] offset:64768
	v_and_b32_e32 v50, 0xfc, v64
	v_mov_b32_e32 v51, v36
	v_lshl_add_u64 v[52:53], s[18:19], 0, v[50:51]
	v_add_co_u32_e32 v54, vcc, s69, v52
	global_load_dword v51, v50, s[18:19]
	global_load_dword v65, v50, s[18:19] offset:1024
	global_load_dword v67, v50, s[18:19] offset:2048
	global_load_dword v71, v50, s[18:19] offset:3072
	v_addc_co_u32_e32 v55, vcc, 0, v53, vcc
	v_add_co_u32_e32 v56, vcc, s67, v52
	s_nop 1
	v_addc_co_u32_e32 v57, vcc, 0, v53, vcc
	v_add_co_u32_e32 v52, vcc, s66, v52
	global_load_dword v76, v[56:57], off offset:-4096
	global_load_dword v77, v[54:55], off offset:1024
	global_load_dword v78, v[54:55], off offset:2048
	global_load_dword v79, v[54:55], off offset:3072
	global_load_dword v80, v[56:57], off
	global_load_dword v81, v[56:57], off offset:1024
	global_load_dword v82, v[56:57], off offset:2048
	global_load_dword v83, v[56:57], off offset:3072
	v_addc_co_u32_e32 v53, vcc, 0, v53, vcc
	global_load_dword v84, v[52:53], off
	global_load_dword v85, v[52:53], off offset:1024
	global_load_dword v86, v[52:53], off offset:2048
	global_load_dword v87, v[52:53], off offset:3072
	global_load_dword v88, v50, s[0:1]
	s_waitcnt lgkmcnt(0)
	s_barrier
; __device__ __forceinline__ void gla_decay(unsigned char* lds, const float* glow_t0, const float* Wg  , const float* bg  , int dir) {
;     ...
;     for (int k = 0; k < 8; ++k) { const float* gl = GLs + (seg * 8 + k) * 16; float a = bias;
; #pragma unroll
;         for (int r = 0; r < 16; ++r) a += gl[r] * w[r];
;         loc[k] = (fminf(a, 0.f) - __logf(1.f + __expf(-fabsf(a)))) * (1.f / 16.f); }
	ds_read_b128 v[52:55], v72 offset:65216
	v_add_u32_e32 v50, 0, v50
	s_waitcnt vmcnt(0) lgkmcnt(0)
	v_fma_f32 v56, v51, v52, v88
	v_fmac_f32_e32 v56, v65, v53
	v_fmac_f32_e32 v56, v67, v54
	v_fmac_f32_e32 v56, v71, v55
	ds_read_b128 v[52:55], v72 offset:65232
	s_waitcnt lgkmcnt(0)
	v_fmac_f32_e32 v56, v76, v52
	v_fmac_f32_e32 v56, v77, v53
	v_fmac_f32_e32 v56, v78, v54
	v_fmac_f32_e32 v56, v79, v55
	ds_read_b128 v[52:55], v72 offset:65248
	s_waitcnt lgkmcnt(0)
	v_fmac_f32_e32 v56, v80, v52
	v_fmac_f32_e32 v56, v81, v53
	v_fmac_f32_e32 v56, v82, v54
	v_fmac_f32_e32 v56, v83, v55
	ds_read_b128 v[52:55], v72 offset:65264
	s_waitcnt lgkmcnt(0)
	v_fmac_f32_e32 v56, v84, v52
	v_fmac_f32_e32 v56, v85, v53
	v_fmac_f32_e32 v56, v86, v54
	v_fmac_f32_e32 v56, v87, v55
	v_mul_f32_e64 v53, |v56|, s55
	v_exp_f32_e32 v53, v53
	v_min_f32_e32 v52, 0, v56
	v_add_f32_e32 v53, 1.0, v53
	v_cmp_gt_f32_e32 vcc, s33, v53
	s_nop 1
	v_cndmask_b32_e64 v54, 0, 32, vcc
	v_ldexp_f32 v53, v53, v54
	v_log_f32_e32 v53, v53
	s_nop 0
	v_mul_f32_e32 v54, 0x3f317217, v53
	v_fma_f32 v54, v53, s57, -v54
	v_fmac_f32_e32 v54, 0x3377d1cf, v53
	v_fmac_f32_e32 v54, 0x3f317217, v53
	v_cmp_lt_f32_e64 s[38:39], |v53|, s58
	s_nop 1
	v_cndmask_b32_e64 v53, v53, v54, s[38:39]
	v_cndmask_b32_e32 v54, 0, v229, vcc
	v_sub_f32_e32 v53, v53, v54
	v_sub_f32_e32 v89, v52, v53
	ds_read_b128 v[52:55], v72 offset:65152
	s_waitcnt lgkmcnt(0)
	v_fma_f32 v56, v51, v52, v88
	v_fmac_f32_e32 v56, v65, v53
	v_fmac_f32_e32 v56, v67, v54
	v_fmac_f32_e32 v56, v71, v55
	ds_read_b128 v[52:55], v72 offset:65168
	s_waitcnt lgkmcnt(0)
	v_fmac_f32_e32 v56, v76, v52
	v_fmac_f32_e32 v56, v77, v53
	v_fmac_f32_e32 v56, v78, v54
	v_fmac_f32_e32 v56, v79, v55
	ds_read_b128 v[52:55], v72 offset:65184
	s_waitcnt lgkmcnt(0)
	v_fmac_f32_e32 v56, v80, v52
	v_fmac_f32_e32 v56, v81, v53
	v_fmac_f32_e32 v56, v82, v54
	v_fmac_f32_e32 v56, v83, v55
	ds_read_b128 v[52:55], v72 offset:65200
	s_waitcnt lgkmcnt(0)
	v_fmac_f32_e32 v56, v84, v52
	v_fmac_f32_e32 v56, v85, v53
	v_fmac_f32_e32 v56, v86, v54
	v_fmac_f32_e32 v56, v87, v55
	v_mul_f32_e64 v53, |v56|, s55
	v_exp_f32_e32 v53, v53
	v_min_f32_e32 v52, 0, v56
	v_add_f32_e32 v53, 1.0, v53
	v_cmp_gt_f32_e32 vcc, s33, v53
	s_nop 1
	v_cndmask_b32_e64 v54, 0, 32, vcc
	v_ldexp_f32 v53, v53, v54
	v_log_f32_e32 v53, v53
	s_nop 0
	v_mul_f32_e32 v54, 0x3f317217, v53
	v_fma_f32 v54, v53, s57, -v54
	v_fmac_f32_e32 v54, 0x3377d1cf, v53
	v_fmac_f32_e32 v54, 0x3f317217, v53
	v_cmp_lt_f32_e64 s[38:39], |v53|, s58
	s_nop 1
	v_cndmask_b32_e64 v53, v53, v54, s[38:39]
	v_cndmask_b32_e32 v54, 0, v229, vcc
	v_sub_f32_e32 v53, v53, v54
	v_sub_f32_e32 v90, v52, v53
	ds_read_b128 v[52:55], v72 offset:65088
	s_waitcnt lgkmcnt(0)
	v_fma_f32 v56, v51, v52, v88
	v_fmac_f32_e32 v56, v65, v53
	v_fmac_f32_e32 v56, v67, v54
	v_fmac_f32_e32 v56, v71, v55
	ds_read_b128 v[52:55], v72 offset:65104
	s_waitcnt lgkmcnt(0)
	v_fmac_f32_e32 v56, v76, v52
	v_fmac_f32_e32 v56, v77, v53
	v_fmac_f32_e32 v56, v78, v54
	v_fmac_f32_e32 v56, v79, v55
	ds_read_b128 v[52:55], v72 offset:65120
	s_waitcnt lgkmcnt(0)
	v_fmac_f32_e32 v56, v80, v52
	v_fmac_f32_e32 v56, v81, v53
	v_fmac_f32_e32 v56, v82, v54
	v_fmac_f32_e32 v56, v83, v55
	ds_read_b128 v[52:55], v72 offset:65136
	s_waitcnt lgkmcnt(0)
	v_fmac_f32_e32 v56, v84, v52
	v_fmac_f32_e32 v56, v85, v53
	v_fmac_f32_e32 v56, v86, v54
	v_fmac_f32_e32 v56, v87, v55
	v_mul_f32_e64 v53, |v56|, s55
	v_exp_f32_e32 v53, v53
	v_min_f32_e32 v52, 0, v56
	v_add_f32_e32 v53, 1.0, v53
	v_cmp_gt_f32_e32 vcc, s33, v53
	s_nop 1
	v_cndmask_b32_e64 v54, 0, 32, vcc
	v_ldexp_f32 v53, v53, v54
	v_log_f32_e32 v53, v53
	s_nop 0
	v_mul_f32_e32 v54, 0x3f317217, v53
	v_fma_f32 v54, v53, s57, -v54
	v_fmac_f32_e32 v54, 0x3377d1cf, v53
	v_fmac_f32_e32 v54, 0x3f317217, v53
	v_cmp_lt_f32_e64 s[38:39], |v53|, s58
	s_nop 1
	v_cndmask_b32_e64 v53, v53, v54, s[38:39]
	v_cndmask_b32_e32 v54, 0, v229, vcc
	v_sub_f32_e32 v53, v53, v54
	v_sub_f32_e32 v91, v52, v53
	ds_read_b128 v[52:55], v72 offset:65024
	s_waitcnt lgkmcnt(0)
	v_fma_f32 v56, v51, v52, v88
	v_fmac_f32_e32 v56, v65, v53
	v_fmac_f32_e32 v56, v67, v54
	v_fmac_f32_e32 v56, v71, v55
	ds_read_b128 v[52:55], v72 offset:65040
	s_waitcnt lgkmcnt(0)
	v_fmac_f32_e32 v56, v76, v52
	v_fmac_f32_e32 v56, v77, v53
	v_fmac_f32_e32 v56, v78, v54
	v_fmac_f32_e32 v56, v79, v55
	ds_read_b128 v[52:55], v72 offset:65056
	s_waitcnt lgkmcnt(0)
	v_fmac_f32_e32 v56, v80, v52
	v_fmac_f32_e32 v56, v81, v53
	v_fmac_f32_e32 v56, v82, v54
	v_fmac_f32_e32 v56, v83, v55
	ds_read_b128 v[52:55], v72 offset:65072
	s_waitcnt lgkmcnt(0)
	v_fmac_f32_e32 v56, v84, v52
	v_fmac_f32_e32 v56, v85, v53
	v_fmac_f32_e32 v56, v86, v54
	v_fmac_f32_e32 v56, v87, v55
	v_mul_f32_e64 v53, |v56|, s55
	v_exp_f32_e32 v53, v53
	v_min_f32_e32 v52, 0, v56
	v_add_f32_e32 v53, 1.0, v53
	v_cmp_gt_f32_e32 vcc, s33, v53
	s_nop 1
	v_cndmask_b32_e64 v54, 0, 32, vcc
	v_ldexp_f32 v53, v53, v54
	v_log_f32_e32 v53, v53
	s_nop 0
	v_mul_f32_e32 v54, 0x3f317217, v53
	v_fma_f32 v54, v53, s57, -v54
	v_fmac_f32_e32 v54, 0x3377d1cf, v53
	v_fmac_f32_e32 v54, 0x3f317217, v53
	v_cmp_lt_f32_e64 s[38:39], |v53|, s58
	s_nop 1
	v_cndmask_b32_e64 v53, v53, v54, s[38:39]
	v_cndmask_b32_e32 v54, 0, v229, vcc
	v_sub_f32_e32 v53, v53, v54
	v_sub_f32_e32 v92, v52, v53
	ds_read_b128 v[52:55], v72 offset:64960
	s_waitcnt lgkmcnt(0)
	v_fma_f32 v56, v51, v52, v88
	v_fmac_f32_e32 v56, v65, v53
	v_fmac_f32_e32 v56, v67, v54
	v_fmac_f32_e32 v56, v71, v55
	ds_read_b128 v[52:55], v72 offset:64976
	s_waitcnt lgkmcnt(0)
	v_fmac_f32_e32 v56, v76, v52
	v_fmac_f32_e32 v56, v77, v53
	v_fmac_f32_e32 v56, v78, v54
	v_fmac_f32_e32 v56, v79, v55
	ds_read_b128 v[52:55], v72 offset:64992
	s_waitcnt lgkmcnt(0)
; __device__ __forceinline__ void gla_decay(unsigned char* lds, const float* glow_t0, const float* Wg  , const float* bg  , int dir) {
;     ...
;     for (int k = 0; k < 8; ++k) { const float* gl = GLs + (seg * 8 + k) * 16; float a = bias;
; #pragma unroll
;         for (int r = 0; r < 16; ++r) a += gl[r] * w[r];
;         loc[k] = (fminf(a, 0.f) - __logf(1.f + __expf(-fabsf(a)))) * (1.f / 16.f); }
;     float run = 0.f;
;     if (dir == 0) {
; #pragma unroll
;         for (int k = 0; k < 8; ++k) { run += loc[k]; loc[k] = run; }
;     } else {
; #pragma unroll
;         for (int k = 7; k >= 0; --k) { run += loc[k]; loc[k] = run; }
;     }
;     Tot[seg * 64 + d] = run;
;     __syncthreads();
	v_fmac_f32_e32 v56, v80, v52
	v_fmac_f32_e32 v56, v81, v53
	v_fmac_f32_e32 v56, v82, v54
	v_fmac_f32_e32 v56, v83, v55
	ds_read_b128 v[52:55], v72 offset:65008
	s_waitcnt lgkmcnt(0)
	v_fmac_f32_e32 v56, v84, v52
	v_fmac_f32_e32 v56, v85, v53
	v_fmac_f32_e32 v56, v86, v54
	v_fmac_f32_e32 v56, v87, v55
	v_mul_f32_e64 v53, |v56|, s55
	v_exp_f32_e32 v53, v53
	v_min_f32_e32 v52, 0, v56
	v_add_f32_e32 v53, 1.0, v53
	v_cmp_gt_f32_e32 vcc, s33, v53
	s_nop 1
	v_cndmask_b32_e64 v54, 0, 32, vcc
	v_ldexp_f32 v53, v53, v54
	v_log_f32_e32 v53, v53
	s_nop 0
	v_mul_f32_e32 v54, 0x3f317217, v53
	v_fma_f32 v54, v53, s57, -v54
	v_fmac_f32_e32 v54, 0x3377d1cf, v53
	v_fmac_f32_e32 v54, 0x3f317217, v53
	v_cmp_lt_f32_e64 s[38:39], |v53|, s58
	s_nop 1
	v_cndmask_b32_e64 v53, v53, v54, s[38:39]
	v_cndmask_b32_e32 v54, 0, v229, vcc
	v_sub_f32_e32 v53, v53, v54
	v_sub_f32_e32 v93, v52, v53
	ds_read_b128 v[52:55], v72 offset:64896
	s_waitcnt lgkmcnt(0)
	v_fma_f32 v56, v51, v52, v88
	v_fmac_f32_e32 v56, v65, v53
	v_fmac_f32_e32 v56, v67, v54
	v_fmac_f32_e32 v56, v71, v55
	ds_read_b128 v[52:55], v72 offset:64912
	s_waitcnt lgkmcnt(0)
	v_fmac_f32_e32 v56, v76, v52
	v_fmac_f32_e32 v56, v77, v53
	v_fmac_f32_e32 v56, v78, v54
	v_fmac_f32_e32 v56, v79, v55
	ds_read_b128 v[52:55], v72 offset:64928
	s_waitcnt lgkmcnt(0)
	v_fmac_f32_e32 v56, v80, v52
	v_fmac_f32_e32 v56, v81, v53
	v_fmac_f32_e32 v56, v82, v54
	v_fmac_f32_e32 v56, v83, v55
	ds_read_b128 v[52:55], v72 offset:64944
	s_waitcnt lgkmcnt(0)
	v_fmac_f32_e32 v56, v84, v52
	v_fmac_f32_e32 v56, v85, v53
	v_fmac_f32_e32 v56, v86, v54
	v_fmac_f32_e32 v56, v87, v55
	v_mul_f32_e64 v53, |v56|, s55
	v_exp_f32_e32 v53, v53
	v_min_f32_e32 v52, 0, v56
	v_add_f32_e32 v53, 1.0, v53
	v_cmp_gt_f32_e32 vcc, s33, v53
	s_nop 1
	v_cndmask_b32_e64 v54, 0, 32, vcc
	v_ldexp_f32 v53, v53, v54
	v_log_f32_e32 v53, v53
	s_nop 0
	v_mul_f32_e32 v54, 0x3f317217, v53
	v_fma_f32 v54, v53, s57, -v54
	v_fmac_f32_e32 v54, 0x3377d1cf, v53
	v_fmac_f32_e32 v54, 0x3f317217, v53
	v_cmp_lt_f32_e64 s[38:39], |v53|, s58
	s_nop 1
	v_cndmask_b32_e64 v53, v53, v54, s[38:39]
	v_cndmask_b32_e32 v54, 0, v229, vcc
	v_sub_f32_e32 v53, v53, v54
	v_sub_f32_e32 v94, v52, v53
	ds_read_b128 v[52:55], v72 offset:64832
	s_waitcnt lgkmcnt(0)
	v_fma_f32 v56, v51, v52, v88
	v_fmac_f32_e32 v56, v65, v53
	v_fmac_f32_e32 v56, v67, v54
	v_fmac_f32_e32 v56, v71, v55
	ds_read_b128 v[52:55], v72 offset:64848
	s_waitcnt lgkmcnt(0)
	v_fmac_f32_e32 v56, v76, v52
	v_fmac_f32_e32 v56, v77, v53
	v_fmac_f32_e32 v56, v78, v54
	v_fmac_f32_e32 v56, v79, v55
	ds_read_b128 v[52:55], v72 offset:64864
	s_waitcnt lgkmcnt(0)
	v_fmac_f32_e32 v56, v80, v52
	v_fmac_f32_e32 v56, v81, v53
	v_fmac_f32_e32 v56, v82, v54
	v_fmac_f32_e32 v56, v83, v55
	ds_read_b128 v[52:55], v72 offset:64880
	s_waitcnt lgkmcnt(0)
	v_fmac_f32_e32 v56, v84, v52
	v_fmac_f32_e32 v56, v85, v53
	v_fmac_f32_e32 v56, v86, v54
	v_fmac_f32_e32 v56, v87, v55
	v_mul_f32_e64 v53, |v56|, s55
	v_exp_f32_e32 v53, v53
	v_min_f32_e32 v52, 0, v56
	v_add_f32_e32 v53, 1.0, v53
	v_cmp_gt_f32_e32 vcc, s33, v53
	s_nop 1
	v_cndmask_b32_e64 v54, 0, 32, vcc
	v_ldexp_f32 v53, v53, v54
	v_log_f32_e32 v53, v53
	s_nop 0
	v_mul_f32_e32 v54, 0x3f317217, v53
	v_fma_f32 v54, v53, s57, -v54
	v_fmac_f32_e32 v54, 0x3377d1cf, v53
	v_fmac_f32_e32 v54, 0x3f317217, v53
	v_cmp_lt_f32_e64 s[38:39], |v53|, s58
	s_nop 1
	v_cndmask_b32_e64 v53, v53, v54, s[38:39]
	v_cndmask_b32_e32 v54, 0, v229, vcc
	v_sub_f32_e32 v53, v53, v54
	v_sub_f32_e32 v95, v52, v53
	ds_read_b128 v[52:55], v72 offset:64768
	ds_read_b128 v[56:59], v72 offset:64784
	ds_read_b128 v[60:63], v72 offset:64800
	ds_read_b128 v[72:75], v72 offset:64816
	s_waitcnt lgkmcnt(3)
	v_fmac_f32_e32 v88, v51, v52
	v_fmac_f32_e32 v88, v65, v53
	v_fmac_f32_e32 v88, v67, v54
	v_fmac_f32_e32 v88, v71, v55
	s_waitcnt lgkmcnt(2)
	v_fmac_f32_e32 v88, v76, v56
	v_fmac_f32_e32 v88, v77, v57
	v_fmac_f32_e32 v88, v78, v58
	v_fmac_f32_e32 v88, v79, v59
	s_waitcnt lgkmcnt(1)
	v_fmac_f32_e32 v88, v80, v60
	v_fmac_f32_e32 v88, v81, v61
	v_fmac_f32_e32 v88, v82, v62
	v_fmac_f32_e32 v88, v83, v63
	s_waitcnt lgkmcnt(0)
	v_fmac_f32_e32 v88, v84, v72
	v_fmac_f32_e32 v88, v85, v73
	v_fmac_f32_e32 v88, v86, v74
	v_fmac_f32_e32 v88, v87, v75
	v_mul_f32_e64 v52, |v88|, s55
	v_exp_f32_e32 v52, v52
	v_min_f32_e32 v51, 0, v88
	v_lshlrev_b32_e32 v62, 16, v27
	v_and_b32_e32 v63, 0xffff0000, v27
	v_add_f32_e32 v52, 1.0, v52
	v_cmp_gt_f32_e32 vcc, s33, v52
	v_and_or_b32 v71, v43, 32, v69
	s_nop 0
	v_cndmask_b32_e64 v53, 0, 32, vcc
	v_ldexp_f32 v52, v52, v53
	v_log_f32_e32 v52, v52
	s_nop 0
	v_mul_f32_e32 v53, 0x3f317217, v52
	v_fma_f32 v53, v52, s57, -v53
	v_fmac_f32_e32 v53, 0x3377d1cf, v52
	v_fmac_f32_e32 v53, 0x3f317217, v52
	v_cmp_lt_f32_e64 s[38:39], |v52|, s58
	s_nop 1
	v_cndmask_b32_e64 v52, v52, v53, s[38:39]
	v_cndmask_b32_e32 v53, 0, v229, vcc
	v_sub_f32_e32 v52, v52, v53
	v_sub_f32_e32 v51, v51, v52
	v_fma_f32 v51, v51, s62, 0
	v_fmamk_f32 v54, v95, 0x3d800000, v51
	v_fmamk_f32 v55, v94, 0x3d800000, v54
	v_fmamk_f32 v56, v93, 0x3d800000, v55
	v_fmamk_f32 v57, v92, 0x3d800000, v56
	v_fmamk_f32 v58, v91, 0x3d800000, v57
	v_fmamk_f32 v59, v90, 0x3d800000, v58
	v_fmamk_f32 v60, v89, 0x3d800000, v59
	v_add_u32_e32 v52, 0, v64
	ds_write_b32 v52, v60 offset:16640
	s_waitcnt lgkmcnt(0)
	s_barrier
; __device__ __forceinline__ unsigned f2bf(float f) { unsigned u = __float_as_uint(f); return (u + 0x7fffu + ((u >> 16) & 1u)) >> 16; }
; __device__ __forceinline__ u32x4 pack8(const float* v) { u32x4 w; w.x = pk2(v[0], v[1]); w.y = pk2(v[2], v[3]); w.z = pk2(v[4], v[5]); w.w = pk2(v[6], v[7]); return w; }
; __device__ __forceinline__ void unpack8(u32x4 w, float* v) { v[0] = bflo(w.x); v[1] = bfhi(w.x); v[2] = bflo(w.y); v[3] = bfhi(w.y); v[4] = bflo(w.z); v[5] = bfhi(w.z); v[6] = bflo(w.w); v[7] = bfhi(w.w); }
; __device__ __forceinline__ void gla_decay(unsigned char* lds, const float* glow_t0, const float* Wg  , const float* bg  , int dir) {
;     ...
;     float off = 0.f;
; #pragma unroll
;     for (int sg = 0; sg < 8; ++sg) { const float tv = Tot[sg * 64 + d]; if (dir == 0 ? (sg < seg) : (sg > seg)) off += tv; }
; #pragma unroll
;     for (int k = 0; k < 8; ++k) Bs[(seg * 8 + k) * 65 + d] = loc[k] + off;
;     __syncthreads();
; __device__ __forceinline__ void gla_out_item(unsigned char* lds, unsigned char* ws, const float* wgate, const float* bgate, const float* hnorm, int l, int item, bool dowrite = true) {
;     ...
;         { const int s = tid >> 3, dg = tid & 7;
;           float qv[8], kv[8];
;           unpack8(qraw, qv);
;           unpack8(kraw, kv);
; #pragma unroll
;           for (int e = 0; e < 8; ++e) { const float bv = Bs[s * 65 + dg * 8 + e]; qv[e] *= __expf(bv); kv[e] *= __expf(-bv); }
;           *(u32x4*)(QE + s * 72 + dg * 8) = pack8(qv); *(u32x4*)(KE + s * 72 + dg * 8) = pack8(kv); }
;         __syncthreads();
;         { const int rb = wid >> 1;
; #pragma unroll
;           for (int cc = 0; cc < 2; ++cc) { const int cb = (wid & 1) * 2 + cc; f32x4 a4 = (f32x4){0.f, 0.f, 0.f, 0.f};
; #pragma unroll
;               for (int kk = 0; kk < 2; ++kk) { const bf16x8 a = *(const bf16x8*)(QE + (rb * 16 + ql) * 72 + kk * 32 + g * 8); const bf16x8 bb = *(const bf16x8*)(KE + (cb * 16 + ql) * 72 + kk * 32 + g * 8);
;                   a4 = __builtin_amdgcn_mfma_f32_16x16x32_bf16(a, bb, a4, 0, 0, 0); }
; #pragma unroll
;               for (int j = 0; j < 4; ++j) { const int i = rb * 16 + g * 4 + j, ip = cb * 16 + ql; const bool keep = dir == 0 ? (ip <= i) : (ip >= i); ATT[i * 72 + ip] = (bf16_t)f2bf(keep ? a4[j] : 0.f); } } }
;         __syncthreads();
	ds_read2st64_b32 v[52:53], v50 offset0:65 offset1:66
	v_cmp_lt_i32_e32 vcc, 0, v49
	s_waitcnt lgkmcnt(0)
	v_add_f32_e32 v52, 0, v52
	v_cndmask_b32_e32 v52, 0, v52, vcc
	v_cmp_lt_i32_e32 vcc, 1, v49
	v_add_f32_e32 v53, v53, v52
	s_nop 0
	v_cndmask_b32_e32 v61, v52, v53, vcc
	ds_read2st64_b32 v[52:53], v50 offset0:67 offset1:68
	v_cmp_lt_i32_e32 vcc, 2, v49
	s_waitcnt lgkmcnt(0)
	v_add_f32_e32 v52, v52, v61
	v_cndmask_b32_e32 v52, v61, v52, vcc
	v_cmp_lt_i32_e32 vcc, 3, v49
	v_add_f32_e32 v53, v53, v52
	s_nop 0
	v_cndmask_b32_e32 v61, v52, v53, vcc
	ds_read2st64_b32 v[52:53], v50 offset0:69 offset1:70
	v_cmp_lt_i32_e32 vcc, 4, v49
	s_waitcnt lgkmcnt(0)
	v_add_f32_e32 v52, v52, v61
	v_cndmask_b32_e32 v52, v61, v52, vcc
	v_cmp_lt_i32_e32 vcc, 5, v49
	v_add_f32_e32 v53, v53, v52
	s_nop 0
	v_cndmask_b32_e32 v61, v52, v53, vcc
	ds_read2st64_b32 v[52:53], v50 offset0:71 offset1:72
	v_cmp_lt_i32_e32 vcc, 6, v49
	s_waitcnt lgkmcnt(0)
	v_add_f32_e32 v52, v52, v61
	v_cndmask_b32_e32 v52, v61, v52, vcc
	v_cmp_lt_i32_e32 vcc, 7, v49
	v_add_f32_e32 v53, v53, v52
	s_nop 0
	v_cndmask_b32_e32 v52, v52, v53, vcc
	v_add_f32_e32 v53, v51, v52
	v_mad_u64_u32 v[50:51], s[0:1], v49, s59, v[50:51]
	v_add_f32_e32 v49, v54, v52
	ds_write2_b32 v50, v53, v49 offset1:65
	v_add_f32_e32 v49, v55, v52
	v_add_f32_e32 v51, v56, v52
	ds_write2_b32 v50, v49, v51 offset0:130 offset1:195
	v_add_f32_e32 v49, v57, v52
	v_add_f32_e32 v51, v58, v52
	v_add_u32_e32 v50, 0x400, v50
	ds_write2_b32 v50, v49, v51 offset0:4 offset1:69
	v_add_f32_e32 v49, v59, v52
	v_add_f32_e32 v51, v60, v52
	ds_write2_b32 v50, v49, v51 offset0:134 offset1:199
	s_waitcnt lgkmcnt(0)
	s_barrier
	ds_read2_b32 v[52:53], v48 offset1:1
	v_lshlrev_b32_e32 v50, 16, v24
	v_and_b32_e32 v51, 0xffff0000, v24
	v_cmp_gt_i32_e32 vcc, v71, v39
	s_waitcnt lgkmcnt(0)
	v_mul_f32_e32 v49, 0x3fb8aa3b, v52
	v_exp_f32_e32 v54, v49
	v_mul_f32_e32 v49, 0xbfb8aa3b, v52
	v_mul_f32_e32 v24, 0xbfb8aa3b, v53
	v_exp_f32_e32 v56, v49
	v_exp_f32_e32 v57, v24
	v_mul_f32_e32 v49, 0x3fb8aa3b, v53
	v_lshlrev_b32_e32 v52, 16, v20
	v_and_b32_e32 v53, 0xffff0000, v20
	v_pk_mul_f32 v[74:75], v[56:57], v[52:53]
	ds_read2_b32 v[56:57], v48 offset0:2 offset1:3
	v_exp_f32_e32 v55, v49
	s_waitcnt lgkmcnt(0)
	v_mul_f32_e32 v20, 0x3fb8aa3b, v56
	v_exp_f32_e32 v58, v20
	v_mul_f32_e32 v20, 0xbfb8aa3b, v56
	v_exp_f32_e32 v24, v20
	v_mul_f32_e32 v20, 0x3fb8aa3b, v57
	v_exp_f32_e32 v59, v20
	v_mul_f32_e32 v20, 0xbfb8aa3b, v57
	v_pk_mul_f32 v[72:73], v[54:55], v[50:51]
	v_lshlrev_b32_e32 v54, 16, v25
	v_and_b32_e32 v55, 0xffff0000, v25
	v_exp_f32_e32 v25, v20
	v_lshlrev_b32_e32 v56, 16, v21
	v_and_b32_e32 v57, 0xffff0000, v21
	ds_read2_b32 v[20:21], v48 offset0:4 offset1:5
	v_pk_mul_f32 v[76:77], v[58:59], v[54:55]
	v_lshlrev_b32_e32 v58, 16, v26
	v_and_b32_e32 v59, 0xffff0000, v26
	v_pk_mul_f32 v[24:25], v[24:25], v[56:57]
	s_waitcnt lgkmcnt(0)
	v_mul_f32_e32 v49, 0x3fb8aa3b, v20
	v_exp_f32_e32 v60, v49
	v_mul_f32_e32 v49, 0x3fb8aa3b, v21
	v_mul_f32_e32 v20, 0xbfb8aa3b, v20
	v_exp_f32_e32 v61, v49
	v_mul_f32_e32 v21, 0xbfb8aa3b, v21
	v_exp_f32_e32 v20, v20
	v_exp_f32_e32 v21, v21
	v_pk_mul_f32 v[78:79], v[60:61], v[58:59]
	v_lshlrev_b32_e32 v60, 16, v22
	v_and_b32_e32 v61, 0xffff0000, v22
	v_pk_mul_f32 v[80:81], v[20:21], v[60:61]
	ds_read2_b32 v[20:21], v48 offset0:6 offset1:7
	v_mad_u32_u24 v49, v71, s76, v66
	v_or_b32_e32 v66, 1, v39
	v_cmp_le_i32_e64 s[38:39], v71, v66
	s_waitcnt lgkmcnt(0)
	v_mul_f32_e32 v22, 0x3fb8aa3b, v20
	v_exp_f32_e32 v64, v22
	v_mul_f32_e32 v22, 0x3fb8aa3b, v21
	v_mul_f32_e32 v20, 0xbfb8aa3b, v20
	v_exp_f32_e32 v65, v22
	v_mul_f32_e32 v21, 0xbfb8aa3b, v21
	v_exp_f32_e32 v20, v20
	v_exp_f32_e32 v21, v21
	v_pk_mul_f32 v[26:27], v[64:65], v[62:63]
	v_lshlrev_b32_e32 v64, 16, v23
	v_and_b32_e32 v65, 0xffff0000, v23
	v_pk_mul_f32 v[82:83], v[20:21], v[64:65]
	v_cvt_pk_bf16_f32 v20, v72, v73
	v_cvt_pk_bf16_f32 v21, v76, v77
	v_cvt_pk_bf16_f32 v22, v78, v79
	v_cvt_pk_bf16_f32 v23, v26, v27
	ds_write_b128 v42, v[20:23] offset:18688
	v_cvt_pk_bf16_f32 v20, v74, v75
	v_cvt_pk_bf16_f32 v21, v24, v25
	v_cvt_pk_bf16_f32 v22, v80, v81
	v_cvt_pk_bf16_f32 v23, v82, v83
	ds_write_b128 v42, v[20:23] offset:27904
	s_waitcnt lgkmcnt(0)
	s_barrier
	ds_read_b128 v[20:23], v38 offset:18688
	ds_read_b128 v[24:27], v49 offset:27904
	s_waitcnt lgkmcnt(0)
	v_mfma_f32_16x16x32_bf16 v[20:23], v[20:23], v[24:27], 0
	ds_read_b128 v[24:27], v38 offset:18752
	ds_read_b128 v[72:75], v49 offset:27968
	s_waitcnt lgkmcnt(0)
	v_mfma_f32_16x16x32_bf16 v[20:23], v[24:27], v[72:75], v[20:23]
	v_lshlrev_b32_e32 v24, 1, v71
	v_or_b32_e32 v72, 2, v39
	v_or_b32_e32 v73, 3, v39
	s_nop 4
	v_cndmask_b32_e64 v20, v20, 0, vcc
	v_bfe_u32 v25, v20, 16, 1
	v_add3_u32 v20, v20, v25, s86
	v_mul_lo_u32 v25, v39, s76
	v_add3_u32 v43, 0, v24, v25
	ds_write_b16_d16_hi v43, v20 offset:37120
	v_cndmask_b32_e64 v20, 0, v21, s[38:39]
	v_bfe_u32 v21, v20, 16, 1
	v_add3_u32 v20, v20, v21, s86
	v_cmp_le_i32_e64 s[38:39], v71, v72
	ds_write_b16_d16_hi v43, v20 offset:37264
	v_or_b32_e32 v74, 16, v71
	v_cndmask_b32_e64 v20, 0, v22, s[38:39]
	v_bfe_u32 v21, v20, 16, 1
	v_add3_u32 v20, v20, v21, s86
	v_cmp_le_i32_e64 s[38:39], v71, v73
	ds_write_b16_d16_hi v43, v20 offset:37408
	v_cmp_le_i32_e64 s[40:41], v74, v66
	v_cndmask_b32_e64 v20, 0, v23, s[38:39]
	v_bfe_u32 v21, v20, 16, 1
	v_add3_u32 v20, v20, v21, s86
	ds_write_b16_d16_hi v43, v20 offset:37552
	ds_read_b128 v[20:23], v38 offset:18688
	ds_read_b128 v[24:27], v49 offset:30208
	s_waitcnt lgkmcnt(0)
	v_mfma_f32_16x16x32_bf16 v[20:23], v[20:23], v[24:27], 0
	ds_read_b128 v[24:27], v38 offset:18752
	ds_read_b128 v[76:79], v49 offset:30272
	v_cmp_gt_i32_e64 s[38:39], v74, v39
	v_mov_b32_e32 v75, v203
	s_waitcnt lgkmcnt(0)
	v_mfma_f32_16x16x32_bf16 v[20:23], v[24:27], v[76:79], v[20:23]
	s_nop 7
	v_cndmask_b32_e64 v20, v20, 0, s[38:39]
	v_bfe_u32 v24, v20, 16, 1
	v_add3_u32 v20, v20, v24, s86
	ds_write_b16_d16_hi v43, v20 offset:37152
	v_cndmask_b32_e64 v20, 0, v21, s[40:41]
	v_bfe_u32 v21, v20, 16, 1
	v_add3_u32 v20, v20, v21, s86
	v_cmp_le_i32_e64 s[40:41], v74, v72
	ds_write_b16_d16_hi v43, v20 offset:37296
	s_nop 0
	v_cndmask_b32_e64 v20, 0, v22, s[40:41]
	v_bfe_u32 v21, v20, 16, 1
	v_add3_u32 v20, v20, v21, s86
	v_cmp_le_i32_e64 s[40:41], v74, v73
	ds_write_b16_d16_hi v43, v20 offset:37440
	s_nop 0
	v_cndmask_b32_e64 v20, 0, v23, s[40:41]
	v_bfe_u32 v21, v20, 16, 1
	v_add3_u32 v20, v20, v21, s86
	ds_write_b16_d16_hi v43, v20 offset:37584
	s_waitcnt lgkmcnt(0)
	s_barrier
; __device__ __forceinline__ void gla_decay(unsigned char* lds, const float* glow_t0, const float* Wg  , const float* bg  , int dir) {
;     ...
;     { const int s = tid >> 3, q = tid & 7;
;       const float* gp = glow_t0 + (size_t)s * 32 + dir * 16 + q * 2;
;       GLs[s * 16 + q * 2] = gp[0]; GLs[s * 16 + q * 2 + 1] = gp[1]; }
;     const int d = tid & 63, seg = tid >> 6;
;     float w[16];
; #pragma unroll
;     for (int r = 0; r < 16; ++r) w[r] = Wg[r * 256 + d];
;     const float bias = bg[d];
;     __syncthreads();
;     float loc[8];
; #pragma unroll
;     for (int k = 0; k < 8; ++k) { const float* gl = GLs + (seg * 8 + k) * 16; float a = bias;
; #pragma unroll
;         for (int r = 0; r < 16; ++r) a += gl[r] * w[r];
;         loc[k] = (fminf(a, 0.f) - __logf(1.f + __expf(-fabsf(a)))) * (1.f / 16.f); }
; __device__ __forceinline__ void gla_out_item(unsigned char* lds, unsigned char* ws, const float* wgate, const float* bgate, const float* hnorm, int l, int item, bool dowrite = true) {
;     ...
;           for (int kk = 0; kk < 2; ++kk) {
;               const bf16x8 bv = *(const bf16x8*)(Vt + (wid * 16 + ql) * 72 + kk * 32 + g * 8);
;               const bf16x8 bs = dir == 0 ? sfr[0][kk] : sfr[1][kk];
; #pragma unroll
;               for (int rb = 0; rb < 4; ++rb) {
;                   const bf16x8 a1 = *(const bf16x8*)(ATT + (rb * 16 + ql) * 72 + kk * 32 + g * 8);
;                   const bf16x8 a2 = *(const bf16x8*)(QE + (rb * 16 + ql) * 72 + kk * 32 + g * 8);
;                   oacc[rb] = __builtin_amdgcn_mfma_f32_16x16x32_bf16(a1, bv, oacc[rb], 0, 0, 0);
;                   oacc[rb] = __builtin_amdgcn_mfma_f32_16x16x32_bf16(a2, bs, oacc[rb], 0, 0, 0);
;               } } }
	ds_read_b128 v[20:23], v34 offset:46336
	ds_read_b128 v[24:27], v35 offset:37120
	ds_read_b128 v[76:79], v35 offset:18688
	s_waitcnt lgkmcnt(1)
	v_mfma_f32_16x16x32_bf16 v[24:27], v[24:27], v[20:23], 0
	s_add_u32 s40, s48, s28
	s_addc_u32 s41, s49, s29
	s_add_u32 s48, s53, s34
	s_waitcnt lgkmcnt(0)
	v_mfma_f32_16x16x32_bf16 v[24:27], v[76:79], v[16:19], v[24:27]
	ds_read_b128 v[76:79], v35 offset:39424
	ds_read_b128 v[80:83], v35 offset:20992
	s_addc_u32 s49, s54, s35
	s_waitcnt lgkmcnt(1)
	v_mfma_f32_16x16x32_bf16 v[76:79], v[76:79], v[20:23], 0
	s_waitcnt lgkmcnt(0)
	v_mfma_f32_16x16x32_bf16 v[76:79], v[80:83], v[16:19], v[76:79]
	ds_read_b128 v[80:83], v35 offset:41728
	ds_read_b128 v[84:87], v35 offset:23296
	s_waitcnt lgkmcnt(1)
	v_mfma_f32_16x16x32_bf16 v[80:83], v[80:83], v[20:23], 0
	s_waitcnt lgkmcnt(0)
	v_mfma_f32_16x16x32_bf16 v[80:83], v[84:87], v[16:19], v[80:83]
	ds_read_b128 v[84:87], v35 offset:44032
	ds_read_b128 v[88:91], v35 offset:25600
	s_waitcnt lgkmcnt(1)
	v_mfma_f32_16x16x32_bf16 v[20:23], v[84:87], v[20:23], 0
	s_waitcnt lgkmcnt(0)
	v_mfma_f32_16x16x32_bf16 v[84:87], v[88:91], v[16:19], v[20:23]
	ds_read_b128 v[88:91], v34 offset:46400
	ds_read_b128 v[16:19], v35 offset:37184
	s_nop 3
	ds_read_b128 v[20:23], v35 offset:18752
	s_waitcnt lgkmcnt(1)
	v_mfma_f32_16x16x32_bf16 v[16:19], v[16:19], v[88:91], v[24:27]
	s_waitcnt lgkmcnt(0)
	v_mfma_f32_16x16x32_bf16 v[16:19], v[20:23], v[28:31], v[16:19]
	ds_read_b128 v[20:23], v35 offset:39488
	ds_read_b128 v[24:27], v35 offset:21056
	s_waitcnt lgkmcnt(1)
	v_mfma_f32_16x16x32_bf16 v[20:23], v[20:23], v[88:91], v[76:79]
	s_waitcnt lgkmcnt(0)
	v_mfma_f32_16x16x32_bf16 v[20:23], v[24:27], v[28:31], v[20:23]
	ds_read_b128 v[24:27], v35 offset:41792
	ds_read_b128 v[76:79], v35 offset:23360
	s_waitcnt lgkmcnt(1)
	v_mfma_f32_16x16x32_bf16 v[24:27], v[24:27], v[88:91], v[80:83]
	s_waitcnt lgkmcnt(0)
	v_mfma_f32_16x16x32_bf16 v[24:27], v[76:79], v[28:31], v[24:27]
	ds_read_b128 v[76:79], v35 offset:44096
	ds_read_b128 v[80:83], v35 offset:25664
	s_waitcnt lgkmcnt(0)
	s_barrier
	v_mfma_f32_16x16x32_bf16 v[76:79], v[76:79], v[88:91], v[84:87]
	s_nop 0
	v_ashrrev_i32_e32 v66, 3, v75
	v_ashrrev_i32_e32 v67, 31, v66
	v_mfma_f32_16x16x32_bf16 v[28:31], v[80:83], v[28:31], v[76:79]
	v_lshlrev_b32_e32 v92, 2, v75
	s_nop 2
	v_lshlrev_b64 v[76:77], 7, v[66:67]
	v_lshlrev_b32_e32 v67, 3, v75
	v_lshl_add_u64 v[76:77], s[42:43], 0, v[76:77]
	v_and_b32_e32 v78, 56, v67
	v_mov_b32_e32 v79, v36
	v_lshl_add_u64 v[76:77], v[76:77], 0, v[78:79]
	v_lshlrev_b32_e32 v66, 6, v66
	v_add3_u32 v78, 0, v66, v78
	global_load_dwordx2 v[66:67], v[76:77], off offset:64
	v_ashrrev_i32_e32 v75, 6, v75
	v_lshl_add_u32 v88, v75, 9, 0
	s_waitcnt vmcnt(0)
	ds_write_b64 v78, v[66:67] offset:64768
	v_and_b32_e32 v66, 0xfc, v92
	v_mov_b32_e32 v67, v36
	v_lshl_add_u64 v[76:77], s[40:41], 0, v[66:67]
	global_load_dword v67, v66, s[40:41]
	global_load_dword v93, v66, s[40:41] offset:1024
	global_load_dword v94, v66, s[40:41] offset:2048
	global_load_dword v95, v66, s[40:41] offset:3072
	v_add_co_u32_e64 v78, s[40:41], s69, v76
	s_nop 1
	v_addc_co_u32_e64 v79, s[40:41], 0, v77, s[40:41]
	v_add_co_u32_e64 v80, s[40:41], s67, v76
	s_nop 1
	v_addc_co_u32_e64 v81, s[40:41], 0, v77, s[40:41]
	v_add_co_u32_e64 v76, s[40:41], s66, v76
	global_load_dword v96, v[80:81], off offset:-4096
	global_load_dword v97, v[78:79], off offset:1024
	global_load_dword v98, v[78:79], off offset:2048
	global_load_dword v99, v[78:79], off offset:3072
	global_load_dword v100, v[80:81], off
	global_load_dword v101, v[80:81], off offset:1024
	global_load_dword v102, v[80:81], off offset:2048
	global_load_dword v103, v[80:81], off offset:3072
	v_addc_co_u32_e64 v77, s[40:41], 0, v77, s[40:41]
	global_load_dword v104, v[76:77], off
	global_load_dword v105, v[76:77], off offset:1024
	global_load_dword v106, v[76:77], off offset:2048
	global_load_dword v107, v[76:77], off offset:3072
	global_load_dword v108, v66, s[48:49]
	s_waitcnt lgkmcnt(0)
	s_barrier
	ds_read_b128 v[76:79], v88 offset:65216
	v_add_u32_e32 v66, 0, v66
	s_waitcnt vmcnt(0) lgkmcnt(0)
	v_fma_f32 v80, v67, v76, v108
	v_fmac_f32_e32 v80, v93, v77
	v_fmac_f32_e32 v80, v94, v78
	v_fmac_f32_e32 v80, v95, v79
	ds_read_b128 v[76:79], v88 offset:65232
	s_waitcnt lgkmcnt(0)
	v_fmac_f32_e32 v80, v96, v76
	v_fmac_f32_e32 v80, v97, v77
	v_fmac_f32_e32 v80, v98, v78
	v_fmac_f32_e32 v80, v99, v79
	ds_read_b128 v[76:79], v88 offset:65248
	s_waitcnt lgkmcnt(0)
	v_fmac_f32_e32 v80, v100, v76
	v_fmac_f32_e32 v80, v101, v77
	v_fmac_f32_e32 v80, v102, v78
	v_fmac_f32_e32 v80, v103, v79
	ds_read_b128 v[76:79], v88 offset:65264
	s_waitcnt lgkmcnt(0)
	v_fmac_f32_e32 v80, v104, v76
	v_fmac_f32_e32 v80, v105, v77
	v_fmac_f32_e32 v80, v106, v78
	v_fmac_f32_e32 v80, v107, v79
	v_mul_f32_e64 v77, |v80|, s55
	v_exp_f32_e32 v77, v77
	v_min_f32_e32 v76, 0, v80
	v_add_f32_e32 v77, 1.0, v77
	v_cmp_gt_f32_e64 s[40:41], s33, v77
	s_nop 1
	v_cndmask_b32_e64 v78, 0, 32, s[40:41]
	v_ldexp_f32 v77, v77, v78
	v_log_f32_e32 v77, v77
	s_nop 0
	v_mul_f32_e32 v78, 0x3f317217, v77
	v_fma_f32 v78, v77, s57, -v78
	v_fmac_f32_e32 v78, 0x3377d1cf, v77
	v_fmac_f32_e32 v78, 0x3f317217, v77
	v_cmp_lt_f32_e64 s[42:43], |v77|, s58
	s_nop 1
	v_cndmask_b32_e64 v77, v77, v78, s[42:43]
	v_cndmask_b32_e64 v78, 0, v229, s[40:41]
	v_sub_f32_e32 v77, v77, v78
	v_sub_f32_e32 v109, v76, v77
	ds_read_b128 v[76:79], v88 offset:65152
	s_waitcnt lgkmcnt(0)
	v_fma_f32 v80, v67, v76, v108
	v_fmac_f32_e32 v80, v93, v77
	v_fmac_f32_e32 v80, v94, v78
	v_fmac_f32_e32 v80, v95, v79
	ds_read_b128 v[76:79], v88 offset:65168
	s_waitcnt lgkmcnt(0)
; __device__ __forceinline__ void gla_decay(unsigned char* lds, const float* glow_t0, const float* Wg  , const float* bg  , int dir) {
;     ...
;     for (int k = 0; k < 8; ++k) { const float* gl = GLs + (seg * 8 + k) * 16; float a = bias;
; #pragma unroll
;         for (int r = 0; r < 16; ++r) a += gl[r] * w[r];
;         loc[k] = (fminf(a, 0.f) - __logf(1.f + __expf(-fabsf(a)))) * (1.f / 16.f); }
	v_fmac_f32_e32 v80, v96, v76
	v_fmac_f32_e32 v80, v97, v77
	v_fmac_f32_e32 v80, v98, v78
	v_fmac_f32_e32 v80, v99, v79
	ds_read_b128 v[76:79], v88 offset:65184
	s_waitcnt lgkmcnt(0)
	v_fmac_f32_e32 v80, v100, v76
	v_fmac_f32_e32 v80, v101, v77
	v_fmac_f32_e32 v80, v102, v78
	v_fmac_f32_e32 v80, v103, v79
	ds_read_b128 v[76:79], v88 offset:65200
	s_waitcnt lgkmcnt(0)
	v_fmac_f32_e32 v80, v104, v76
	v_fmac_f32_e32 v80, v105, v77
	v_fmac_f32_e32 v80, v106, v78
	v_fmac_f32_e32 v80, v107, v79
	v_mul_f32_e64 v77, |v80|, s55
	v_exp_f32_e32 v77, v77
	v_min_f32_e32 v76, 0, v80
	v_add_f32_e32 v77, 1.0, v77
	v_cmp_gt_f32_e64 s[40:41], s33, v77
	s_nop 1
	v_cndmask_b32_e64 v78, 0, 32, s[40:41]
	v_ldexp_f32 v77, v77, v78
	v_log_f32_e32 v77, v77
	s_nop 0
	v_mul_f32_e32 v78, 0x3f317217, v77
	v_fma_f32 v78, v77, s57, -v78
	v_fmac_f32_e32 v78, 0x3377d1cf, v77
	v_fmac_f32_e32 v78, 0x3f317217, v77
	v_cmp_lt_f32_e64 s[42:43], |v77|, s58
	s_nop 1
	v_cndmask_b32_e64 v77, v77, v78, s[42:43]
	v_cndmask_b32_e64 v78, 0, v229, s[40:41]
	v_sub_f32_e32 v77, v77, v78
	v_sub_f32_e32 v110, v76, v77
	ds_read_b128 v[76:79], v88 offset:65088
	s_waitcnt lgkmcnt(0)
	v_fma_f32 v80, v67, v76, v108
	v_fmac_f32_e32 v80, v93, v77
	v_fmac_f32_e32 v80, v94, v78
	v_fmac_f32_e32 v80, v95, v79
	ds_read_b128 v[76:79], v88 offset:65104
	s_waitcnt lgkmcnt(0)
	v_fmac_f32_e32 v80, v96, v76
	v_fmac_f32_e32 v80, v97, v77
	v_fmac_f32_e32 v80, v98, v78
	v_fmac_f32_e32 v80, v99, v79
	ds_read_b128 v[76:79], v88 offset:65120
	s_waitcnt lgkmcnt(0)
	v_fmac_f32_e32 v80, v100, v76
	v_fmac_f32_e32 v80, v101, v77
	v_fmac_f32_e32 v80, v102, v78
	v_fmac_f32_e32 v80, v103, v79
	ds_read_b128 v[76:79], v88 offset:65136
	s_waitcnt lgkmcnt(0)
	v_fmac_f32_e32 v80, v104, v76
	v_fmac_f32_e32 v80, v105, v77
	v_fmac_f32_e32 v80, v106, v78
	v_fmac_f32_e32 v80, v107, v79
	v_mul_f32_e64 v77, |v80|, s55
	v_exp_f32_e32 v77, v77
	v_min_f32_e32 v76, 0, v80
	v_add_f32_e32 v77, 1.0, v77
	v_cmp_gt_f32_e64 s[40:41], s33, v77
	s_nop 1
	v_cndmask_b32_e64 v78, 0, 32, s[40:41]
	v_ldexp_f32 v77, v77, v78
	v_log_f32_e32 v77, v77
	s_nop 0
	v_mul_f32_e32 v78, 0x3f317217, v77
	v_fma_f32 v78, v77, s57, -v78
	v_fmac_f32_e32 v78, 0x3377d1cf, v77
	v_fmac_f32_e32 v78, 0x3f317217, v77
	v_cmp_lt_f32_e64 s[42:43], |v77|, s58
	s_nop 1
	v_cndmask_b32_e64 v77, v77, v78, s[42:43]
	v_cndmask_b32_e64 v78, 0, v229, s[40:41]
	v_sub_f32_e32 v77, v77, v78
	v_sub_f32_e32 v111, v76, v77
	ds_read_b128 v[76:79], v88 offset:65024
	s_waitcnt lgkmcnt(0)
	v_fma_f32 v80, v67, v76, v108
	v_fmac_f32_e32 v80, v93, v77
	v_fmac_f32_e32 v80, v94, v78
	v_fmac_f32_e32 v80, v95, v79
	ds_read_b128 v[76:79], v88 offset:65040
	s_waitcnt lgkmcnt(0)
	v_fmac_f32_e32 v80, v96, v76
	v_fmac_f32_e32 v80, v97, v77
	v_fmac_f32_e32 v80, v98, v78
	v_fmac_f32_e32 v80, v99, v79
	ds_read_b128 v[76:79], v88 offset:65056
	s_waitcnt lgkmcnt(0)
	v_fmac_f32_e32 v80, v100, v76
	v_fmac_f32_e32 v80, v101, v77
	v_fmac_f32_e32 v80, v102, v78
	v_fmac_f32_e32 v80, v103, v79
	ds_read_b128 v[76:79], v88 offset:65072
	s_waitcnt lgkmcnt(0)
	v_fmac_f32_e32 v80, v104, v76
	v_fmac_f32_e32 v80, v105, v77
	v_fmac_f32_e32 v80, v106, v78
	v_fmac_f32_e32 v80, v107, v79
	v_mul_f32_e64 v77, |v80|, s55
	v_exp_f32_e32 v77, v77
	v_min_f32_e32 v76, 0, v80
	v_add_f32_e32 v77, 1.0, v77
	v_cmp_gt_f32_e64 s[40:41], s33, v77
	s_nop 1
	v_cndmask_b32_e64 v78, 0, 32, s[40:41]
	v_ldexp_f32 v77, v77, v78
	v_log_f32_e32 v77, v77
	s_nop 0
	v_mul_f32_e32 v78, 0x3f317217, v77
	v_fma_f32 v78, v77, s57, -v78
	v_fmac_f32_e32 v78, 0x3377d1cf, v77
	v_fmac_f32_e32 v78, 0x3f317217, v77
	v_cmp_lt_f32_e64 s[42:43], |v77|, s58
	s_nop 1
	v_cndmask_b32_e64 v77, v77, v78, s[42:43]
	v_cndmask_b32_e64 v78, 0, v229, s[40:41]
	v_sub_f32_e32 v77, v77, v78
	v_sub_f32_e32 v112, v76, v77
	ds_read_b128 v[76:79], v88 offset:64960
	s_waitcnt lgkmcnt(0)
	v_fma_f32 v80, v67, v76, v108
	v_fmac_f32_e32 v80, v93, v77
	v_fmac_f32_e32 v80, v94, v78
	v_fmac_f32_e32 v80, v95, v79
	ds_read_b128 v[76:79], v88 offset:64976
	s_waitcnt lgkmcnt(0)
	v_fmac_f32_e32 v80, v96, v76
	v_fmac_f32_e32 v80, v97, v77
	v_fmac_f32_e32 v80, v98, v78
	v_fmac_f32_e32 v80, v99, v79
	ds_read_b128 v[76:79], v88 offset:64992
	s_waitcnt lgkmcnt(0)
	v_fmac_f32_e32 v80, v100, v76
	v_fmac_f32_e32 v80, v101, v77
	v_fmac_f32_e32 v80, v102, v78
	v_fmac_f32_e32 v80, v103, v79
	ds_read_b128 v[76:79], v88 offset:65008
	s_waitcnt lgkmcnt(0)
	v_fmac_f32_e32 v80, v104, v76
	v_fmac_f32_e32 v80, v105, v77
	v_fmac_f32_e32 v80, v106, v78
	v_fmac_f32_e32 v80, v107, v79
	v_mul_f32_e64 v77, |v80|, s55
	v_exp_f32_e32 v77, v77
	v_min_f32_e32 v76, 0, v80
	v_add_f32_e32 v77, 1.0, v77
	v_cmp_gt_f32_e64 s[40:41], s33, v77
	s_nop 1
	v_cndmask_b32_e64 v78, 0, 32, s[40:41]
	v_ldexp_f32 v77, v77, v78
	v_log_f32_e32 v77, v77
	s_nop 0
	v_mul_f32_e32 v78, 0x3f317217, v77
	v_fma_f32 v78, v77, s57, -v78
	v_fmac_f32_e32 v78, 0x3377d1cf, v77
	v_fmac_f32_e32 v78, 0x3f317217, v77
	v_cmp_lt_f32_e64 s[42:43], |v77|, s58
	s_nop 1
	v_cndmask_b32_e64 v77, v77, v78, s[42:43]
	v_cndmask_b32_e64 v78, 0, v229, s[40:41]
	v_sub_f32_e32 v77, v77, v78
	v_sub_f32_e32 v113, v76, v77
	ds_read_b128 v[76:79], v88 offset:64896
	s_waitcnt lgkmcnt(0)
	v_fma_f32 v80, v67, v76, v108
	v_fmac_f32_e32 v80, v93, v77
	v_fmac_f32_e32 v80, v94, v78
	v_fmac_f32_e32 v80, v95, v79
	ds_read_b128 v[76:79], v88 offset:64912
	s_waitcnt lgkmcnt(0)
	v_fmac_f32_e32 v80, v96, v76
	v_fmac_f32_e32 v80, v97, v77
	v_fmac_f32_e32 v80, v98, v78
	v_fmac_f32_e32 v80, v99, v79
	ds_read_b128 v[76:79], v88 offset:64928
	s_waitcnt lgkmcnt(0)
	v_fmac_f32_e32 v80, v100, v76
	v_fmac_f32_e32 v80, v101, v77
	v_fmac_f32_e32 v80, v102, v78
	v_fmac_f32_e32 v80, v103, v79
	ds_read_b128 v[76:79], v88 offset:64944
	s_waitcnt lgkmcnt(0)
; __device__ __forceinline__ void gla_decay(unsigned char* lds, const float* glow_t0, const float* Wg  , const float* bg  , int dir) {
;     ...
;     for (int k = 0; k < 8; ++k) { const float* gl = GLs + (seg * 8 + k) * 16; float a = bias;
; #pragma unroll
;         for (int r = 0; r < 16; ++r) a += gl[r] * w[r];
;         loc[k] = (fminf(a, 0.f) - __logf(1.f + __expf(-fabsf(a)))) * (1.f / 16.f); }
;     float run = 0.f;
;     if (dir == 0) {
; #pragma unroll
;         for (int k = 0; k < 8; ++k) { run += loc[k]; loc[k] = run; }
;     } else {
; #pragma unroll
;         for (int k = 7; k >= 0; --k) { run += loc[k]; loc[k] = run; }
;     }
;     Tot[seg * 64 + d] = run;
;     __syncthreads();
;     float off = 0.f;
; #pragma unroll
;     for (int sg = 0; sg < 8; ++sg) { const float tv = Tot[sg * 64 + d]; if (dir == 0 ? (sg < seg) : (sg > seg)) off += tv; }
; #pragma unroll
;     for (int k = 0; k < 8; ++k) Bs[(seg * 8 + k) * 65 + d] = loc[k] + off;
;     __syncthreads();
	v_fmac_f32_e32 v80, v104, v76
	v_fmac_f32_e32 v80, v105, v77
	v_fmac_f32_e32 v80, v106, v78
	v_fmac_f32_e32 v80, v107, v79
	v_mul_f32_e64 v77, |v80|, s55
	v_exp_f32_e32 v77, v77
	v_min_f32_e32 v76, 0, v80
	v_add_f32_e32 v77, 1.0, v77
	v_cmp_gt_f32_e64 s[40:41], s33, v77
	s_nop 1
	v_cndmask_b32_e64 v78, 0, 32, s[40:41]
	v_ldexp_f32 v77, v77, v78
	v_log_f32_e32 v77, v77
	s_nop 0
	v_mul_f32_e32 v78, 0x3f317217, v77
	v_fma_f32 v78, v77, s57, -v78
	v_fmac_f32_e32 v78, 0x3377d1cf, v77
	v_fmac_f32_e32 v78, 0x3f317217, v77
	v_cmp_lt_f32_e64 s[42:43], |v77|, s58
	s_nop 1
	v_cndmask_b32_e64 v77, v77, v78, s[42:43]
	v_cndmask_b32_e64 v78, 0, v229, s[40:41]
	v_sub_f32_e32 v77, v77, v78
	v_sub_f32_e32 v114, v76, v77
	ds_read_b128 v[76:79], v88 offset:64832
	s_waitcnt lgkmcnt(0)
	v_fma_f32 v80, v67, v76, v108
	v_fmac_f32_e32 v80, v93, v77
	v_fmac_f32_e32 v80, v94, v78
	v_fmac_f32_e32 v80, v95, v79
	ds_read_b128 v[76:79], v88 offset:64848
	s_waitcnt lgkmcnt(0)
	v_fmac_f32_e32 v80, v96, v76
	v_fmac_f32_e32 v80, v97, v77
	v_fmac_f32_e32 v80, v98, v78
	v_fmac_f32_e32 v80, v99, v79
	ds_read_b128 v[76:79], v88 offset:64864
	s_waitcnt lgkmcnt(0)
	v_fmac_f32_e32 v80, v100, v76
	v_fmac_f32_e32 v80, v101, v77
	v_fmac_f32_e32 v80, v102, v78
	v_fmac_f32_e32 v80, v103, v79
	ds_read_b128 v[76:79], v88 offset:64880
	s_waitcnt lgkmcnt(0)
	v_fmac_f32_e32 v80, v104, v76
	v_fmac_f32_e32 v80, v105, v77
	v_fmac_f32_e32 v80, v106, v78
	v_fmac_f32_e32 v80, v107, v79
	v_mul_f32_e64 v77, |v80|, s55
	v_exp_f32_e32 v77, v77
	v_min_f32_e32 v76, 0, v80
	v_add_f32_e32 v77, 1.0, v77
	v_cmp_gt_f32_e64 s[40:41], s33, v77
	s_nop 1
	v_cndmask_b32_e64 v78, 0, 32, s[40:41]
	v_ldexp_f32 v77, v77, v78
	v_log_f32_e32 v77, v77
	s_nop 0
	v_mul_f32_e32 v78, 0x3f317217, v77
	v_fma_f32 v78, v77, s57, -v78
	v_fmac_f32_e32 v78, 0x3377d1cf, v77
	v_fmac_f32_e32 v78, 0x3f317217, v77
	v_cmp_lt_f32_e64 s[42:43], |v77|, s58
	s_nop 1
	v_cndmask_b32_e64 v77, v77, v78, s[42:43]
	v_cndmask_b32_e64 v78, 0, v229, s[40:41]
	v_sub_f32_e32 v77, v77, v78
	v_sub_f32_e32 v115, v76, v77
	ds_read_b128 v[76:79], v88 offset:64768
	ds_read_b128 v[80:83], v88 offset:64784
	ds_read_b128 v[84:87], v88 offset:64800
	ds_read_b128 v[88:91], v88 offset:64816
	s_waitcnt lgkmcnt(3)
	v_fmac_f32_e32 v108, v67, v76
	v_fmac_f32_e32 v108, v93, v77
	v_fmac_f32_e32 v108, v94, v78
	v_fmac_f32_e32 v108, v95, v79
	s_waitcnt lgkmcnt(2)
	v_fmac_f32_e32 v108, v96, v80
	v_fmac_f32_e32 v108, v97, v81
	v_fmac_f32_e32 v108, v98, v82
	v_fmac_f32_e32 v108, v99, v83
	s_waitcnt lgkmcnt(1)
	v_fmac_f32_e32 v108, v100, v84
	v_fmac_f32_e32 v108, v101, v85
	v_fmac_f32_e32 v108, v102, v86
	v_fmac_f32_e32 v108, v103, v87
	s_waitcnt lgkmcnt(0)
	v_fmac_f32_e32 v108, v104, v88
	v_fmac_f32_e32 v108, v105, v89
	v_fmac_f32_e32 v108, v106, v90
	v_fmac_f32_e32 v108, v107, v91
	v_mul_f32_e64 v76, |v108|, s55
	v_exp_f32_e32 v76, v76
	v_fma_f32 v78, v109, s62, 0
	v_fmamk_f32 v79, v110, 0x3d800000, v78
	v_fmamk_f32 v80, v111, 0x3d800000, v79
	v_add_f32_e32 v76, 1.0, v76
	v_cmp_gt_f32_e64 s[40:41], s33, v76
	v_fmamk_f32 v81, v112, 0x3d800000, v80
	v_fmamk_f32 v82, v113, 0x3d800000, v81
	v_cndmask_b32_e64 v77, 0, 32, s[40:41]
	v_ldexp_f32 v76, v76, v77
	v_log_f32_e32 v76, v76
	v_min_f32_e32 v67, 0, v108
	v_fmamk_f32 v83, v114, 0x3d800000, v82
	v_fmamk_f32 v84, v115, 0x3d800000, v83
	v_mul_f32_e32 v77, 0x3f317217, v76
	v_fma_f32 v77, v76, s57, -v77
	v_fmac_f32_e32 v77, 0x3377d1cf, v76
	v_fmac_f32_e32 v77, 0x3f317217, v76
	v_cmp_lt_f32_e64 s[42:43], |v76|, s58
	s_nop 1
	v_cndmask_b32_e64 v76, v76, v77, s[42:43]
	v_cndmask_b32_e64 v77, 0, v229, s[40:41]
	v_sub_f32_e32 v76, v76, v77
	v_sub_f32_e32 v67, v67, v76
	v_fmamk_f32 v67, v67, 0x3d800000, v84
	v_add_u32_e32 v76, 0, v92
	ds_write_b32 v76, v67 offset:16640
	s_waitcnt lgkmcnt(0)
	s_barrier
	ds_read2st64_b32 v[76:77], v66 offset0:65 offset1:66
	v_cmp_gt_i32_e64 s[40:41], 0, v75
	s_waitcnt lgkmcnt(0)
	v_add_f32_e32 v76, 0, v76
	v_cndmask_b32_e64 v76, 0, v76, s[40:41]
	v_cmp_gt_i32_e64 s[40:41], 1, v75
	v_add_f32_e32 v76, v77, v76
	s_nop 0
	v_cndmask_b32_e64 v85, 0, v76, s[40:41]
	ds_read2st64_b32 v[76:77], v66 offset0:67 offset1:68
	v_cmp_gt_i32_e64 s[40:41], 2, v75
	s_waitcnt lgkmcnt(0)
	v_add_f32_e32 v76, v76, v85
	v_cndmask_b32_e64 v76, 0, v76, s[40:41]
	v_cmp_gt_i32_e64 s[40:41], 3, v75
	v_add_f32_e32 v76, v77, v76
	s_nop 0
	v_cndmask_b32_e64 v85, 0, v76, s[40:41]
	ds_read2st64_b32 v[76:77], v66 offset0:69 offset1:70
	v_cmp_gt_i32_e64 s[40:41], 4, v75
	s_waitcnt lgkmcnt(0)
	v_add_f32_e32 v76, v76, v85
	v_cndmask_b32_e64 v76, 0, v76, s[40:41]
	v_cmp_gt_i32_e64 s[40:41], 5, v75
	v_add_f32_e32 v76, v77, v76
	s_nop 0
	v_cndmask_b32_e64 v85, 0, v76, s[40:41]
	ds_read2st64_b32 v[76:77], v66 offset0:71 offset1:72
	v_cmp_gt_i32_e64 s[40:41], 6, v75
	s_waitcnt lgkmcnt(0)
	v_add_f32_e32 v76, v76, v85
	v_cndmask_b32_e64 v76, 0, v76, s[40:41]
	v_cmp_gt_i32_e64 s[40:41], 7, v75
	v_add_f32_e32 v76, v77, v76
	s_nop 0
	v_cndmask_b32_e64 v76, 0, v76, s[40:41]
	v_add_f32_e32 v77, v67, v76
	v_mad_u64_u32 v[66:67], s[0:1], v75, s59, v[66:67]
	v_add_f32_e32 v67, v84, v76
	ds_write2_b32 v66, v77, v67 offset1:65
	v_add_f32_e32 v67, v83, v76
	v_add_f32_e32 v75, v82, v76
	ds_write2_b32 v66, v67, v75 offset0:130 offset1:195
	v_add_f32_e32 v67, v81, v76
	v_add_f32_e32 v75, v80, v76
	v_add_u32_e32 v66, 0x400, v66
	ds_write2_b32 v66, v67, v75 offset0:4 offset1:69
	v_add_f32_e32 v67, v79, v76
	v_add_f32_e32 v75, v78, v76
	ds_write2_b32 v66, v67, v75 offset0:134 offset1:199
	s_waitcnt lgkmcnt(0)
	s_barrier
; __device__ __forceinline__ unsigned f2bf(float f) { unsigned u = __float_as_uint(f); return (u + 0x7fffu + ((u >> 16) & 1u)) >> 16; }
; __device__ __forceinline__ void gla_out_item(unsigned char* lds, unsigned char* ws, const float* wgate, const float* bgate, const float* hnorm, int l, int item, bool dowrite = true) {
;     ...
;         { const int s = tid >> 3, dg = tid & 7;
;           float qv[8], kv[8];
;           unpack8(qraw, qv);
;           unpack8(kraw, kv);
; #pragma unroll
;           for (int e = 0; e < 8; ++e) { const float bv = Bs[s * 65 + dg * 8 + e]; qv[e] *= __expf(bv); kv[e] *= __expf(-bv); }
;           *(u32x4*)(QE + s * 72 + dg * 8) = pack8(qv); *(u32x4*)(KE + s * 72 + dg * 8) = pack8(kv); }
;         __syncthreads();
;         { const int rb = wid >> 1;
; #pragma unroll
;           for (int cc = 0; cc < 2; ++cc) { const int cb = (wid & 1) * 2 + cc; f32x4 a4 = (f32x4){0.f, 0.f, 0.f, 0.f};
; #pragma unroll
;               for (int kk = 0; kk < 2; ++kk) { const bf16x8 a = *(const bf16x8*)(QE + (rb * 16 + ql) * 72 + kk * 32 + g * 8); const bf16x8 bb = *(const bf16x8*)(KE + (cb * 16 + ql) * 72 + kk * 32 + g * 8);
;                   a4 = __builtin_amdgcn_mfma_f32_16x16x32_bf16(a, bb, a4, 0, 0, 0); }
; #pragma unroll
;               for (int j = 0; j < 4; ++j) { const int i = rb * 16 + g * 4 + j, ip = cb * 16 + ql; const bool keep = dir == 0 ? (ip <= i) : (ip >= i); ATT[i * 72 + ip] = (bf16_t)f2bf(keep ? a4[j] : 0.f); } } }
;         __syncthreads();
;         { const int sidx = ((b * 4 + h) * 2 + dir) * 132 + c;
;           const bf16_t* st = (const bf16_t*)(ws + O_ST) + (size_t)sidx * 8192;
; #pragma unroll
;           for (int kk = 0; kk < 2; ++kk) {
;               const bf16x8 bv = *(const bf16x8*)(Vt + (wid * 16 + ql) * 72 + kk * 32 + g * 8);
;               const bf16x8 bs = dir == 0 ? sfr[0][kk] : sfr[1][kk];
; #pragma unroll
;               for (int rb = 0; rb < 4; ++rb) {
;                   const bf16x8 a1 = *(const bf16x8*)(ATT + (rb * 16 + ql) * 72 + kk * 32 + g * 8);
;                   const bf16x8 a2 = *(const bf16x8*)(QE + (rb * 16 + ql) * 72 + kk * 32 + g * 8);
;                   oacc[rb] = __builtin_amdgcn_mfma_f32_16x16x32_bf16(a1, bv, oacc[rb], 0, 0, 0);
;                   oacc[rb] = __builtin_amdgcn_mfma_f32_16x16x32_bf16(a2, bs, oacc[rb], 0, 0, 0);
;               } } }
	ds_read2_b32 v[66:67], v48 offset1:1
	v_cmp_ge_i32_e64 s[40:41], v71, v39
	s_movk_i32 s0, 0x210
	s_waitcnt lgkmcnt(0)
	v_mul_f32_e32 v75, 0x3fb8aa3b, v66
	v_exp_f32_e32 v76, v75
	v_mul_f32_e32 v66, 0xbfb8aa3b, v66
	v_mul_f32_e32 v75, 0x3fb8aa3b, v67
	v_mul_f32_e32 v67, 0xbfb8aa3b, v67
	v_exp_f32_e32 v66, v66
	v_exp_f32_e32 v67, v67
	v_exp_f32_e32 v77, v75
	v_pk_mul_f32 v[66:67], v[66:67], v[52:53]
	ds_read2_b32 v[52:53], v48 offset0:2 offset1:3
	v_pk_mul_f32 v[50:51], v[76:77], v[50:51]
	s_waitcnt lgkmcnt(0)
	v_mul_f32_e32 v75, 0x3fb8aa3b, v52
	v_exp_f32_e32 v76, v75
	v_mul_f32_e32 v52, 0xbfb8aa3b, v52
	v_mul_f32_e32 v75, 0x3fb8aa3b, v53
	v_mul_f32_e32 v53, 0xbfb8aa3b, v53
	v_exp_f32_e32 v52, v52
	v_exp_f32_e32 v53, v53
	v_exp_f32_e32 v77, v75
	v_cvt_pk_bf16_f32 v50, v50, v51
	v_pk_mul_f32 v[56:57], v[52:53], v[56:57]
	ds_read2_b32 v[52:53], v48 offset0:4 offset1:5
	v_pk_mul_f32 v[54:55], v[76:77], v[54:55]
	s_waitcnt lgkmcnt(0)
	v_mul_f32_e32 v75, 0x3fb8aa3b, v52
	v_exp_f32_e32 v76, v75
	v_mul_f32_e32 v52, 0xbfb8aa3b, v52
	v_mul_f32_e32 v75, 0x3fb8aa3b, v53
	v_mul_f32_e32 v53, 0xbfb8aa3b, v53
	v_exp_f32_e32 v52, v52
	v_exp_f32_e32 v53, v53
	v_exp_f32_e32 v77, v75
	v_cvt_pk_bf16_f32 v51, v54, v55
	v_pk_mul_f32 v[60:61], v[52:53], v[60:61]
	ds_read2_b32 v[52:53], v48 offset0:6 offset1:7
	v_pk_mul_f32 v[58:59], v[76:77], v[58:59]
	s_waitcnt lgkmcnt(0)
	v_mul_f32_e32 v48, 0x3fb8aa3b, v52
	v_exp_f32_e32 v76, v48
	v_mul_f32_e32 v48, 0xbfb8aa3b, v52
	v_exp_f32_e32 v52, v48
	v_mul_f32_e32 v48, 0x3fb8aa3b, v53
	v_exp_f32_e32 v77, v48
	v_mul_f32_e32 v48, 0xbfb8aa3b, v53
	v_exp_f32_e32 v53, v48
	v_pk_mul_f32 v[62:63], v[76:77], v[62:63]
	v_pk_mul_f32 v[64:65], v[52:53], v[64:65]
	v_cvt_pk_bf16_f32 v52, v58, v59
	v_cvt_pk_bf16_f32 v53, v62, v63
	ds_write_b128 v42, v[50:53] offset:18688
	v_cvt_pk_bf16_f32 v50, v66, v67
	v_cvt_pk_bf16_f32 v51, v56, v57
	v_cvt_pk_bf16_f32 v52, v60, v61
	v_cvt_pk_bf16_f32 v53, v64, v65
	ds_write_b128 v42, v[50:53] offset:27904
	s_waitcnt lgkmcnt(0)
	s_barrier
	ds_read_b128 v[50:53], v38 offset:18688
	ds_read_b128 v[54:57], v49 offset:27904
	s_waitcnt lgkmcnt(0)
	v_mfma_f32_16x16x32_bf16 v[50:53], v[50:53], v[54:57], 0
	ds_read_b128 v[54:57], v38 offset:18752
	ds_read_b128 v[58:61], v49 offset:27968
	v_and_b32_e32 v67, 0xffff0000, v0
	s_waitcnt lgkmcnt(0)
	v_mfma_f32_16x16x32_bf16 v[50:53], v[54:57], v[58:61], v[50:53]
	s_nop 7
	v_cndmask_b32_e64 v42, 0, v50, s[40:41]
	v_bfe_u32 v48, v42, 16, 1
	v_add3_u32 v42, v42, v48, s86
	ds_write_b16_d16_hi v43, v42 offset:37120
	v_cndmask_b32_e32 v42, 0, v51, vcc
	v_bfe_u32 v48, v42, 16, 1
	v_add3_u32 v42, v42, v48, s86
	v_cmp_ge_i32_e32 vcc, v71, v72
	ds_write_b16_d16_hi v43, v42 offset:37264
	s_nop 0
	v_cndmask_b32_e32 v42, 0, v52, vcc
	v_bfe_u32 v48, v42, 16, 1
	v_add3_u32 v42, v42, v48, s86
	v_cmp_ge_i32_e32 vcc, v71, v73
	ds_write_b16_d16_hi v43, v42 offset:37408
	s_nop 0
	v_cndmask_b32_e32 v42, 0, v53, vcc
	v_bfe_u32 v48, v42, 16, 1
	v_add3_u32 v42, v42, v48, s86
	ds_write_b16_d16_hi v43, v42 offset:37552
	ds_read_b128 v[50:53], v38 offset:18688
	ds_read_b128 v[54:57], v49 offset:30208
	s_waitcnt lgkmcnt(0)
	v_mfma_f32_16x16x32_bf16 v[50:53], v[50:53], v[54:57], 0
	ds_read_b128 v[54:57], v38 offset:18752
	ds_read_b128 v[58:61], v49 offset:30272
	v_cmp_ge_i32_e32 vcc, v74, v39
	v_lshlrev_b32_e32 v42, 16, v6
	s_waitcnt lgkmcnt(0)
	v_mfma_f32_16x16x32_bf16 v[48:51], v[54:57], v[58:61], v[50:53]
	s_nop 7
	v_cndmask_b32_e32 v38, 0, v48, vcc
	v_bfe_u32 v39, v38, 16, 1
	v_add3_u32 v38, v38, v39, s86
	ds_write_b16_d16_hi v43, v38 offset:37152
	v_cndmask_b32_e64 v38, 0, v49, s[38:39]
	v_bfe_u32 v39, v38, 16, 1
	v_add3_u32 v38, v38, v39, s86
	v_cmp_ge_i32_e32 vcc, v74, v72
	ds_write_b16_d16_hi v43, v38 offset:37296
	s_nop 0
	v_cndmask_b32_e32 v38, 0, v50, vcc
	v_bfe_u32 v39, v38, 16, 1
	v_add3_u32 v38, v38, v39, s86
	v_cmp_ge_i32_e32 vcc, v74, v73
	ds_write_b16_d16_hi v43, v38 offset:37440
	s_nop 0
	v_cndmask_b32_e32 v38, 0, v51, vcc
	v_bfe_u32 v39, v38, 16, 1
	v_add3_u32 v38, v38, v39, s86
	ds_write_b16_d16_hi v43, v38 offset:37584
	s_waitcnt lgkmcnt(0)
	s_barrier
	ds_read_b128 v[48:51], v34 offset:46336
	ds_read_b128 v[52:55], v35 offset:37120
	ds_read_b128 v[56:59], v35 offset:18688
	s_waitcnt lgkmcnt(1)
	v_mfma_f32_16x16x32_bf16 v[16:19], v[52:55], v[48:51], v[16:19]
	v_and_b32_e32 v43, 0xffff0000, v6
	v_mul_f32_e32 v6, 0xbfb8aa3b, v42
	v_exp_f32_e32 v6, v6
	s_waitcnt lgkmcnt(0)
	v_mfma_f32_16x16x32_bf16 v[16:19], v[56:59], v[12:15], v[16:19]
	ds_read_b128 v[52:55], v35 offset:39424
	ds_read_b128 v[56:59], v35 offset:20992
	v_cmp_lt_i32_e32 vcc, v220, v219
	s_waitcnt lgkmcnt(1)
	v_mfma_f32_16x16x32_bf16 v[20:23], v[52:55], v[48:51], v[20:23]
	s_waitcnt lgkmcnt(0)
	v_mfma_f32_16x16x32_bf16 v[20:23], v[56:59], v[12:15], v[20:23]
	ds_read_b128 v[52:55], v35 offset:41728
	ds_read_b128 v[56:59], v35 offset:23296
	s_waitcnt lgkmcnt(1)
	v_mfma_f32_16x16x32_bf16 v[24:27], v[52:55], v[48:51], v[24:27]
	s_waitcnt lgkmcnt(0)
	v_mfma_f32_16x16x32_bf16 v[24:27], v[56:59], v[12:15], v[24:27]
	ds_read_b128 v[52:55], v35 offset:44032
	ds_read_b128 v[56:59], v35 offset:25600
	s_waitcnt lgkmcnt(1)
	v_mfma_f32_16x16x32_bf16 v[28:31], v[52:55], v[48:51], v[28:31]
	s_waitcnt lgkmcnt(0)
	v_mfma_f32_16x16x32_bf16 v[12:15], v[56:59], v[12:15], v[28:31]
	s_nop 5
	ds_read_b128 v[28:31], v34 offset:46400
	ds_read_b128 v[48:51], v35 offset:37184
	ds_read_b128 v[52:55], v35 offset:18752
	s_waitcnt lgkmcnt(1)
	v_mfma_f32_16x16x32_bf16 v[16:19], v[48:51], v[28:31], v[16:19]
	s_waitcnt lgkmcnt(0)
	v_mfma_f32_16x16x32_bf16 v[16:19], v[52:55], v[8:11], v[16:19]
	ds_read_b128 v[48:51], v35 offset:39488
	ds_read_b128 v[52:55], v35 offset:21056
	s_waitcnt lgkmcnt(1)
	v_mfma_f32_16x16x32_bf16 v[20:23], v[48:51], v[28:31], v[20:23]
	s_waitcnt lgkmcnt(0)
	v_mfma_f32_16x16x32_bf16 v[20:23], v[52:55], v[8:11], v[20:23]
	ds_read_b128 v[48:51], v35 offset:41792
	ds_read_b128 v[52:55], v35 offset:23360
	s_waitcnt lgkmcnt(1)
	v_mfma_f32_16x16x32_bf16 v[24:27], v[48:51], v[28:31], v[24:27]
	s_waitcnt lgkmcnt(0)
	v_mfma_f32_16x16x32_bf16 v[24:27], v[52:55], v[8:11], v[24:27]
	ds_read_b128 v[48:51], v35 offset:44096
	ds_read_b128 v[52:55], v35 offset:25664
	s_waitcnt lgkmcnt(0)
	s_barrier
; __device__ __forceinline__ u32x4 pack8(const float* v) { u32x4 w; w.x = pk2(v[0], v[1]); w.y = pk2(v[2], v[3]); w.z = pk2(v[4], v[5]); w.w = pk2(v[6], v[7]); return w; }
; __device__ __forceinline__ void unpack8(u32x4 w, float* v) { v[0] = bflo(w.x); v[1] = bfhi(w.x); v[2] = bflo(w.y); v[3] = bfhi(w.y); v[4] = bflo(w.z); v[5] = bfhi(w.z); v[6] = bflo(w.w); v[7] = bfhi(w.w); }
; __device__ __forceinline__ float siluf_(float x) { return x / (1.f + __expf(-x)); }
; __device__ __forceinline__ void gla_out_item(unsigned char* lds, unsigned char* ws, const float* wgate, const float* bgate, const float* hnorm, int l, int item, bool dowrite = true) {
;     ...
;     float* Os = (float*)(lds + GL_O);
; #pragma unroll
;     for (int rb = 0; rb < 4; ++rb)
; #pragma unroll
;         for (int j = 0; j < 4; ++j) Os[(rb * 16 + g * 4 + j) * 132 + wid * 16 + ql] = oacc[rb][j];
;     ...
;       for (int hh = 0; hh < 2; ++hh) { float rv[8]; unpack8(hh == 0 ? rraw0 : rraw1, rv);
; #pragma unroll
;           for (int e = 0; e < 8; ++e) rv[e] = ov[hh * 8 + e] * rstd * gn[hh * 8 + e] * siluf_(rv[e]);
;           if (dowrite) *(u32x4*)(rp + hh * 8) = pack8(rv); } }
	v_mfma_f32_16x16x32_bf16 v[12:15], v[48:51], v[28:31], v[12:15]
	v_lshlrev_b32_e32 v28, 6, v41
	v_and_b32_e32 v41, 0xffff0000, v7
	v_mfma_f32_16x16x32_bf16 v[8:11], v[52:55], v[8:11], v[12:15]
	v_cndmask_b32_e32 v29, v218, v220, vcc
	v_cmp_lt_i32_e32 vcc, v221, v219
	v_lshlrev_b32_e32 v29, 2, v29
	s_nop 1
	v_and_b32_e32 v12, 0xffffffc0, v68
	v_add_u32_e32 v12, 0, v12
	v_lshlrev_b32_e32 v13, 2, v69
	v_mul_u32_u24_e32 v14, 0x840, v70
	v_add3_u32 v12, v12, v13, v14
	v_add_u32_e32 v13, 0xfd00, v12
	v_add_u32_e32 v12, 0xfc00, v12
	ds_write2_b32 v12, v16, v17 offset0:64 offset1:196
	v_add_u32_e32 v12, 0x400, v13
	ds_write2_b32 v12, v18, v19 offset0:8 offset1:140
	v_add_u32_e32 v12, 0x2000, v13
	ds_write2_b32 v12, v20, v21 offset0:64 offset1:196
	v_add_u32_e32 v12, 0x2400, v13
	ds_write2_b32 v12, v22, v23 offset0:72 offset1:204
	v_add_u32_e32 v12, 0x4200, v13
	ds_write2_b32 v12, v24, v25 offset1:132
	v_add_u32_e32 v12, 0x4600, v13
	ds_write2_b32 v12, v26, v27 offset0:8 offset1:140
	v_add_u32_e32 v12, 0x6200, v13
	ds_write2_b32 v12, v8, v9 offset0:64 offset1:196
	v_add_u32_e32 v8, 0x6600, v13
	ds_write2_b32 v8, v10, v11 offset0:72 offset1:204
	v_mul_lo_u32 v8, v37, s0
	v_lshlrev_b32_e32 v37, 16, v7
	v_mul_f32_e32 v7, 0xbfb8aa3b, v43
	v_exp_f32_e32 v7, v7
	v_cndmask_b32_e32 v30, v218, v221, vcc
	v_cmp_lt_i32_e32 vcc, v222, v219
	s_lshl_b32 s0, s52, 9
	v_pk_add_f32 v[6:7], v[6:7], 1.0 op_sel_hi:[1,0]
	v_cndmask_b32_e32 v31, v218, v222, vcc
	s_add_u32 s0, s27, s0
	v_add3_u32 v8, 0, v8, v28
	s_addc_u32 s1, s36, 0
	v_rcp_f32_e32 v56, v7
	s_nop 0
	v_mul_f32_e32 v7, v43, v56
	s_waitcnt lgkmcnt(0)
	s_barrier
; __device__ __forceinline__ u32x4 pack8(const float* v) { u32x4 w; w.x = pk2(v[0], v[1]); w.y = pk2(v[2], v[3]); w.z = pk2(v[4], v[5]); w.w = pk2(v[6], v[7]); return w; }
; __device__ __forceinline__ void unpack8(u32x4 w, float* v) { v[0] = bflo(w.x); v[1] = bfhi(w.x); v[2] = bflo(w.y); v[3] = bfhi(w.y); v[4] = bflo(w.z); v[5] = bfhi(w.z); v[6] = bflo(w.w); v[7] = bfhi(w.w); }
; __device__ __forceinline__ float siluf_(float x) { return x / (1.f + __expf(-x)); }
; __device__ __forceinline__ void gla_out_item(unsigned char* lds, unsigned char* ws, const float* wgate, const float* bgate, const float* hnorm, int l, int item, bool dowrite = true) {
;     ...
;     { const int i = tid >> 3, eg = tid & 7;
;       float ov[16]; float ss = 0.f;
; #pragma unroll
;       for (int e = 0; e < 16; ++e) { ov[e] = Os[i * 132 + eg * 16 + e]; ss += ov[e] * ov[e]; }
;       ss += __shfl_xor(ss, 1); ss += __shfl_xor(ss, 2); ss += __shfl_xor(ss, 4);
;       const float rstd = rsqrtf(ss * (1.f / 128.f) + EPS);
;       const float* gn = hnorm + l * 512 + h * 128 + eg * 16;
;       bf16_t* rp = (bf16_t*)(ws + O_CR) + (size_t)(t0 + i) * 512 + h * 128 + eg * 16;
; #pragma unroll
;       for (int hh = 0; hh < 2; ++hh) { float rv[8]; unpack8(hh == 0 ? rraw0 : rraw1, rv);
; #pragma unroll
;           for (int e = 0; e < 8; ++e) rv[e] = ov[hh * 8 + e] * rstd * gn[hh * 8 + e] * siluf_(rv[e]);
;           if (dowrite) *(u32x4*)(rp + hh * 8) = pack8(rv); } }
	v_lshlrev_b32_e32 v58, 16, v5
	v_and_b32_e32 v5, 0xffff0000, v5
	v_mul_f32_e32 v56, 0xbfb8aa3b, v58
	v_mul_f32_e32 v57, 0xbfb8aa3b, v5
	v_exp_f32_e32 v56, v56
	v_exp_f32_e32 v57, v57
	ds_read_b128 v[20:23], v8 offset:64768
	ds_read_b128 v[16:19], v8 offset:64784
	ds_read_b128 v[12:15], v8 offset:64800
	ds_read_b128 v[8:11], v8 offset:64816
	global_load_dwordx4 v[48:51], v28, s[0:1] offset:16
	global_load_dwordx4 v[52:55], v28, s[0:1]
	v_rcp_f32_e32 v43, v6
	s_nop 0
	v_mul_f32_e32 v6, v42, v43
	v_pk_add_f32 v[56:57], v[56:57], 1.0 op_sel_hi:[1,0]
	s_waitcnt lgkmcnt(3)
	v_pk_mul_f32 v[42:43], v[22:23], v[22:23]
	s_waitcnt lgkmcnt(2)
	v_pk_mul_f32 v[38:39], v[16:17], v[16:17]
	v_pk_mul_f32 v[34:35], v[18:19], v[18:19]
	s_waitcnt lgkmcnt(0)
	v_pk_mul_f32 v[26:27], v[8:9], v[8:9]
	v_rcp_f32_e32 v59, v57
	s_nop 0
	v_mul_f32_e32 v57, v5, v59
	v_pk_mul_f32 v[24:25], v[10:11], v[10:11]
	v_lshlrev_b32_e32 v30, 2, v30
	v_lshlrev_b32_e32 v31, 2, v31
	v_lshlrev_b32_e32 v60, 16, v4
	v_and_b32_e32 v61, 0xffff0000, v4
	v_rcp_f32_e32 v5, v56
	s_nop 0
	v_mul_f32_e32 v56, v58, v5
	v_mul_f32_e32 v4, 0xbfb8aa3b, v60
	v_mul_f32_e32 v5, 0xbfb8aa3b, v61
	v_exp_f32_e32 v4, v4
	v_exp_f32_e32 v5, v5
	v_pk_mul_f32 v[58:59], v[20:21], v[20:21]
	s_add_i32 s51, s51, s97
	v_add_f32_e32 v58, v58, v59
	v_pk_add_f32 v[4:5], v[4:5], 1.0 op_sel_hi:[1,0]
	v_add_f32_e32 v42, v58, v42
	v_add_f32_e32 v42, v42, v43
	v_add_f32_e32 v38, v42, v38
	v_add_f32_e32 v38, v38, v39
	v_rcp_f32_e32 v62, v5
	s_nop 0
	v_mul_f32_e32 v5, v61, v62
	v_add_f32_e32 v34, v38, v34
	v_add_f32_e32 v34, v34, v35
	s_add_i32 s37, s37, s50
	v_rcp_f32_e32 v61, v4
	s_nop 0
	v_mul_f32_e32 v4, v60, v61
	v_mul_f32_e32 v60, 0xbfb8aa3b, v37
	v_mul_f32_e32 v61, 0xbfb8aa3b, v41
	v_exp_f32_e32 v60, v60
	v_exp_f32_e32 v61, v61
	s_cmpk_gt_i32 s51, 0x41f
	v_pk_add_f32 v[60:61], v[60:61], 1.0 op_sel_hi:[1,0]
	s_nop 0
	s_nop 0
	v_rcp_f32_e32 v62, v61
	s_nop 0
	v_mul_f32_e32 v61, v41, v62
	v_lshlrev_b32_e32 v66, 16, v0
	v_mul_f32_e32 v0, 0xbfb8aa3b, v66
	v_exp_f32_e32 v0, v0
	v_rcp_f32_e32 v41, v60
	s_nop 0
	v_mul_f32_e32 v60, v37, v41
	v_lshlrev_b32_e32 v37, 16, v1
	v_and_b32_e32 v41, 0xffff0000, v1
	v_mul_f32_e32 v1, 0xbfb8aa3b, v67
	v_pk_mul_f32 v[64:65], v[12:13], v[12:13]
	v_exp_f32_e32 v1, v1
	v_add_f32_e32 v34, v34, v64
	v_pk_mul_f32 v[62:63], v[14:15], v[14:15]
	v_add_f32_e32 v34, v34, v65
	v_add_f32_e32 v34, v34, v62
	v_pk_add_f32 v[0:1], v[0:1], 1.0 op_sel_hi:[1,0]
	v_add_f32_e32 v34, v34, v63
	v_add_f32_e32 v26, v34, v26
	v_add_f32_e32 v26, v26, v27
	v_add_f32_e32 v24, v26, v24
	v_add_f32_e32 v24, v24, v25
	ds_bpermute_b32 v25, v29, v24
	s_waitcnt lgkmcnt(0)
	v_add_f32_e32 v24, v24, v25
	ds_bpermute_b32 v25, v30, v24
	v_rcp_f32_e32 v68, v1
	s_nop 0
	v_mul_f32_e32 v1, v67, v68
	s_waitcnt lgkmcnt(0)
	v_add_f32_e32 v24, v24, v25
	ds_bpermute_b32 v25, v31, v24
	s_waitcnt lgkmcnt(0)
	v_add_f32_e32 v24, v24, v25
	v_fmamk_f32 v24, v24, 0x3c000000, v216
	v_cmp_gt_f32_e32 vcc, s33, v24
	v_mul_f32_e32 v25, 0x4b800000, v24
	v_rcp_f32_e32 v67, v0
	s_nop 0
	v_mul_f32_e32 v0, v66, v67
	v_cndmask_b32_e32 v24, v24, v25, vcc
	v_rsq_f32_e32 v24, v24
	s_nop 0
	v_mul_f32_e32 v25, 0x45800000, v24
	v_cndmask_b32_e32 v24, v24, v25, vcc
	v_pk_mul_f32 v[20:21], v[20:21], v[24:25] op_sel_hi:[1,0]
	v_pk_mul_f32 v[16:17], v[16:17], v[24:25] op_sel_hi:[1,0]
	s_waitcnt vmcnt(0)
	v_pk_mul_f32 v[20:21], v[52:53], v[20:21]
	v_pk_mul_f32 v[16:17], v[48:49], v[16:17]
	v_pk_mul_f32 v[4:5], v[4:5], v[20:21]
	v_pk_mul_f32 v[20:21], v[22:23], v[24:25] op_sel_hi:[1,0]
	v_pk_mul_f32 v[6:7], v[6:7], v[16:17]
	v_pk_mul_f32 v[16:17], v[18:19], v[24:25] op_sel_hi:[1,0]
	v_pk_mul_f32 v[20:21], v[54:55], v[20:21]
	v_pk_mul_f32 v[16:17], v[50:51], v[16:17]
	v_pk_mul_f32 v[20:21], v[56:57], v[20:21]
	v_pk_mul_f32 v[16:17], v[60:61], v[16:17]
	v_cvt_pk_bf16_f32 v4, v4, v5
	v_cvt_pk_bf16_f32 v5, v20, v21
	v_cvt_pk_bf16_f32 v6, v6, v7
	v_cvt_pk_bf16_f32 v7, v16, v17
	global_store_dwordx4 v[32:33], v[4:7], off
	global_load_dwordx4 v[4:7], v28, s[0:1] offset:48
	s_nop 0
	global_load_dwordx4 v[16:19], v28, s[0:1] offset:32
	v_pk_mul_f32 v[12:13], v[12:13], v[24:25] op_sel_hi:[1,0]
	v_pk_mul_f32 v[14:15], v[14:15], v[24:25] op_sel_hi:[1,0]
	v_pk_mul_f32 v[8:9], v[8:9], v[24:25] op_sel_hi:[1,0]
	s_waitcnt vmcnt(0)
	v_pk_mul_f32 v[12:13], v[12:13], v[16:17]
	s_nop 0
	v_pk_mul_f32 v[0:1], v[0:1], v[12:13]
	v_mul_f32_e32 v12, 0xbfb8aa3b, v37
	v_mul_f32_e32 v13, 0xbfb8aa3b, v41
	v_exp_f32_e32 v12, v12
	v_exp_f32_e32 v13, v13
	v_pk_mul_f32 v[14:15], v[14:15], v[18:19]
	v_pk_mul_f32 v[4:5], v[8:9], v[4:5]
	v_cvt_pk_bf16_f32 v0, v0, v1
	v_pk_add_f32 v[12:13], v[12:13], 1.0 op_sel_hi:[1,0]
	s_nop 0
	s_nop 0
	v_rcp_f32_e32 v16, v13
	s_nop 0
	v_mul_f32_e32 v13, v41, v16
	s_nop 0
	v_rcp_f32_e32 v16, v12
	s_nop 0
	v_mul_f32_e32 v12, v37, v16
	v_lshlrev_b32_e32 v16, 16, v2
	v_and_b32_e32 v2, 0xffff0000, v2
	v_pk_mul_f32 v[12:13], v[12:13], v[14:15]
	v_mul_f32_e32 v14, 0xbfb8aa3b, v16
	v_mul_f32_e32 v8, 0xbfb8aa3b, v2
	v_exp_f32_e32 v14, v14
	v_exp_f32_e32 v15, v8
	v_cvt_pk_bf16_f32 v1, v12, v13
	v_pk_add_f32 v[8:9], v[14:15], 1.0 op_sel_hi:[1,0]
	s_nop 0
	s_nop 0
	v_rcp_f32_e32 v14, v9
	s_nop 0
	v_mul_f32_e32 v9, v2, v14
	s_nop 0
	v_lshlrev_b32_e32 v14, 16, v3
	v_and_b32_e32 v15, 0xffff0000, v3
	v_rcp_f32_e32 v2, v8
	s_nop 0
	v_mul_f32_e32 v8, v16, v2
	v_mul_f32_e32 v2, 0xbfb8aa3b, v14
	v_mul_f32_e32 v3, 0xbfb8aa3b, v15
	v_exp_f32_e32 v2, v2
	v_exp_f32_e32 v3, v3
	v_pk_mul_f32 v[4:5], v[8:9], v[4:5]
	v_pk_mul_f32 v[8:9], v[10:11], v[24:25] op_sel_hi:[1,0]
	v_pk_add_f32 v[2:3], v[2:3], 1.0 op_sel_hi:[1,0]
	v_pk_mul_f32 v[6:7], v[8:9], v[6:7]
	s_nop 0
	v_rcp_f32_e32 v8, v3
	s_nop 0
	v_mul_f32_e32 v3, v15, v8
	s_nop 0
	v_rcp_f32_e32 v8, v2
	s_nop 0
	v_mul_f32_e32 v2, v14, v8
	v_pk_mul_f32 v[6:7], v[2:3], v[6:7]
	v_cvt_pk_bf16_f32 v2, v4, v5
	v_cvt_pk_bf16_f32 v3, v6, v7
	global_store_dwordx4 v[32:33], v[0:3], off offset:16
	s_barrier
	s_cbranch_scc0 .LBB0_394

; __device__ __forceinline__ u32x4 pack8(const float* v) { u32x4 w; w.x = pk2(v[0], v[1]); w.y = pk2(v[2], v[3]); w.z = pk2(v[4], v[5]); w.w = pk2(v[6], v[7]); return w; }
; __device__ __forceinline__ float sigmoidf_(float x) { return 1.f / (1.f + __expf(-x)); }
;     __device__ __forceinline__ void operator()(const f32x4 (&acc)[2][2][4][2], const pg8::Unit& u, int wr, int wc, int fr, int fq) const {
;         EPI_LOOP_BEGIN
;             const int b = (t >= TB) ? 1 : 0, i = t - b * TB; const bool lat = i >= LC; const int pos = i - LC;
;             if (c0 < 640) {
;     ...
;             } else {
; #pragma unroll
;                 for (int e = 0; e < 8; ++e) v[e] = sigmoidf_(v[e]);
;                 *(u32x4*)((bf16_t*)(ws + O_GATES) + (size_t)t * 3072 + (c0 - 2816)) = pack8(v);
.LBB0_756:
	v_mov_b32_e32 v149, v37
	v_mov_b32_e32 v150, v41
	v_readlane_b32 s0, v254, 50
	v_mov_b32_e32 v161, v36
	v_mov_b32_e32 v163, v36
	v_lshl_add_u32 v148, v149, 3, s0
	v_cmp_eq_u32_e64 s[0:1], 0, v149
	v_lshl_add_u32 v160, s27, 8, v148
	v_subrev_co_u32_e32 v149, vcc, 0x480, v160
	v_writelane_b32 v252, s0, 15
	v_lshrrev_b32_e32 v162, 1, v149
	v_add_u32_e32 v149, 0xfffffd80, v160
	v_writelane_b32 v252, s1, 16
	s_movk_i32 s0, 0x27f
	v_cmp_lt_i32_e64 s[94:95], s0, v160
	s_movk_i32 s0, 0x2ff
	v_cmp_lt_u32_e64 s[92:93], s0, v160
	s_movk_i32 s0, 0x49f
	v_cmp_lt_u32_e64 s[90:91], s0, v160
	s_movk_i32 s0, 0x4bf
	v_cmp_lt_u32_e64 s[80:81], s0, v160
	s_movk_i32 s0, 0x4ff
	v_cmp_lt_u32_e64 s[78:79], s0, v160
	s_movk_i32 s0, 0x5ff
	v_cmp_lt_u32_e64 s[0:1], s0, v160
	v_lshrrev_b32_e32 v168, 6, v149
	s_xor_b64 s[96:97], vcc, -1
	v_writelane_b32 v252, s0, 17
	v_and_b32_e32 v166, 56, v148
	s_nop 0
	v_writelane_b32 v252, s1, 18
	s_movk_i32 s0, 0x6ff
	v_cmp_lt_u32_e64 s[54:55], s0, v160
	s_movk_i32 s0, 0x8ff
	v_cmp_lt_u32_e64 s[62:63], s0, v160
	s_movk_i32 s0, 0xaff
	v_cmp_lt_u32_e64 s[58:59], s0, v160
	s_movk_i32 s0, 0x3ff
	v_cmp_lt_i32_e64 s[76:77], s0, v160
	s_movk_i32 s0, 0x1ff
	v_cmp_lt_i32_e64 s[74:75], s0, v160
	s_lshl_b32 s0, s26, 8
	v_readlane_b32 s1, v254, 49
	s_add_i32 s0, s0, s1
	v_add_u32_e32 v150, s0, v150
	v_cmp_lt_i32_e64 s[72:73], s84, v150
	s_movk_i32 s0, 0xff
	s_nop 0
	v_cndmask_b32_e64 v149, 0, v226, s[72:73]
	v_add_u32_e32 v158, v149, v150
	v_cmp_lt_i32_e64 s[64:65], s0, v158
	v_add_u32_e32 v154, 0xffffff00, v158
	s_and_saveexec_b64 s[0:1], s[94:95]
	s_xor_b64 s[36:37], exec, s[0:1]
	s_cbranch_execz .LBB0_801
	s_and_saveexec_b64 s[0:1], s[92:93]
	s_xor_b64 s[24:25], exec, s[0:1]
	s_cbranch_execz .LBB0_798
	s_and_saveexec_b64 s[0:1], s[96:97]
	s_xor_b64 s[26:27], exec, s[0:1]
	s_cbranch_execz .LBB0_787
	s_and_saveexec_b64 s[0:1], s[90:91]
	s_xor_b64 s[0:1], exec, s[0:1]
	s_cbranch_execz .LBB0_782
	s_and_saveexec_b64 s[18:19], s[80:81]
	s_xor_b64 s[18:19], exec, s[18:19]
	s_cbranch_execz .LBB0_779
	s_and_saveexec_b64 s[40:41], s[78:79]
	s_cbranch_execz .LBB0_778
	v_readlane_b32 s14, v252, 17
	v_readlane_b32 s15, v252, 18
	s_and_saveexec_b64 s[44:45], s[14:15]
	s_xor_b64 s[44:45], exec, s[44:45]
	s_cbranch_execz .LBB0_776
	s_and_saveexec_b64 s[46:47], s[54:55]
	s_xor_b64 s[46:47], exec, s[46:47]
	s_cbranch_execz .LBB0_773
	s_and_saveexec_b64 s[48:49], s[62:63]
	s_xor_b64 s[48:49], exec, s[48:49]
	s_cbranch_execz .LBB0_770
	s_and_saveexec_b64 s[50:51], s[58:59]
	s_xor_b64 s[50:51], exec, s[50:51]
	s_cbranch_execz .LBB0_767
	v_mul_f32_e32 v28, 0xbfb8aa3b, v28
	v_mul_f32_e32 v29, 0xbfb8aa3b, v29
	v_exp_f32_e32 v28, v28
	v_exp_f32_e32 v29, v29
	s_nop 0
	v_pk_add_f32 v[28:29], v[28:29], 1.0 op_sel_hi:[1,0]
	s_nop 0
	s_nop 0
	v_rcp_f32_e32 v149, v29
	s_nop 0
	v_rcp_f32_e32 v151, v28
	v_mul_f32_e32 v28, 0xbfb8aa3b, v30
	v_mul_f32_e32 v29, 0xbfb8aa3b, v31
	v_exp_f32_e32 v28, v28
	v_exp_f32_e32 v29, v29
	s_nop 0
	v_pk_add_f32 v[28:29], v[28:29], 1.0 op_sel_hi:[1,0]
	s_nop 0
	s_nop 0
	v_rcp_f32_e32 v30, v29
	s_nop 0
	v_rcp_f32_e32 v31, v28
	v_mul_f32_e32 v28, 0xbfb8aa3b, v32
	v_mul_f32_e32 v29, 0xbfb8aa3b, v33
	v_exp_f32_e32 v28, v28
	v_exp_f32_e32 v29, v29
	s_nop 0
	v_pk_add_f32 v[28:29], v[28:29], 1.0 op_sel_hi:[1,0]
	s_nop 0
	s_nop 0
	v_rcp_f32_e32 v32, v29
	s_nop 0
	v_rcp_f32_e32 v33, v28
	v_mul_f32_e32 v28, 0xbfb8aa3b, v34
	v_mul_f32_e32 v29, 0xbfb8aa3b, v35
	v_exp_f32_e32 v28, v28
	v_exp_f32_e32 v29, v29
	s_nop 0
	v_pk_add_f32 v[28:29], v[28:29], 1.0 op_sel_hi:[1,0]
	s_nop 0
	s_nop 0
	v_rcp_f32_e32 v34, v29
	s_nop 0
	v_rcp_f32_e32 v35, v28
	v_cvt_pk_bf16_f32 v29, v31, v30
	v_cvt_pk_bf16_f32 v30, v33, v32
	v_mov_b64_e32 v[32:33], s[4:5]
	v_mad_i64_i32 v[32:33], s[52:53], v150, s85, v[32:33]
	v_lshl_add_u64 v[32:33], v[160:161], 1, v[32:33]
	v_add_co_u32_e32 v32, vcc, 0x1286e000, v32
	v_cvt_pk_bf16_f32 v28, v151, v149
	v_cvt_pk_bf16_f32 v31, v35, v34
	v_addc_co_u32_e32 v33, vcc, 0, v33, vcc
	global_store_dwordx4 v[32:33], v[28:31], off offset:2560

; __device__ __forceinline__ u32x4 pack8(const float* v) { u32x4 w; w.x = pk2(v[0], v[1]); w.y = pk2(v[2], v[3]); w.z = pk2(v[4], v[5]); w.w = pk2(v[6], v[7]); return w; }
; __device__ __forceinline__ float sigmoidf_(float x) { return 1.f / (1.f + __expf(-x)); }
;     __device__ __forceinline__ void operator()(const f32x4 (&acc)[2][2][4][2], const pg8::Unit& u, int wr, int wc, int fr, int fq) const {
;         EPI_LOOP_BEGIN
;             const int b = (t >= TB) ? 1 : 0, i = t - b * TB; const bool lat = i >= LC; const int pos = i - LC;
;             if (c0 < 640) {
;     ...
;             } else {
; #pragma unroll
;                 for (int e = 0; e < 8; ++e) v[e] = sigmoidf_(v[e]);
;                 *(u32x4*)((bf16_t*)(ws + O_GATES) + (size_t)t * 3072 + (c0 - 2816)) = pack8(v);
.LBB0_807:
	s_or_b64 exec, exec, s[0:1]
	v_add_u32_e32 v32, 16, v150
	v_cmp_lt_i32_e64 s[70:71], s84, v32
	s_movk_i32 s0, 0xff
	s_nop 0
	v_cndmask_b32_e64 v28, 0, v226, s[70:71]
	v_add_u32_e32 v156, v28, v32
	v_cmp_lt_i32_e64 s[60:61], s0, v156
	v_add_u32_e32 v152, 0xffffff00, v156
	s_and_saveexec_b64 s[0:1], s[94:95]
	s_xor_b64 s[36:37], exec, s[0:1]
	s_cbranch_execz .LBB0_852
	s_and_saveexec_b64 s[0:1], s[92:93]
	s_xor_b64 s[24:25], exec, s[0:1]
	s_cbranch_execz .LBB0_849
	s_and_saveexec_b64 s[0:1], s[96:97]
	s_xor_b64 s[26:27], exec, s[0:1]
	s_cbranch_execz .LBB0_838
	s_and_saveexec_b64 s[0:1], s[90:91]
	s_xor_b64 s[0:1], exec, s[0:1]
	s_cbranch_execz .LBB0_833
	s_and_saveexec_b64 s[18:19], s[80:81]
	s_xor_b64 s[18:19], exec, s[18:19]
	s_cbranch_execz .LBB0_830
	s_and_saveexec_b64 s[40:41], s[78:79]
	s_cbranch_execz .LBB0_829
	v_readlane_b32 s14, v252, 17
	v_readlane_b32 s15, v252, 18
	s_and_saveexec_b64 s[44:45], s[14:15]
	s_xor_b64 s[44:45], exec, s[44:45]
	s_cbranch_execz .LBB0_827
	s_and_saveexec_b64 s[46:47], s[54:55]
	s_xor_b64 s[46:47], exec, s[46:47]
	s_cbranch_execz .LBB0_824
	s_and_saveexec_b64 s[48:49], s[62:63]
	s_xor_b64 s[48:49], exec, s[48:49]
	s_cbranch_execz .LBB0_821
	s_and_saveexec_b64 s[50:51], s[58:59]
	s_xor_b64 s[50:51], exec, s[50:51]
	s_cbranch_execz .LBB0_818
	v_mul_f32_e32 v24, 0xbfb8aa3b, v24
	v_mul_f32_e32 v25, 0xbfb8aa3b, v25
	v_exp_f32_e32 v24, v24
	v_exp_f32_e32 v25, v25
	s_nop 0
	v_pk_add_f32 v[24:25], v[24:25], 1.0 op_sel_hi:[1,0]
	s_nop 0
	s_nop 0
	v_rcp_f32_e32 v28, v25
	s_nop 0
	v_rcp_f32_e32 v29, v24
	v_mul_f32_e32 v24, 0xbfb8aa3b, v26
	v_mul_f32_e32 v25, 0xbfb8aa3b, v27
	v_exp_f32_e32 v24, v24
	v_exp_f32_e32 v25, v25
	s_nop 0
	v_pk_add_f32 v[24:25], v[24:25], 1.0 op_sel_hi:[1,0]
	s_nop 0
	s_nop 0
	v_rcp_f32_e32 v26, v25
	s_nop 0
	v_rcp_f32_e32 v27, v24
	v_mul_f32_e32 v24, 0xbfb8aa3b, v136
	v_mul_f32_e32 v25, 0xbfb8aa3b, v137
	v_exp_f32_e32 v24, v24
	v_exp_f32_e32 v25, v25
	s_nop 0
	v_pk_add_f32 v[24:25], v[24:25], 1.0 op_sel_hi:[1,0]
	s_nop 0
	s_nop 0
	v_rcp_f32_e32 v30, v25
	s_nop 0
	v_rcp_f32_e32 v31, v24
	v_mul_f32_e32 v24, 0xbfb8aa3b, v138
	v_mul_f32_e32 v25, 0xbfb8aa3b, v139
	v_exp_f32_e32 v24, v24
	v_exp_f32_e32 v25, v25
	s_nop 0
	v_pk_add_f32 v[24:25], v[24:25], 1.0 op_sel_hi:[1,0]
	s_nop 0
	s_nop 0
	v_rcp_f32_e32 v33, v25
	s_nop 0
	v_rcp_f32_e32 v34, v24
	v_cvt_pk_bf16_f32 v24, v29, v28
	v_mov_b64_e32 v[28:29], s[4:5]
	v_mad_i64_i32 v[28:29], s[52:53], v32, s85, v[28:29]
	v_lshl_add_u64 v[28:29], v[160:161], 1, v[28:29]
	v_add_co_u32_e32 v28, vcc, 0x1286e000, v28
	v_cvt_pk_bf16_f32 v25, v27, v26
	v_cvt_pk_bf16_f32 v26, v31, v30
	v_cvt_pk_bf16_f32 v27, v34, v33
	v_addc_co_u32_e32 v29, vcc, 0, v29, vcc
	global_store_dwordx4 v[28:29], v[24:27], off offset:2560

; __device__ __forceinline__ u32x4 pack8(const float* v) { u32x4 w; w.x = pk2(v[0], v[1]); w.y = pk2(v[2], v[3]); w.z = pk2(v[4], v[5]); w.w = pk2(v[6], v[7]); return w; }
; __device__ __forceinline__ float sigmoidf_(float x) { return 1.f / (1.f + __expf(-x)); }
;     __device__ __forceinline__ void operator()(const f32x4 (&acc)[2][2][4][2], const pg8::Unit& u, int wr, int wc, int fr, int fq) const {
;         EPI_LOOP_BEGIN
;             const int b = (t >= TB) ? 1 : 0, i = t - b * TB; const bool lat = i >= LC; const int pos = i - LC;
;             if (c0 < 640) {
;     ...
;             } else {
; #pragma unroll
;                 for (int e = 0; e < 8; ++e) v[e] = sigmoidf_(v[e]);
;                 *(u32x4*)((bf16_t*)(ws + O_GATES) + (size_t)t * 3072 + (c0 - 2816)) = pack8(v);
.LBB0_858:
	s_or_b64 exec, exec, s[0:1]
	v_add_u32_e32 v28, 32, v150
	v_cmp_lt_i32_e64 s[68:69], s84, v28
	s_movk_i32 s0, 0xff
	s_nop 0
	v_cndmask_b32_e64 v24, 0, v226, s[68:69]
	v_add_u32_e32 v138, v24, v28
	v_cmp_lt_i32_e64 s[56:57], s0, v138
	v_add_u32_e32 v136, 0xffffff00, v138
	s_and_saveexec_b64 s[0:1], s[94:95]
	s_xor_b64 s[36:37], exec, s[0:1]
	s_cbranch_execz .LBB0_903
	s_and_saveexec_b64 s[0:1], s[92:93]
	s_xor_b64 s[24:25], exec, s[0:1]
	s_cbranch_execz .LBB0_900
	s_and_saveexec_b64 s[0:1], s[96:97]
	s_xor_b64 s[26:27], exec, s[0:1]
	s_cbranch_execz .LBB0_889
	s_and_saveexec_b64 s[0:1], s[90:91]
	s_xor_b64 s[0:1], exec, s[0:1]
	s_cbranch_execz .LBB0_884
	s_and_saveexec_b64 s[18:19], s[80:81]
	s_xor_b64 s[18:19], exec, s[18:19]
	s_cbranch_execz .LBB0_881
	s_and_saveexec_b64 s[40:41], s[78:79]
	s_cbranch_execz .LBB0_880
	v_readlane_b32 s14, v252, 17
	v_readlane_b32 s15, v252, 18
	s_and_saveexec_b64 s[44:45], s[14:15]
	s_xor_b64 s[44:45], exec, s[44:45]
	s_cbranch_execz .LBB0_878
	s_and_saveexec_b64 s[46:47], s[54:55]
	s_xor_b64 s[46:47], exec, s[46:47]
	s_cbranch_execz .LBB0_875
	s_and_saveexec_b64 s[48:49], s[62:63]
	s_xor_b64 s[48:49], exec, s[48:49]
	s_cbranch_execz .LBB0_872
	s_and_saveexec_b64 s[50:51], s[58:59]
	s_xor_b64 s[50:51], exec, s[50:51]
	s_cbranch_execz .LBB0_869
	v_mul_f32_e32 v20, 0xbfb8aa3b, v20
	v_mul_f32_e32 v21, 0xbfb8aa3b, v21
	v_exp_f32_e32 v20, v20
	v_exp_f32_e32 v21, v21
	s_nop 0
	v_pk_add_f32 v[20:21], v[20:21], 1.0 op_sel_hi:[1,0]
	s_nop 0
	s_nop 0
	v_rcp_f32_e32 v24, v21
	s_nop 0
	v_rcp_f32_e32 v25, v20
	v_mul_f32_e32 v20, 0xbfb8aa3b, v22
	v_mul_f32_e32 v21, 0xbfb8aa3b, v23
	v_exp_f32_e32 v20, v20
	v_exp_f32_e32 v21, v21
	s_nop 0
	v_pk_add_f32 v[20:21], v[20:21], 1.0 op_sel_hi:[1,0]
	s_nop 0
	s_nop 0
	v_rcp_f32_e32 v22, v21
	s_nop 0
	v_rcp_f32_e32 v23, v20
	v_mul_f32_e32 v20, 0xbfb8aa3b, v132
	v_mul_f32_e32 v21, 0xbfb8aa3b, v133
	v_exp_f32_e32 v20, v20
	v_exp_f32_e32 v21, v21
	s_nop 0
	v_pk_add_f32 v[20:21], v[20:21], 1.0 op_sel_hi:[1,0]
	s_nop 0
	s_nop 0
	v_rcp_f32_e32 v26, v21
	s_nop 0
	v_rcp_f32_e32 v27, v20
	v_mul_f32_e32 v20, 0xbfb8aa3b, v134
	v_mul_f32_e32 v21, 0xbfb8aa3b, v135
	v_exp_f32_e32 v20, v20
	v_exp_f32_e32 v21, v21
	s_nop 0
	v_pk_add_f32 v[20:21], v[20:21], 1.0 op_sel_hi:[1,0]
	s_nop 0
	s_nop 0
	v_rcp_f32_e32 v29, v21
	s_nop 0
	v_rcp_f32_e32 v30, v20
	v_cvt_pk_bf16_f32 v20, v25, v24
	v_mov_b64_e32 v[24:25], s[4:5]
	v_mad_i64_i32 v[24:25], s[52:53], v28, s85, v[24:25]
	v_lshl_add_u64 v[24:25], v[160:161], 1, v[24:25]
	v_add_co_u32_e32 v24, vcc, 0x1286e000, v24
	v_cvt_pk_bf16_f32 v21, v23, v22
	v_cvt_pk_bf16_f32 v22, v27, v26
	v_cvt_pk_bf16_f32 v23, v30, v29
	v_addc_co_u32_e32 v25, vcc, 0, v25, vcc
	global_store_dwordx4 v[24:25], v[20:23], off offset:2560

; __device__ __forceinline__ u32x4 pack8(const float* v) { u32x4 w; w.x = pk2(v[0], v[1]); w.y = pk2(v[2], v[3]); w.z = pk2(v[4], v[5]); w.w = pk2(v[6], v[7]); return w; }
; __device__ __forceinline__ float sigmoidf_(float x) { return 1.f / (1.f + __expf(-x)); }
;     __device__ __forceinline__ void operator()(const f32x4 (&acc)[2][2][4][2], const pg8::Unit& u, int wr, int wc, int fr, int fq) const {
;         EPI_LOOP_BEGIN
;             const int b = (t >= TB) ? 1 : 0, i = t - b * TB; const bool lat = i >= LC; const int pos = i - LC;
;             if (c0 < 640) {
;     ...
;             } else {
; #pragma unroll
;                 for (int e = 0; e < 8; ++e) v[e] = sigmoidf_(v[e]);
;                 *(u32x4*)((bf16_t*)(ws + O_GATES) + (size_t)t * 3072 + (c0 - 2816)) = pack8(v);
.LBB0_909:
	s_or_b64 exec, exec, s[0:1]
	v_add_u32_e32 v24, 48, v150
	v_cmp_lt_i32_e64 s[66:67], s84, v24
	s_movk_i32 s0, 0xff
	s_nop 0
	v_cndmask_b32_e64 v20, 0, v226, s[66:67]
	v_add_u32_e32 v132, v20, v24
	v_cmp_lt_i32_e64 s[46:47], s0, v132
	v_add_u32_e32 v34, 0xffffff00, v132
	s_and_saveexec_b64 s[0:1], s[94:95]
	s_xor_b64 s[36:37], exec, s[0:1]
	s_mov_b64 s[52:53], s[54:55]
	s_cbranch_execz .LBB0_954
	s_and_saveexec_b64 s[0:1], s[92:93]
	s_xor_b64 s[24:25], exec, s[0:1]
	s_cbranch_execz .LBB0_951
	s_and_saveexec_b64 s[0:1], s[96:97]
	s_xor_b64 s[26:27], exec, s[0:1]
	s_cbranch_execz .LBB0_940
	s_and_saveexec_b64 s[0:1], s[90:91]
	s_xor_b64 s[0:1], exec, s[0:1]
	s_cbranch_execz .LBB0_935
	s_and_saveexec_b64 s[18:19], s[80:81]
	s_xor_b64 s[18:19], exec, s[18:19]
	s_cbranch_execz .LBB0_932
	s_and_saveexec_b64 s[40:41], s[78:79]
	s_cbranch_execz .LBB0_931
	s_mov_b64 s[14:15], s[46:47]
	s_mov_b64 s[44:45], exec
	v_readlane_b32 s46, v252, 17
	v_readlane_b32 s47, v252, 18
	s_and_b64 s[46:47], s[44:45], s[46:47]
	s_xor_b64 s[44:45], s[46:47], s[44:45]
	s_mov_b64 exec, s[46:47]
	s_cbranch_execz .LBB0_929
	s_and_saveexec_b64 s[46:47], s[54:55]
	s_xor_b64 s[46:47], exec, s[46:47]
	s_cbranch_execz .LBB0_926
	s_and_saveexec_b64 s[48:49], s[62:63]
	s_xor_b64 s[48:49], exec, s[48:49]
	s_cbranch_execz .LBB0_923
	s_and_saveexec_b64 s[50:51], s[58:59]
	s_xor_b64 s[50:51], exec, s[50:51]
	s_cbranch_execz .LBB0_920
	v_mul_f32_e32 v16, 0xbfb8aa3b, v16
	v_mul_f32_e32 v17, 0xbfb8aa3b, v17
	v_exp_f32_e32 v16, v16
	v_exp_f32_e32 v17, v17
	s_nop 0
	v_pk_add_f32 v[16:17], v[16:17], 1.0 op_sel_hi:[1,0]
	s_nop 0
	s_nop 0
	v_rcp_f32_e32 v20, v17
	s_nop 0
	v_rcp_f32_e32 v21, v16
	v_mul_f32_e32 v16, 0xbfb8aa3b, v18
	v_mul_f32_e32 v17, 0xbfb8aa3b, v19
	v_exp_f32_e32 v16, v16
	v_exp_f32_e32 v17, v17
	s_nop 0
	v_pk_add_f32 v[16:17], v[16:17], 1.0 op_sel_hi:[1,0]
	s_nop 0
	s_nop 0
	v_rcp_f32_e32 v18, v17
	s_nop 0
	v_rcp_f32_e32 v19, v16
	v_mul_f32_e32 v16, 0xbfb8aa3b, v128
	v_mul_f32_e32 v17, 0xbfb8aa3b, v129
	v_exp_f32_e32 v16, v16
	v_exp_f32_e32 v17, v17
	s_nop 0
	v_pk_add_f32 v[16:17], v[16:17], 1.0 op_sel_hi:[1,0]
	s_nop 0
	s_nop 0
	v_rcp_f32_e32 v22, v17
	s_nop 0
	v_rcp_f32_e32 v23, v16
	v_mul_f32_e32 v16, 0xbfb8aa3b, v130
	v_mul_f32_e32 v17, 0xbfb8aa3b, v131
	v_exp_f32_e32 v16, v16
	v_exp_f32_e32 v17, v17
	s_nop 0
	v_pk_add_f32 v[16:17], v[16:17], 1.0 op_sel_hi:[1,0]
	s_nop 0
	s_nop 0
	v_rcp_f32_e32 v25, v17
	s_nop 0
	v_rcp_f32_e32 v26, v16
	v_cvt_pk_bf16_f32 v16, v21, v20
	v_mov_b64_e32 v[20:21], s[4:5]
	v_mad_i64_i32 v[20:21], s[54:55], v24, s85, v[20:21]
	v_lshl_add_u64 v[20:21], v[160:161], 1, v[20:21]
	v_add_co_u32_e32 v20, vcc, 0x1286e000, v20
	v_cvt_pk_bf16_f32 v17, v19, v18
	v_cvt_pk_bf16_f32 v18, v23, v22
	v_cvt_pk_bf16_f32 v19, v26, v25
	v_addc_co_u32_e32 v21, vcc, 0, v21, vcc
	global_store_dwordx4 v[20:21], v[16:19], off offset:2560

; __device__ __forceinline__ u32x4 pack8(const float* v) { u32x4 w; w.x = pk2(v[0], v[1]); w.y = pk2(v[2], v[3]); w.z = pk2(v[4], v[5]); w.w = pk2(v[6], v[7]); return w; }
; __device__ __forceinline__ float sigmoidf_(float x) { return 1.f / (1.f + __expf(-x)); }
;     __device__ __forceinline__ void operator()(const f32x4 (&acc)[2][2][4][2], const pg8::Unit& u, int wr, int wc, int fr, int fq) const {
;         EPI_LOOP_BEGIN
;             const int b = (t >= TB) ? 1 : 0, i = t - b * TB; const bool lat = i >= LC; const int pos = i - LC;
;             if (c0 < 640) {
;     ...
;             } else {
; #pragma unroll
;                 for (int e = 0; e < 8; ++e) v[e] = sigmoidf_(v[e]);
;                 *(u32x4*)((bf16_t*)(ws + O_GATES) + (size_t)t * 3072 + (c0 - 2816)) = pack8(v);
.LBB0_960:
	s_or_b64 exec, exec, s[0:1]
	v_add_u32_e32 v20, 0x80, v150
	v_cmp_lt_i32_e64 s[14:15], s84, v20
	s_movk_i32 s0, 0xff
	s_nop 0
	v_cndmask_b32_e64 v16, 0, v226, s[14:15]
	v_add_u32_e32 v128, v16, v20
	v_cmp_lt_i32_e64 s[54:55], s0, v128
	v_add_u32_e32 v26, 0xffffff00, v128
	s_and_saveexec_b64 s[0:1], s[94:95]
	v_writelane_b32 v252, s54, 19
	s_xor_b64 s[36:37], exec, s[0:1]
	s_mov_b64 s[50:51], s[58:59]
	v_writelane_b32 v252, s55, 20
	v_writelane_b32 v252, s46, 21
	s_nop 1
	v_writelane_b32 v252, s47, 22
	s_cbranch_execz .LBB0_1005
	s_and_saveexec_b64 s[0:1], s[92:93]
	s_xor_b64 s[24:25], exec, s[0:1]
	s_cbranch_execz .LBB0_1002
	s_and_saveexec_b64 s[0:1], s[96:97]
	s_xor_b64 s[26:27], exec, s[0:1]
	s_cbranch_execz .LBB0_991
	s_and_saveexec_b64 s[0:1], s[90:91]
	s_xor_b64 s[0:1], exec, s[0:1]
	s_cbranch_execz .LBB0_986
	s_and_saveexec_b64 s[18:19], s[80:81]
	s_xor_b64 s[18:19], exec, s[18:19]
	s_cbranch_execz .LBB0_983
	s_and_saveexec_b64 s[40:41], s[78:79]
	s_cbranch_execz .LBB0_982
	s_mov_b64 s[44:45], exec
	v_readlane_b32 s46, v252, 17
	v_readlane_b32 s47, v252, 18
	s_and_b64 s[46:47], s[44:45], s[46:47]
	s_xor_b64 s[44:45], s[46:47], s[44:45]
	s_mov_b64 exec, s[46:47]
	s_cbranch_execz .LBB0_980
	s_and_saveexec_b64 s[46:47], s[52:53]
	s_xor_b64 s[46:47], exec, s[46:47]
	s_cbranch_execz .LBB0_977
	s_and_saveexec_b64 s[48:49], s[62:63]
	s_xor_b64 s[48:49], exec, s[48:49]
	s_cbranch_execz .LBB0_974
	s_and_saveexec_b64 s[54:55], s[58:59]
	s_xor_b64 s[54:55], exec, s[54:55]
	s_cbranch_execz .LBB0_971
	v_mul_f32_e32 v12, 0xbfb8aa3b, v12
	v_mul_f32_e32 v13, 0xbfb8aa3b, v13
	v_exp_f32_e32 v12, v12
	v_exp_f32_e32 v13, v13
	s_nop 0
	v_pk_add_f32 v[12:13], v[12:13], 1.0 op_sel_hi:[1,0]
	s_nop 0
	s_nop 0
	v_rcp_f32_e32 v16, v13
	s_nop 0
	v_rcp_f32_e32 v17, v12
	v_mul_f32_e32 v12, 0xbfb8aa3b, v14
	v_mul_f32_e32 v13, 0xbfb8aa3b, v15
	v_exp_f32_e32 v12, v12
	v_exp_f32_e32 v13, v13
	s_nop 0
	v_pk_add_f32 v[12:13], v[12:13], 1.0 op_sel_hi:[1,0]
	s_nop 0
	s_nop 0
	v_rcp_f32_e32 v14, v13
	s_nop 0
	v_rcp_f32_e32 v15, v12
	v_mul_f32_e32 v12, 0xbfb8aa3b, v124
	v_mul_f32_e32 v13, 0xbfb8aa3b, v125
	v_exp_f32_e32 v12, v12
	v_exp_f32_e32 v13, v13
	s_nop 0
	v_pk_add_f32 v[12:13], v[12:13], 1.0 op_sel_hi:[1,0]
	s_nop 0
	s_nop 0
	v_rcp_f32_e32 v18, v13
	s_nop 0
	v_rcp_f32_e32 v19, v12
	v_mul_f32_e32 v12, 0xbfb8aa3b, v126
	v_mul_f32_e32 v13, 0xbfb8aa3b, v127
	v_exp_f32_e32 v12, v12
	v_exp_f32_e32 v13, v13
	s_nop 0
	v_pk_add_f32 v[12:13], v[12:13], 1.0 op_sel_hi:[1,0]
	s_nop 0
	s_nop 0
	v_rcp_f32_e32 v21, v13
	s_nop 0
	v_rcp_f32_e32 v22, v12
	v_cvt_pk_bf16_f32 v12, v17, v16
	v_mov_b64_e32 v[16:17], s[4:5]
	v_mad_i64_i32 v[16:17], s[58:59], v20, s85, v[16:17]
	v_lshl_add_u64 v[16:17], v[160:161], 1, v[16:17]
	v_add_co_u32_e32 v16, vcc, 0x1286e000, v16
	v_cvt_pk_bf16_f32 v13, v15, v14
	v_cvt_pk_bf16_f32 v14, v19, v18
	v_cvt_pk_bf16_f32 v15, v22, v21
	v_addc_co_u32_e32 v17, vcc, 0, v17, vcc
	global_store_dwordx4 v[16:17], v[12:15], off offset:2560

; __device__ __forceinline__ u32x4 pack8(const float* v) { u32x4 w; w.x = pk2(v[0], v[1]); w.y = pk2(v[2], v[3]); w.z = pk2(v[4], v[5]); w.w = pk2(v[6], v[7]); return w; }
; __device__ __forceinline__ float sigmoidf_(float x) { return 1.f / (1.f + __expf(-x)); }
;     __device__ __forceinline__ void operator()(const f32x4 (&acc)[2][2][4][2], const pg8::Unit& u, int wr, int wc, int fr, int fq) const {
;         EPI_LOOP_BEGIN
;             const int b = (t >= TB) ? 1 : 0, i = t - b * TB; const bool lat = i >= LC; const int pos = i - LC;
;             if (c0 < 640) {
;     ...
;             } else {
; #pragma unroll
;                 for (int e = 0; e < 8; ++e) v[e] = sigmoidf_(v[e]);
;                 *(u32x4*)((bf16_t*)(ws + O_GATES) + (size_t)t * 3072 + (c0 - 2816)) = pack8(v);
.LBB0_1011:
	s_or_b64 exec, exec, s[0:1]
	v_add_u32_e32 v16, 0x90, v150
	v_cmp_lt_i32_e64 s[58:59], s84, v16
	s_movk_i32 s0, 0xff
	s_nop 0
	v_cndmask_b32_e64 v12, 0, v226, s[58:59]
	v_add_u32_e32 v124, v12, v16
	v_cmp_lt_i32_e64 s[46:47], s0, v124
	v_add_u32_e32 v18, 0xffffff00, v124
	s_and_saveexec_b64 s[0:1], s[94:95]
	s_xor_b64 s[36:37], exec, s[0:1]
	s_cbranch_execz .LBB0_1056
	s_and_saveexec_b64 s[0:1], s[92:93]
	s_xor_b64 s[24:25], exec, s[0:1]
	s_cbranch_execz .LBB0_1053
	s_and_saveexec_b64 s[0:1], s[96:97]
	s_xor_b64 s[26:27], exec, s[0:1]
	s_cbranch_execz .LBB0_1042
	s_and_saveexec_b64 s[0:1], s[90:91]
	s_xor_b64 s[0:1], exec, s[0:1]
	s_cbranch_execz .LBB0_1037
	s_and_saveexec_b64 s[18:19], s[80:81]
	s_xor_b64 s[18:19], exec, s[18:19]
	s_cbranch_execz .LBB0_1034
	s_and_saveexec_b64 s[40:41], s[78:79]
	s_cbranch_execz .LBB0_1033
	s_mov_b64 s[44:45], exec
	v_readlane_b32 s48, v252, 17
	v_readlane_b32 s49, v252, 18
	s_and_b64 s[48:49], s[44:45], s[48:49]
	s_xor_b64 s[44:45], s[48:49], s[44:45]
	s_mov_b64 exec, s[48:49]
	s_cbranch_execz .LBB0_1031
	s_and_saveexec_b64 s[48:49], s[52:53]
	s_xor_b64 s[48:49], exec, s[48:49]
	s_cbranch_execz .LBB0_1028
	s_and_saveexec_b64 s[54:55], s[62:63]
	s_xor_b64 s[54:55], exec, s[54:55]
	v_writelane_b32 v252, s54, 23
	s_nop 1
	v_writelane_b32 v252, s55, 24
	s_cbranch_execz .LBB0_1025
	s_and_saveexec_b64 s[54:55], s[50:51]
	s_xor_b64 s[54:55], exec, s[54:55]
	s_cbranch_execz .LBB0_1022
	v_mul_f32_e32 v8, 0xbfb8aa3b, v8
	v_mul_f32_e32 v9, 0xbfb8aa3b, v9
	v_exp_f32_e32 v8, v8
	v_exp_f32_e32 v9, v9
	v_writelane_b32 v252, s54, 25
	v_pk_add_f32 v[8:9], v[8:9], 1.0 op_sel_hi:[1,0]
	s_nop 0
	v_writelane_b32 v252, s55, 26
	s_nop 0
	v_rcp_f32_e32 v12, v9
	s_nop 0
	v_rcp_f32_e32 v13, v8
	v_mul_f32_e32 v8, 0xbfb8aa3b, v10
	v_mul_f32_e32 v9, 0xbfb8aa3b, v11
	v_exp_f32_e32 v8, v8
	v_exp_f32_e32 v9, v9
	s_nop 0
	v_pk_add_f32 v[8:9], v[8:9], 1.0 op_sel_hi:[1,0]
	s_nop 0
	s_nop 0
	v_rcp_f32_e32 v10, v9
	s_nop 0
	v_rcp_f32_e32 v11, v8
	v_mul_f32_e32 v8, 0xbfb8aa3b, v120
	v_mul_f32_e32 v9, 0xbfb8aa3b, v121
	v_exp_f32_e32 v8, v8
	v_exp_f32_e32 v9, v9
	s_nop 0
	v_pk_add_f32 v[8:9], v[8:9], 1.0 op_sel_hi:[1,0]
	s_nop 0
	s_nop 0
	v_rcp_f32_e32 v14, v9
	s_nop 0
	v_rcp_f32_e32 v15, v8
	v_mul_f32_e32 v8, 0xbfb8aa3b, v122
	v_mul_f32_e32 v9, 0xbfb8aa3b, v123
	v_exp_f32_e32 v8, v8
	v_exp_f32_e32 v9, v9
	s_nop 0
	v_pk_add_f32 v[8:9], v[8:9], 1.0 op_sel_hi:[1,0]
	s_nop 0
	s_nop 0
	v_rcp_f32_e32 v17, v9
	s_nop 0
	v_rcp_f32_e32 v19, v8
	v_cvt_pk_bf16_f32 v8, v13, v12
	v_mov_b64_e32 v[12:13], s[4:5]
	v_mad_i64_i32 v[12:13], s[54:55], v16, s85, v[12:13]
	v_lshl_add_u64 v[12:13], v[160:161], 1, v[12:13]
	v_readlane_b32 s54, v252, 25
	v_add_co_u32_e32 v12, vcc, 0x1286e000, v12
	v_cvt_pk_bf16_f32 v9, v11, v10
	v_cvt_pk_bf16_f32 v10, v15, v14
	v_cvt_pk_bf16_f32 v11, v19, v17
	v_readlane_b32 s55, v252, 26
	v_addc_co_u32_e32 v13, vcc, 0, v13, vcc
	global_store_dwordx4 v[12:13], v[8:11], off offset:2560

; __device__ __forceinline__ u32x4 pack8(const float* v) { u32x4 w; w.x = pk2(v[0], v[1]); w.y = pk2(v[2], v[3]); w.z = pk2(v[4], v[5]); w.w = pk2(v[6], v[7]); return w; }
; __device__ __forceinline__ float sigmoidf_(float x) { return 1.f / (1.f + __expf(-x)); }
;     __device__ __forceinline__ void operator()(const f32x4 (&acc)[2][2][4][2], const pg8::Unit& u, int wr, int wc, int fr, int fq) const {
;         EPI_LOOP_BEGIN
;             const int b = (t >= TB) ? 1 : 0, i = t - b * TB; const bool lat = i >= LC; const int pos = i - LC;
;             if (c0 < 640) {
;     ...
;             } else {
; #pragma unroll
;                 for (int e = 0; e < 8; ++e) v[e] = sigmoidf_(v[e]);
;                 *(u32x4*)((bf16_t*)(ws + O_GATES) + (size_t)t * 3072 + (c0 - 2816)) = pack8(v);
.LBB0_1062:
	s_or_b64 exec, exec, s[0:1]
	v_add_u32_e32 v12, 0xa0, v150
	v_cmp_lt_i32_e64 s[54:55], s84, v12
	s_movk_i32 s0, 0xff
	s_nop 0
	v_cndmask_b32_e64 v8, 0, v226, s[54:55]
	v_add_u32_e32 v30, v8, v12
	v_cmp_lt_i32_e64 s[44:45], s0, v30
	v_add_u32_e32 v14, 0xffffff00, v30
	s_and_saveexec_b64 s[0:1], s[94:95]
	s_xor_b64 s[36:37], exec, s[0:1]
	s_cbranch_execz .LBB0_1107
	s_and_saveexec_b64 s[0:1], s[92:93]
	s_xor_b64 s[24:25], exec, s[0:1]
	s_cbranch_execz .LBB0_1104
	s_and_saveexec_b64 s[0:1], s[96:97]
	s_xor_b64 s[26:27], exec, s[0:1]
	s_cbranch_execz .LBB0_1093
	s_and_saveexec_b64 s[0:1], s[90:91]
	s_xor_b64 s[0:1], exec, s[0:1]
	s_cbranch_execz .LBB0_1088
	s_and_saveexec_b64 s[18:19], s[80:81]
	s_xor_b64 s[18:19], exec, s[18:19]
	s_cbranch_execz .LBB0_1085
	s_and_saveexec_b64 s[40:41], s[78:79]
	s_cbranch_execz .LBB0_1084
	s_mov_b64 s[48:49], exec
	v_readlane_b32 vcc_lo, v252, 17
	v_readlane_b32 vcc_hi, v252, 18
	s_and_b64 vcc, s[48:49], vcc
	s_xor_b64 s[48:49], vcc, s[48:49]
	v_writelane_b32 v252, s48, 23
	s_nop 1
	v_writelane_b32 v252, s49, 24
	s_mov_b64 exec, vcc
	s_cbranch_execz .LBB0_1082
	s_and_saveexec_b64 s[48:49], s[52:53]
	s_xor_b64 s[48:49], exec, s[48:49]
	v_writelane_b32 v252, s48, 25
	s_nop 1
	v_writelane_b32 v252, s49, 26
	s_cbranch_execz .LBB0_1079
	s_and_saveexec_b64 s[48:49], s[62:63]
	s_xor_b64 s[48:49], exec, s[48:49]
	v_writelane_b32 v252, s48, 27
	s_nop 1
	v_writelane_b32 v252, s49, 28
	s_cbranch_execz .LBB0_1076
	s_and_saveexec_b64 s[48:49], s[50:51]
	s_xor_b64 s[48:49], exec, s[48:49]
	s_cbranch_execz .LBB0_1073
	v_mul_f32_e32 v4, 0xbfb8aa3b, v4
	v_mul_f32_e32 v5, 0xbfb8aa3b, v5
	v_exp_f32_e32 v4, v4
	v_exp_f32_e32 v5, v5
	v_writelane_b32 v252, s48, 29
	v_pk_add_f32 v[4:5], v[4:5], 1.0 op_sel_hi:[1,0]
	s_nop 0
	v_writelane_b32 v252, s49, 30
	s_nop 0
	v_rcp_f32_e32 v8, v5
	s_nop 0
	v_rcp_f32_e32 v9, v4
	v_mul_f32_e32 v4, 0xbfb8aa3b, v6
	v_mul_f32_e32 v5, 0xbfb8aa3b, v7
	v_exp_f32_e32 v4, v4
	v_exp_f32_e32 v5, v5
	s_nop 0
	v_pk_add_f32 v[4:5], v[4:5], 1.0 op_sel_hi:[1,0]
	s_nop 0
	s_nop 0
	v_rcp_f32_e32 v6, v5
	s_nop 0
	v_rcp_f32_e32 v7, v4
	v_mul_f32_e32 v4, 0xbfb8aa3b, v116
	v_mul_f32_e32 v5, 0xbfb8aa3b, v117
	v_exp_f32_e32 v4, v4
	v_exp_f32_e32 v5, v5
	s_nop 0
	v_pk_add_f32 v[4:5], v[4:5], 1.0 op_sel_hi:[1,0]
	s_nop 0
	s_nop 0
	v_rcp_f32_e32 v10, v5
	s_nop 0
	v_rcp_f32_e32 v11, v4
	v_mul_f32_e32 v4, 0xbfb8aa3b, v118
	v_mul_f32_e32 v5, 0xbfb8aa3b, v119
	v_exp_f32_e32 v4, v4
	v_exp_f32_e32 v5, v5
	s_nop 0
	v_pk_add_f32 v[4:5], v[4:5], 1.0 op_sel_hi:[1,0]
	s_nop 0
	s_nop 0
	v_rcp_f32_e32 v13, v5
	s_nop 0
	v_rcp_f32_e32 v15, v4
	v_cvt_pk_bf16_f32 v4, v9, v8
	v_mov_b64_e32 v[8:9], s[4:5]
	v_mad_i64_i32 v[8:9], s[48:49], v12, s85, v[8:9]
	v_lshl_add_u64 v[8:9], v[160:161], 1, v[8:9]
	v_readlane_b32 s48, v252, 29
	v_add_co_u32_e32 v8, vcc, 0x1286e000, v8
	v_cvt_pk_bf16_f32 v5, v7, v6
	v_cvt_pk_bf16_f32 v6, v11, v10
	v_cvt_pk_bf16_f32 v7, v15, v13
	v_readlane_b32 s49, v252, 30
	v_addc_co_u32_e32 v9, vcc, 0, v9, vcc
	global_store_dwordx4 v[8:9], v[4:7], off offset:2560

; __device__ __forceinline__ u32x4 pack8(const float* v) { u32x4 w; w.x = pk2(v[0], v[1]); w.y = pk2(v[2], v[3]); w.z = pk2(v[4], v[5]); w.w = pk2(v[6], v[7]); return w; }
; __device__ __forceinline__ float sigmoidf_(float x) { return 1.f / (1.f + __expf(-x)); }
;     __device__ __forceinline__ void operator()(const f32x4 (&acc)[2][2][4][2], const pg8::Unit& u, int wr, int wc, int fr, int fq) const {
;         EPI_LOOP_BEGIN
;             const int b = (t >= TB) ? 1 : 0, i = t - b * TB; const bool lat = i >= LC; const int pos = i - LC;
;             if (c0 < 640) {
;     ...
;             } else {
; #pragma unroll
;                 for (int e = 0; e < 8; ++e) v[e] = sigmoidf_(v[e]);
;                 *(u32x4*)((bf16_t*)(ws + O_GATES) + (size_t)t * 3072 + (c0 - 2816)) = pack8(v);
.LBB0_1113:
	s_or_b64 exec, exec, s[0:1]
	v_add_u32_e32 v8, 0xb0, v150
	v_cmp_lt_i32_e64 s[48:49], s84, v8
	s_movk_i32 s0, 0xff
	s_nop 0
	v_cndmask_b32_e64 v4, 0, v226, s[48:49]
	v_add_u32_e32 v22, v4, v8
	v_cmp_lt_i32_e64 s[40:41], s0, v22
	v_add_u32_e32 v10, 0xffffff00, v22
	s_and_saveexec_b64 s[0:1], s[94:95]
	s_xor_b64 s[36:37], exec, s[0:1]
	s_cbranch_execz .LBB0_1158
	s_and_saveexec_b64 s[0:1], s[92:93]
	s_xor_b64 s[24:25], exec, s[0:1]
	s_cbranch_execz .LBB0_1155
	s_and_saveexec_b64 s[0:1], s[96:97]
	s_xor_b64 s[26:27], exec, s[0:1]
	s_cbranch_execz .LBB0_1144
	s_and_saveexec_b64 s[0:1], s[90:91]
	s_xor_b64 s[0:1], exec, s[0:1]
	s_cbranch_execz .LBB0_1139
	s_and_saveexec_b64 s[18:19], s[80:81]
	s_xor_b64 s[18:19], exec, s[18:19]
	s_cbranch_execz .LBB0_1136
	s_and_saveexec_b64 s[94:95], s[78:79]
	s_cbranch_execz .LBB0_1135
	s_mov_b64 s[78:79], exec
	v_readlane_b32 s80, v252, 17
	v_readlane_b32 s81, v252, 18
	s_and_b64 s[80:81], s[78:79], s[80:81]
	s_xor_b64 s[90:91], s[80:81], s[78:79]
	s_mov_b64 exec, s[80:81]
	s_cbranch_execz .LBB0_1133
	s_and_saveexec_b64 s[78:79], s[52:53]
	s_xor_b64 s[92:93], exec, s[78:79]
	s_cbranch_execz .LBB0_1130
	s_and_saveexec_b64 s[78:79], s[62:63]
	s_xor_b64 s[80:81], exec, s[78:79]
	s_cbranch_execz .LBB0_1127
	s_and_saveexec_b64 s[78:79], s[50:51]
	s_xor_b64 s[78:79], exec, s[78:79]
	s_cbranch_execz .LBB0_1124
	v_mul_f32_e32 v0, 0xbfb8aa3b, v0
	v_mul_f32_e32 v1, 0xbfb8aa3b, v1
	v_exp_f32_e32 v0, v0
	v_exp_f32_e32 v1, v1
	s_nop 0
	v_pk_add_f32 v[0:1], v[0:1], 1.0 op_sel_hi:[1,0]
	s_nop 0
	s_nop 0
	v_rcp_f32_e32 v4, v1
	s_nop 0
	v_rcp_f32_e32 v5, v0
	v_mul_f32_e32 v0, 0xbfb8aa3b, v2
	v_mul_f32_e32 v1, 0xbfb8aa3b, v3
	v_exp_f32_e32 v0, v0
	v_exp_f32_e32 v1, v1
	s_nop 0
	v_pk_add_f32 v[0:1], v[0:1], 1.0 op_sel_hi:[1,0]
	s_nop 0
	s_nop 0
	v_rcp_f32_e32 v2, v1
	s_nop 0
	v_rcp_f32_e32 v3, v0
	v_mul_f32_e32 v0, 0xbfb8aa3b, v112
	v_mul_f32_e32 v1, 0xbfb8aa3b, v113
	v_exp_f32_e32 v0, v0
	v_exp_f32_e32 v1, v1
	s_nop 0
	v_pk_add_f32 v[0:1], v[0:1], 1.0 op_sel_hi:[1,0]
	s_nop 0
	s_nop 0
	v_rcp_f32_e32 v6, v1
	s_nop 0
	v_rcp_f32_e32 v7, v0
	v_mul_f32_e32 v0, 0xbfb8aa3b, v114
	v_mul_f32_e32 v1, 0xbfb8aa3b, v115
	v_exp_f32_e32 v0, v0
	v_exp_f32_e32 v1, v1
	s_nop 0
	v_pk_add_f32 v[0:1], v[0:1], 1.0 op_sel_hi:[1,0]
	s_nop 0
	s_nop 0
	v_rcp_f32_e32 v9, v1
	s_nop 0
	v_rcp_f32_e32 v11, v0
	v_cvt_pk_bf16_f32 v0, v5, v4
	v_mov_b64_e32 v[4:5], s[4:5]
	v_mad_i64_i32 v[4:5], s[96:97], v8, s85, v[4:5]
	v_lshl_add_u64 v[4:5], v[160:161], 1, v[4:5]
	v_add_co_u32_e32 v4, vcc, 0x1286e000, v4
	v_cvt_pk_bf16_f32 v1, v3, v2
	v_cvt_pk_bf16_f32 v2, v7, v6
	v_cvt_pk_bf16_f32 v3, v11, v9
	v_addc_co_u32_e32 v5, vcc, 0, v5, vcc
	global_store_dwordx4 v[4:5], v[0:3], off offset:2560

; __device__ __forceinline__ u32x4 pack8(const float* v) { u32x4 w; w.x = pk2(v[0], v[1]); w.y = pk2(v[2], v[3]); w.z = pk2(v[4], v[5]); w.w = pk2(v[6], v[7]); return w; }
; __device__ __forceinline__ float sigmoidf_(float x) { return 1.f / (1.f + __expf(-x)); }
;     __device__ __forceinline__ void operator()(const f32x4 (&acc)[2][2][4][2], const pg8::Unit& u, int wr, int wc, int fr, int fq) const {
;         EPI_LOOP_BEGIN
;             const int b = (t >= TB) ? 1 : 0, i = t - b * TB; const bool lat = i >= LC; const int pos = i - LC;
;             if (c0 < 640) {
;     ...
;             } else {
; #pragma unroll
;                 for (int e = 0; e < 8; ++e) v[e] = sigmoidf_(v[e]);
;                 *(u32x4*)((bf16_t*)(ws + O_GATES) + (size_t)t * 3072 + (c0 - 2816)) = pack8(v);
.LBB0_1164:
	s_or_b64 exec, exec, s[0:1]
	v_add_u32_e32 v4, 0x80, v160
	s_movk_i32 s0, 0x27f
	v_cmp_lt_i32_e64 s[96:97], s0, v4
	s_movk_i32 s0, 0x2ff
	v_cmp_lt_u32_e64 s[94:95], s0, v4
	s_movk_i32 s0, 0x47f
	v_cmp_lt_u32_e64 s[92:93], s0, v4
	s_movk_i32 s0, 0x49f
	v_cmp_lt_u32_e64 s[90:91], s0, v4
	s_movk_i32 s0, 0x4bf
	v_cmp_lt_u32_e64 s[0:1], s0, v4
	v_add_u32_e32 v0, 0xfffffc00, v148
	v_lshrrev_b32_e32 v6, 1, v0
	v_writelane_b32 v252, s0, 17
	v_add_u32_e32 v0, 0xfffffe00, v160
	v_mov_b32_e32 v5, v36
	v_writelane_b32 v252, s1, 18
	s_movk_i32 s0, 0x4ff
	v_cmp_lt_u32_e64 s[0:1], s0, v4
	v_mov_b32_e32 v7, v36
	v_lshrrev_b32_e32 v9, 6, v0
	v_writelane_b32 v252, s0, 23
	s_nop 1
	v_writelane_b32 v252, s1, 24
	s_movk_i32 s0, 0x5ff
	v_cmp_lt_u32_e64 s[0:1], s0, v4
	s_nop 1
	v_writelane_b32 v252, s0, 25
	s_nop 1
	v_writelane_b32 v252, s1, 26
	s_movk_i32 s0, 0x6ff
	v_cmp_lt_u32_e64 s[0:1], s0, v4
	s_nop 1
	v_writelane_b32 v252, s0, 27
	s_nop 1
	v_writelane_b32 v252, s1, 28
	s_movk_i32 s0, 0x8ff
	v_cmp_lt_u32_e64 s[0:1], s0, v4
	s_nop 1
	v_writelane_b32 v252, s0, 29
	s_nop 1
	v_writelane_b32 v252, s1, 30
	s_movk_i32 s0, 0xaff
	v_cmp_lt_u32_e64 s[0:1], s0, v4
	s_nop 1
	v_writelane_b32 v252, s0, 31
	s_nop 1
	v_writelane_b32 v252, s1, 32
	s_movk_i32 s0, 0x3ff
	v_cmp_lt_i32_e64 s[76:77], s0, v4
	s_movk_i32 s0, 0x1ff
	v_cmp_lt_i32_e64 s[74:75], s0, v4
	s_and_saveexec_b64 s[0:1], s[96:97]
	s_xor_b64 s[36:37], exec, s[0:1]
	s_mov_b32 s79, 0x10000
	s_mov_b32 s78, 0x14000
	s_cbranch_execz .LBB0_1209
	s_and_saveexec_b64 s[0:1], s[94:95]
	s_xor_b64 s[24:25], exec, s[0:1]
	s_cbranch_execz .LBB0_1206
	s_and_saveexec_b64 s[0:1], s[92:93]
	s_xor_b64 s[26:27], exec, s[0:1]
	s_cbranch_execz .LBB0_1195
	s_and_saveexec_b64 s[0:1], s[90:91]
	s_xor_b64 s[0:1], exec, s[0:1]
	s_cbranch_execz .LBB0_1190
	s_mov_b64 s[18:19], exec
	v_readlane_b32 s78, v252, 17
	v_readlane_b32 s79, v252, 18
	s_and_b64 s[78:79], s[18:19], s[78:79]
	s_xor_b64 s[18:19], s[78:79], s[18:19]
	s_mov_b64 exec, s[78:79]
	s_cbranch_execz .LBB0_1187
	s_mov_b64 s[78:79], exec
	v_readlane_b32 s80, v252, 23
	v_readlane_b32 s81, v252, 24
	s_and_b64 s[80:81], s[78:79], s[80:81]
	s_mov_b64 exec, s[80:81]
	s_cbranch_execz .LBB0_1186
	s_mov_b64 s[80:81], exec
	v_readlane_b32 vcc_lo, v252, 25
	v_readlane_b32 vcc_hi, v252, 26
	s_and_b64 vcc, s[80:81], vcc
	s_xor_b64 s[50:51], vcc, s[80:81]
	s_mov_b64 exec, vcc
	s_cbranch_execz .LBB0_1184
	s_mov_b64 s[80:81], exec
	v_readlane_b32 vcc_lo, v252, 27
	v_readlane_b32 vcc_hi, v252, 28
	s_and_b64 vcc, s[80:81], vcc
	s_xor_b64 s[52:53], vcc, s[80:81]
	s_mov_b64 exec, vcc
	s_cbranch_execz .LBB0_1181
	s_mov_b64 s[80:81], exec
	v_readlane_b32 vcc_lo, v252, 29
	v_readlane_b32 vcc_hi, v252, 30
	s_and_b64 vcc, s[80:81], vcc
	s_xor_b64 s[62:63], vcc, s[80:81]
	s_mov_b64 exec, vcc
	s_cbranch_execz .LBB0_1178
	s_mov_b64 s[80:81], exec
	v_readlane_b32 vcc_lo, v252, 31
	v_readlane_b32 vcc_hi, v252, 32
	s_and_b64 vcc, s[80:81], vcc
	s_xor_b64 s[80:81], vcc, s[80:81]
	s_mov_b64 exec, vcc
	s_cbranch_execz .LBB0_1175
	v_mul_f32_e32 v0, 0xbfb8aa3b, v108
	v_mul_f32_e32 v1, 0xbfb8aa3b, v109
	v_exp_f32_e32 v0, v0
	v_exp_f32_e32 v1, v1
	v_writelane_b32 v252, s80, 33
	v_pk_add_f32 v[0:1], v[0:1], 1.0 op_sel_hi:[1,0]
	s_nop 0
	v_writelane_b32 v252, s81, 34
	s_nop 0
	v_rcp_f32_e32 v2, v1
	s_nop 0
	v_rcp_f32_e32 v3, v0
	v_mul_f32_e32 v0, 0xbfb8aa3b, v110
	v_mul_f32_e32 v1, 0xbfb8aa3b, v111
	v_exp_f32_e32 v0, v0
	v_exp_f32_e32 v1, v1
	s_nop 0
	v_pk_add_f32 v[0:1], v[0:1], 1.0 op_sel_hi:[1,0]
	s_nop 0
	s_nop 0
	v_rcp_f32_e32 v11, v1
	s_nop 0
	v_rcp_f32_e32 v13, v0
	v_mul_f32_e32 v0, 0xbfb8aa3b, v104
	v_mul_f32_e32 v1, 0xbfb8aa3b, v105
	v_exp_f32_e32 v0, v0
	v_exp_f32_e32 v1, v1
	v_mov_b64_e32 v[104:105], s[4:5]
	v_mad_i64_i32 v[104:105], s[80:81], v150, s85, v[104:105]
	v_pk_add_f32 v[0:1], v[0:1], 1.0 op_sel_hi:[1,0]
	v_lshl_add_u64 v[104:105], v[4:5], 1, v[104:105]
	s_nop 0
	v_rcp_f32_e32 v15, v1
	s_nop 0
	v_rcp_f32_e32 v17, v0
	v_mul_f32_e32 v0, 0xbfb8aa3b, v106
	v_mul_f32_e32 v1, 0xbfb8aa3b, v107
	v_exp_f32_e32 v0, v0
	v_exp_f32_e32 v1, v1
	s_nop 0
	v_pk_add_f32 v[0:1], v[0:1], 1.0 op_sel_hi:[1,0]
	s_nop 0
	s_nop 0
	v_rcp_f32_e32 v19, v1
	v_readlane_b32 s80, v252, 33
	v_readlane_b32 s81, v252, 34
	v_rcp_f32_e32 v21, v0
	v_add_co_u32_e32 v104, vcc, 0x1286e000, v104
	v_cvt_pk_bf16_f32 v0, v3, v2
	v_cvt_pk_bf16_f32 v1, v13, v11
	v_cvt_pk_bf16_f32 v2, v17, v15
	v_cvt_pk_bf16_f32 v3, v21, v19
	v_addc_co_u32_e32 v105, vcc, 0, v105, vcc
	global_store_dwordx4 v[104:105], v[0:3], off offset:2560

; __device__ __forceinline__ u32x4 pack8(const float* v) { u32x4 w; w.x = pk2(v[0], v[1]); w.y = pk2(v[2], v[3]); w.z = pk2(v[4], v[5]); w.w = pk2(v[6], v[7]); return w; }
; __device__ __forceinline__ float sigmoidf_(float x) { return 1.f / (1.f + __expf(-x)); }
;     __device__ __forceinline__ void operator()(const f32x4 (&acc)[2][2][4][2], const pg8::Unit& u, int wr, int wc, int fr, int fq) const {
;     ...
;             const int b = (t >= TB) ? 1 : 0, i = t - b * TB; const bool lat = i >= LC; const int pos = i - LC;
;             if (c0 < 640) {
;     ...
;             } else {
; #pragma unroll
;                 for (int e = 0; e < 8; ++e) v[e] = sigmoidf_(v[e]);
;                 *(u32x4*)((bf16_t*)(ws + O_GATES) + (size_t)t * 3072 + (c0 - 2816)) = pack8(v);
.LBB0_1217:
	s_or_b64 exec, exec, s[0:1]
	s_and_saveexec_b64 s[0:1], s[96:97]
	s_xor_b64 s[36:37], exec, s[0:1]
	s_cbranch_execz .LBB0_1262
	s_and_saveexec_b64 s[0:1], s[94:95]
	s_xor_b64 s[24:25], exec, s[0:1]
	s_cbranch_execz .LBB0_1259
	s_and_saveexec_b64 s[0:1], s[92:93]
	s_xor_b64 s[26:27], exec, s[0:1]
	s_cbranch_execz .LBB0_1248
	s_and_saveexec_b64 s[0:1], s[90:91]
	s_xor_b64 s[0:1], exec, s[0:1]
	s_cbranch_execz .LBB0_1243
	s_mov_b64 s[18:19], exec
	v_readlane_b32 s64, v252, 17
	v_readlane_b32 s65, v252, 18
	s_and_b64 s[64:65], s[18:19], s[64:65]
	s_xor_b64 s[18:19], s[64:65], s[18:19]
	s_mov_b64 exec, s[64:65]
	s_cbranch_execz .LBB0_1240
	s_mov_b64 s[64:65], exec
	v_readlane_b32 s72, v252, 23
	v_readlane_b32 s73, v252, 24
	s_and_b64 s[72:73], s[64:65], s[72:73]
	s_mov_b64 exec, s[72:73]
	s_cbranch_execz .LBB0_1239
	s_mov_b64 s[72:73], exec
	v_readlane_b32 s78, v252, 25
	v_readlane_b32 s79, v252, 26
	s_and_b64 s[78:79], s[72:73], s[78:79]
	s_xor_b64 s[72:73], s[78:79], s[72:73]
	s_mov_b64 exec, s[78:79]
	s_cbranch_execz .LBB0_1237
	s_mov_b64 s[78:79], exec
	v_readlane_b32 s80, v252, 27
	v_readlane_b32 s81, v252, 28
	s_and_b64 s[80:81], s[78:79], s[80:81]
	s_xor_b64 s[78:79], s[80:81], s[78:79]
	s_mov_b64 exec, s[80:81]
	s_cbranch_execz .LBB0_1234
	s_mov_b64 s[80:81], exec
	v_readlane_b32 vcc_lo, v252, 29
	v_readlane_b32 vcc_hi, v252, 30
	s_and_b64 vcc, s[80:81], vcc
	s_xor_b64 s[50:51], vcc, s[80:81]
	s_mov_b64 exec, vcc
	s_cbranch_execz .LBB0_1231
	s_mov_b64 s[80:81], exec
	v_readlane_b32 vcc_lo, v252, 31
	v_readlane_b32 vcc_hi, v252, 32
	s_and_b64 vcc, s[80:81], vcc
	s_xor_b64 s[52:53], vcc, s[80:81]
	s_mov_b64 exec, vcc
	s_cbranch_execz .LBB0_1228
	v_mul_f32_e32 v0, 0xbfb8aa3b, v100
	v_mul_f32_e32 v1, 0xbfb8aa3b, v101
	v_exp_f32_e32 v0, v0
	v_exp_f32_e32 v1, v1
	s_nop 0
	v_pk_add_f32 v[0:1], v[0:1], 1.0 op_sel_hi:[1,0]
	s_nop 0
	s_nop 0
	v_rcp_f32_e32 v2, v1
	s_nop 0
	v_rcp_f32_e32 v3, v0
	v_mul_f32_e32 v0, 0xbfb8aa3b, v102
	v_mul_f32_e32 v1, 0xbfb8aa3b, v103
	v_exp_f32_e32 v0, v0
	v_exp_f32_e32 v1, v1
	s_nop 0
	v_pk_add_f32 v[0:1], v[0:1], 1.0 op_sel_hi:[1,0]
	s_nop 0
	s_nop 0
	v_rcp_f32_e32 v11, v1
	s_nop 0
	v_rcp_f32_e32 v13, v0
	v_mul_f32_e32 v0, 0xbfb8aa3b, v96
	v_mul_f32_e32 v1, 0xbfb8aa3b, v97
	v_exp_f32_e32 v0, v0
	v_exp_f32_e32 v1, v1
	v_mov_b64_e32 v[96:97], s[4:5]
	v_mad_i64_i32 v[32:33], s[80:81], v32, s85, v[96:97]
	v_pk_add_f32 v[0:1], v[0:1], 1.0 op_sel_hi:[1,0]
	v_lshl_add_u64 v[32:33], v[4:5], 1, v[32:33]
	s_nop 0
	v_rcp_f32_e32 v15, v1
	s_nop 0
	v_rcp_f32_e32 v17, v0
	v_mul_f32_e32 v0, 0xbfb8aa3b, v98
	v_mul_f32_e32 v1, 0xbfb8aa3b, v99
	v_exp_f32_e32 v0, v0
	v_exp_f32_e32 v1, v1
	s_nop 0
	v_pk_add_f32 v[0:1], v[0:1], 1.0 op_sel_hi:[1,0]
	s_nop 0
	s_nop 0
	v_rcp_f32_e32 v19, v1
	s_nop 0
	v_rcp_f32_e32 v21, v0
	v_add_co_u32_e32 v32, vcc, 0x1286e000, v32
	v_cvt_pk_bf16_f32 v0, v3, v2
	v_cvt_pk_bf16_f32 v1, v13, v11
	v_cvt_pk_bf16_f32 v2, v17, v15
	v_cvt_pk_bf16_f32 v3, v21, v19
	v_addc_co_u32_e32 v33, vcc, 0, v33, vcc
	global_store_dwordx4 v[32:33], v[0:3], off offset:2560

; __device__ __forceinline__ u32x4 pack8(const float* v) { u32x4 w; w.x = pk2(v[0], v[1]); w.y = pk2(v[2], v[3]); w.z = pk2(v[4], v[5]); w.w = pk2(v[6], v[7]); return w; }
; __device__ __forceinline__ float sigmoidf_(float x) { return 1.f / (1.f + __expf(-x)); }
;     __device__ __forceinline__ void operator()(const f32x4 (&acc)[2][2][4][2], const pg8::Unit& u, int wr, int wc, int fr, int fq) const {
;     ...
;             const int b = (t >= TB) ? 1 : 0, i = t - b * TB; const bool lat = i >= LC; const int pos = i - LC;
;             if (c0 < 640) {
;     ...
;             } else {
; #pragma unroll
;                 for (int e = 0; e < 8; ++e) v[e] = sigmoidf_(v[e]);
;                 *(u32x4*)((bf16_t*)(ws + O_GATES) + (size_t)t * 3072 + (c0 - 2816)) = pack8(v);
.LBB0_1270:
	s_or_b64 exec, exec, s[0:1]
	s_and_saveexec_b64 s[0:1], s[96:97]
	s_xor_b64 s[36:37], exec, s[0:1]
	s_cbranch_execz .LBB0_1315
	s_and_saveexec_b64 s[0:1], s[94:95]
	s_xor_b64 s[24:25], exec, s[0:1]
	s_cbranch_execz .LBB0_1312
	s_and_saveexec_b64 s[0:1], s[92:93]
	s_xor_b64 s[26:27], exec, s[0:1]
	s_cbranch_execz .LBB0_1301
	s_and_saveexec_b64 s[0:1], s[90:91]
	s_xor_b64 s[0:1], exec, s[0:1]
	s_cbranch_execz .LBB0_1296
	s_mov_b64 s[18:19], exec
	v_readlane_b32 s60, v252, 17
	v_readlane_b32 s61, v252, 18
	s_and_b64 s[60:61], s[18:19], s[60:61]
	s_xor_b64 s[18:19], s[60:61], s[18:19]
	s_mov_b64 exec, s[60:61]
	s_cbranch_execz .LBB0_1293
	s_mov_b64 s[60:61], exec
	v_readlane_b32 s64, v252, 23
	v_readlane_b32 s65, v252, 24
	s_and_b64 s[64:65], s[60:61], s[64:65]
	s_mov_b64 exec, s[64:65]
	s_cbranch_execz .LBB0_1292
	s_mov_b64 s[64:65], exec
	v_readlane_b32 s70, v252, 25
	v_readlane_b32 s71, v252, 26
	s_and_b64 s[70:71], s[64:65], s[70:71]
	s_xor_b64 s[64:65], s[70:71], s[64:65]
	s_mov_b64 exec, s[70:71]
	s_cbranch_execz .LBB0_1290
	s_mov_b64 s[70:71], exec
	v_readlane_b32 s72, v252, 27
	v_readlane_b32 s73, v252, 28
	s_and_b64 s[72:73], s[70:71], s[72:73]
	s_xor_b64 s[70:71], s[72:73], s[70:71]
	s_mov_b64 exec, s[72:73]
	s_cbranch_execz .LBB0_1287
	s_mov_b64 s[72:73], exec
	v_readlane_b32 s78, v252, 29
	v_readlane_b32 s79, v252, 30
	s_and_b64 s[78:79], s[72:73], s[78:79]
	s_xor_b64 s[72:73], s[78:79], s[72:73]
	s_mov_b64 exec, s[78:79]
	s_cbranch_execz .LBB0_1284
	s_mov_b64 s[78:79], exec
	v_readlane_b32 s80, v252, 31
	v_readlane_b32 s81, v252, 32
	s_and_b64 s[80:81], s[78:79], s[80:81]
	s_xor_b64 s[78:79], s[80:81], s[78:79]
	s_mov_b64 exec, s[80:81]
	s_cbranch_execz .LBB0_1281
	v_mul_f32_e32 v0, 0xbfb8aa3b, v92
	v_mul_f32_e32 v1, 0xbfb8aa3b, v93
	v_exp_f32_e32 v0, v0
	v_exp_f32_e32 v1, v1
	v_mov_b64_e32 v[32:33], s[4:5]
	v_mad_i64_i32 v[28:29], s[80:81], v28, s85, v[32:33]
	v_pk_add_f32 v[0:1], v[0:1], 1.0 op_sel_hi:[1,0]
	v_lshl_add_u64 v[28:29], v[4:5], 1, v[28:29]
	s_nop 0
	v_rcp_f32_e32 v2, v1
	s_nop 0
	v_rcp_f32_e32 v3, v0
	v_mul_f32_e32 v0, 0xbfb8aa3b, v94
	v_mul_f32_e32 v1, 0xbfb8aa3b, v95
	v_exp_f32_e32 v0, v0
	v_exp_f32_e32 v1, v1
	s_nop 0
	v_pk_add_f32 v[0:1], v[0:1], 1.0 op_sel_hi:[1,0]
	s_nop 0
	s_nop 0
	v_rcp_f32_e32 v11, v1
	s_nop 0
	v_rcp_f32_e32 v13, v0
	v_mul_f32_e32 v0, 0xbfb8aa3b, v88
	v_mul_f32_e32 v1, 0xbfb8aa3b, v89
	v_exp_f32_e32 v0, v0
	v_exp_f32_e32 v1, v1
	s_nop 0
	v_pk_add_f32 v[0:1], v[0:1], 1.0 op_sel_hi:[1,0]
	s_nop 0
	s_nop 0
	v_rcp_f32_e32 v15, v1
	s_nop 0
	v_rcp_f32_e32 v17, v0
	v_mul_f32_e32 v0, 0xbfb8aa3b, v90
	v_mul_f32_e32 v1, 0xbfb8aa3b, v91
	v_exp_f32_e32 v0, v0
	v_exp_f32_e32 v1, v1
	s_nop 0
	v_pk_add_f32 v[0:1], v[0:1], 1.0 op_sel_hi:[1,0]
	s_nop 0
	s_nop 0
	v_rcp_f32_e32 v19, v1
	s_nop 0
	v_rcp_f32_e32 v21, v0
	v_add_co_u32_e32 v28, vcc, 0x1286e000, v28
	v_cvt_pk_bf16_f32 v0, v3, v2
	v_cvt_pk_bf16_f32 v1, v13, v11
	v_cvt_pk_bf16_f32 v2, v17, v15
	v_cvt_pk_bf16_f32 v3, v21, v19
	v_addc_co_u32_e32 v29, vcc, 0, v29, vcc
	global_store_dwordx4 v[28:29], v[0:3], off offset:2560

; __device__ __forceinline__ u32x4 pack8(const float* v) { u32x4 w; w.x = pk2(v[0], v[1]); w.y = pk2(v[2], v[3]); w.z = pk2(v[4], v[5]); w.w = pk2(v[6], v[7]); return w; }
; __device__ __forceinline__ float sigmoidf_(float x) { return 1.f / (1.f + __expf(-x)); }
;     __device__ __forceinline__ void operator()(const f32x4 (&acc)[2][2][4][2], const pg8::Unit& u, int wr, int wc, int fr, int fq) const {
;     ...
;             const int b = (t >= TB) ? 1 : 0, i = t - b * TB; const bool lat = i >= LC; const int pos = i - LC;
;             if (c0 < 640) {
;     ...
;             } else {
; #pragma unroll
;                 for (int e = 0; e < 8; ++e) v[e] = sigmoidf_(v[e]);
;                 *(u32x4*)((bf16_t*)(ws + O_GATES) + (size_t)t * 3072 + (c0 - 2816)) = pack8(v);
.LBB0_1323:
	s_or_b64 exec, exec, s[0:1]
	s_and_saveexec_b64 s[0:1], s[96:97]
	s_xor_b64 s[36:37], exec, s[0:1]
	s_cbranch_execz .LBB0_1368
	s_and_saveexec_b64 s[0:1], s[94:95]
	s_xor_b64 s[24:25], exec, s[0:1]
	s_cbranch_execz .LBB0_1365
	s_and_saveexec_b64 s[0:1], s[92:93]
	s_xor_b64 s[26:27], exec, s[0:1]
	s_cbranch_execz .LBB0_1354
	s_and_saveexec_b64 s[0:1], s[90:91]
	s_xor_b64 s[0:1], exec, s[0:1]
	s_cbranch_execz .LBB0_1349
	s_mov_b64 s[18:19], exec
	v_readlane_b32 s56, v252, 17
	v_readlane_b32 s57, v252, 18
	s_and_b64 s[56:57], s[18:19], s[56:57]
	s_xor_b64 s[18:19], s[56:57], s[18:19]
	s_mov_b64 exec, s[56:57]
	s_cbranch_execz .LBB0_1346
	s_mov_b64 s[56:57], exec
	v_readlane_b32 s60, v252, 23
	v_readlane_b32 s61, v252, 24
	s_and_b64 s[60:61], s[56:57], s[60:61]
	s_mov_b64 exec, s[60:61]
	s_cbranch_execz .LBB0_1345
	s_mov_b64 s[60:61], exec
	v_readlane_b32 s64, v252, 25
	v_readlane_b32 s65, v252, 26
	s_and_b64 s[64:65], s[60:61], s[64:65]
	s_xor_b64 s[60:61], s[64:65], s[60:61]
	s_mov_b64 exec, s[64:65]
	s_cbranch_execz .LBB0_1343
	s_mov_b64 s[64:65], exec
	v_readlane_b32 s68, v252, 27
	v_readlane_b32 s69, v252, 28
	s_and_b64 s[68:69], s[64:65], s[68:69]
	s_xor_b64 s[64:65], s[68:69], s[64:65]
	s_mov_b64 exec, s[68:69]
	s_cbranch_execz .LBB0_1340
	s_mov_b64 s[68:69], exec
	v_readlane_b32 s70, v252, 29
	v_readlane_b32 s71, v252, 30
	s_and_b64 s[70:71], s[68:69], s[70:71]
	s_xor_b64 s[68:69], s[70:71], s[68:69]
	s_mov_b64 exec, s[70:71]
	s_cbranch_execz .LBB0_1337
	s_mov_b64 s[70:71], exec
	v_readlane_b32 s72, v252, 31
	v_readlane_b32 s73, v252, 32
	s_and_b64 s[72:73], s[70:71], s[72:73]
	s_xor_b64 s[70:71], s[72:73], s[70:71]
	s_mov_b64 exec, s[72:73]
	s_cbranch_execz .LBB0_1334
	v_mul_f32_e32 v0, 0xbfb8aa3b, v84
	v_mul_f32_e32 v1, 0xbfb8aa3b, v85
	v_exp_f32_e32 v0, v0
	v_exp_f32_e32 v1, v1
	v_mov_b64_e32 v[28:29], s[4:5]
	v_pk_add_f32 v[0:1], v[0:1], 1.0 op_sel_hi:[1,0]
	s_nop 0
	s_nop 0
	v_rcp_f32_e32 v2, v1
	s_nop 0
	v_rcp_f32_e32 v3, v0
	v_mul_f32_e32 v0, 0xbfb8aa3b, v86
	v_mul_f32_e32 v1, 0xbfb8aa3b, v87
	v_exp_f32_e32 v0, v0
	v_exp_f32_e32 v1, v1
	s_nop 0
	v_pk_add_f32 v[0:1], v[0:1], 1.0 op_sel_hi:[1,0]
	s_nop 0
	s_nop 0
	v_rcp_f32_e32 v11, v1
	s_nop 0
	v_rcp_f32_e32 v13, v0
	v_mul_f32_e32 v0, 0xbfb8aa3b, v80
	v_mul_f32_e32 v1, 0xbfb8aa3b, v81
	v_exp_f32_e32 v0, v0
	v_exp_f32_e32 v1, v1
	s_nop 0
	v_pk_add_f32 v[0:1], v[0:1], 1.0 op_sel_hi:[1,0]
	s_nop 0
	s_nop 0
	v_rcp_f32_e32 v15, v1
	s_nop 0
	v_rcp_f32_e32 v17, v0
	v_mul_f32_e32 v0, 0xbfb8aa3b, v82
	v_mul_f32_e32 v1, 0xbfb8aa3b, v83
	v_exp_f32_e32 v0, v0
	v_exp_f32_e32 v1, v1
	s_nop 0
	v_pk_add_f32 v[0:1], v[0:1], 1.0 op_sel_hi:[1,0]
	s_nop 0
	s_nop 0
	v_rcp_f32_e32 v19, v1
	s_nop 0
	v_mad_i64_i32 v[24:25], s[72:73], v24, s85, v[28:29]
	v_lshl_add_u64 v[24:25], v[4:5], 1, v[24:25]
	v_rcp_f32_e32 v21, v0
	v_add_co_u32_e32 v24, vcc, 0x1286e000, v24
	v_cvt_pk_bf16_f32 v0, v3, v2
	v_cvt_pk_bf16_f32 v1, v13, v11
	v_cvt_pk_bf16_f32 v2, v17, v15
	v_cvt_pk_bf16_f32 v3, v21, v19
	v_addc_co_u32_e32 v25, vcc, 0, v25, vcc
	global_store_dwordx4 v[24:25], v[0:3], off offset:2560

; __device__ __forceinline__ u32x4 pack8(const float* v) { u32x4 w; w.x = pk2(v[0], v[1]); w.y = pk2(v[2], v[3]); w.z = pk2(v[4], v[5]); w.w = pk2(v[6], v[7]); return w; }
; __device__ __forceinline__ float sigmoidf_(float x) { return 1.f / (1.f + __expf(-x)); }
;     __device__ __forceinline__ void operator()(const f32x4 (&acc)[2][2][4][2], const pg8::Unit& u, int wr, int wc, int fr, int fq) const {
;     ...
;             const int b = (t >= TB) ? 1 : 0, i = t - b * TB; const bool lat = i >= LC; const int pos = i - LC;
;             if (c0 < 640) {
;     ...
;             } else {
; #pragma unroll
;                 for (int e = 0; e < 8; ++e) v[e] = sigmoidf_(v[e]);
;                 *(u32x4*)((bf16_t*)(ws + O_GATES) + (size_t)t * 3072 + (c0 - 2816)) = pack8(v);
.LBB0_1376:
	s_or_b64 exec, exec, s[0:1]
	s_and_saveexec_b64 s[0:1], s[96:97]
	s_xor_b64 s[36:37], exec, s[0:1]
	s_cbranch_execz .LBB0_1421
	s_and_saveexec_b64 s[0:1], s[94:95]
	s_xor_b64 s[24:25], exec, s[0:1]
	s_cbranch_execz .LBB0_1418
	s_and_saveexec_b64 s[0:1], s[92:93]
	s_xor_b64 s[26:27], exec, s[0:1]
	s_cbranch_execz .LBB0_1407
	s_and_saveexec_b64 s[0:1], s[90:91]
	s_xor_b64 s[0:1], exec, s[0:1]
	s_cbranch_execz .LBB0_1402
	s_mov_b64 s[18:19], exec
	v_readlane_b32 s52, v252, 17
	v_readlane_b32 s53, v252, 18
	s_and_b64 s[52:53], s[18:19], s[52:53]
	s_xor_b64 s[18:19], s[52:53], s[18:19]
	s_mov_b64 exec, s[52:53]
	s_cbranch_execz .LBB0_1399
	s_mov_b64 s[52:53], exec
	v_readlane_b32 s56, v252, 23
	v_readlane_b32 s57, v252, 24
	s_and_b64 s[56:57], s[52:53], s[56:57]
	s_mov_b64 exec, s[56:57]
	s_cbranch_execz .LBB0_1398
	s_mov_b64 s[56:57], exec
	v_readlane_b32 s60, v252, 25
	v_readlane_b32 s61, v252, 26
	s_and_b64 s[60:61], s[56:57], s[60:61]
	s_xor_b64 s[56:57], s[60:61], s[56:57]
	s_mov_b64 exec, s[60:61]
	s_cbranch_execz .LBB0_1396
	s_mov_b64 s[60:61], exec
	v_readlane_b32 s64, v252, 27
	v_readlane_b32 s65, v252, 28
	s_and_b64 s[64:65], s[60:61], s[64:65]
	s_xor_b64 s[60:61], s[64:65], s[60:61]
	s_mov_b64 exec, s[64:65]
	s_cbranch_execz .LBB0_1393
	s_mov_b64 s[64:65], exec
	v_readlane_b32 s66, v252, 29
	v_readlane_b32 s67, v252, 30
	s_and_b64 s[66:67], s[64:65], s[66:67]
	s_xor_b64 s[64:65], s[66:67], s[64:65]
	s_mov_b64 exec, s[66:67]
	s_cbranch_execz .LBB0_1390
	s_mov_b64 s[66:67], exec
	v_readlane_b32 s68, v252, 31
	v_readlane_b32 s69, v252, 32
	s_and_b64 s[68:69], s[66:67], s[68:69]
	s_xor_b64 s[66:67], s[68:69], s[66:67]
	s_mov_b64 exec, s[68:69]
	s_cbranch_execz .LBB0_1387
	v_mul_f32_e32 v0, 0xbfb8aa3b, v76
	v_mul_f32_e32 v1, 0xbfb8aa3b, v77
	v_exp_f32_e32 v0, v0
	v_exp_f32_e32 v1, v1
	s_nop 0
	v_pk_add_f32 v[0:1], v[0:1], 1.0 op_sel_hi:[1,0]
	s_nop 0
	s_nop 0
	v_rcp_f32_e32 v2, v1
	s_nop 0
	v_rcp_f32_e32 v3, v0
	v_mul_f32_e32 v0, 0xbfb8aa3b, v78
	v_mul_f32_e32 v1, 0xbfb8aa3b, v79
	v_exp_f32_e32 v0, v0
	v_exp_f32_e32 v1, v1
	s_nop 0
	v_pk_add_f32 v[0:1], v[0:1], 1.0 op_sel_hi:[1,0]
	s_nop 0
	s_nop 0
	v_rcp_f32_e32 v11, v1
	s_nop 0
	v_rcp_f32_e32 v13, v0
	v_mul_f32_e32 v0, 0xbfb8aa3b, v72
	v_mul_f32_e32 v1, 0xbfb8aa3b, v73
	v_exp_f32_e32 v0, v0
	v_exp_f32_e32 v1, v1
	s_nop 0
	v_pk_add_f32 v[0:1], v[0:1], 1.0 op_sel_hi:[1,0]
	s_nop 0
	s_nop 0
	v_rcp_f32_e32 v15, v1
	s_nop 0
	v_rcp_f32_e32 v17, v0
	v_mul_f32_e32 v0, 0xbfb8aa3b, v74
	v_mul_f32_e32 v1, 0xbfb8aa3b, v75
	v_exp_f32_e32 v0, v0
	v_exp_f32_e32 v1, v1
	s_nop 0
	v_pk_add_f32 v[0:1], v[0:1], 1.0 op_sel_hi:[1,0]
	s_nop 0
	s_nop 0
	v_rcp_f32_e32 v19, v1
	s_nop 0
	v_rcp_f32_e32 v21, v0
	v_mov_b64_e32 v[24:25], s[4:5]
	v_cvt_pk_bf16_f32 v0, v3, v2
	v_cvt_pk_bf16_f32 v3, v21, v19
	v_mad_i64_i32 v[20:21], s[68:69], v20, s85, v[24:25]
	v_lshl_add_u64 v[20:21], v[4:5], 1, v[20:21]
	v_add_co_u32_e32 v20, vcc, 0x1286e000, v20
	v_cvt_pk_bf16_f32 v1, v13, v11
	v_cvt_pk_bf16_f32 v2, v17, v15
	v_addc_co_u32_e32 v21, vcc, 0, v21, vcc
	global_store_dwordx4 v[20:21], v[0:3], off offset:2560

; __device__ __forceinline__ u32x4 pack8(const float* v) { u32x4 w; w.x = pk2(v[0], v[1]); w.y = pk2(v[2], v[3]); w.z = pk2(v[4], v[5]); w.w = pk2(v[6], v[7]); return w; }
; __device__ __forceinline__ float sigmoidf_(float x) { return 1.f / (1.f + __expf(-x)); }
;     __device__ __forceinline__ void operator()(const f32x4 (&acc)[2][2][4][2], const pg8::Unit& u, int wr, int wc, int fr, int fq) const {
;     ...
;             const int b = (t >= TB) ? 1 : 0, i = t - b * TB; const bool lat = i >= LC; const int pos = i - LC;
;             if (c0 < 640) {
;     ...
;             } else {
; #pragma unroll
;                 for (int e = 0; e < 8; ++e) v[e] = sigmoidf_(v[e]);
;                 *(u32x4*)((bf16_t*)(ws + O_GATES) + (size_t)t * 3072 + (c0 - 2816)) = pack8(v);
.LBB0_1429:
	s_or_b64 exec, exec, s[0:1]
	s_and_saveexec_b64 s[0:1], s[96:97]
	s_xor_b64 s[36:37], exec, s[0:1]
	s_cbranch_execz .LBB0_1474
	s_and_saveexec_b64 s[0:1], s[94:95]
	s_xor_b64 s[24:25], exec, s[0:1]
	s_cbranch_execz .LBB0_1471
	s_and_saveexec_b64 s[0:1], s[92:93]
	s_xor_b64 s[26:27], exec, s[0:1]
	s_cbranch_execz .LBB0_1460
	s_and_saveexec_b64 s[0:1], s[90:91]
	s_xor_b64 s[0:1], exec, s[0:1]
	s_cbranch_execz .LBB0_1455
	s_mov_b64 s[18:19], exec
	v_readlane_b32 s50, v252, 17
	v_readlane_b32 s51, v252, 18
	s_and_b64 s[50:51], s[18:19], s[50:51]
	s_xor_b64 s[18:19], s[50:51], s[18:19]
	s_mov_b64 exec, s[50:51]
	s_cbranch_execz .LBB0_1452
	s_mov_b64 s[50:51], exec
	v_readlane_b32 s52, v252, 23
	v_readlane_b32 s53, v252, 24
	s_and_b64 s[52:53], s[50:51], s[52:53]
	s_mov_b64 exec, s[52:53]
	s_cbranch_execz .LBB0_1451
	s_mov_b64 s[52:53], exec
	v_readlane_b32 s56, v252, 25
	v_readlane_b32 s57, v252, 26
	s_and_b64 s[56:57], s[52:53], s[56:57]
	s_xor_b64 s[52:53], s[56:57], s[52:53]
	s_mov_b64 exec, s[56:57]
	s_cbranch_execz .LBB0_1449
	s_mov_b64 s[56:57], exec
	v_readlane_b32 s60, v252, 27
	v_readlane_b32 s61, v252, 28
	s_and_b64 s[60:61], s[56:57], s[60:61]
	s_xor_b64 s[56:57], s[60:61], s[56:57]
	s_mov_b64 exec, s[60:61]
	s_cbranch_execz .LBB0_1446
	s_mov_b64 s[60:61], exec
	v_readlane_b32 s62, v252, 29
	v_readlane_b32 s63, v252, 30
	s_and_b64 s[62:63], s[60:61], s[62:63]
	s_xor_b64 s[60:61], s[62:63], s[60:61]
	s_mov_b64 exec, s[62:63]
	s_cbranch_execz .LBB0_1443
	s_mov_b64 s[62:63], exec
	v_readlane_b32 s64, v252, 31
	v_readlane_b32 s65, v252, 32
	s_and_b64 s[64:65], s[62:63], s[64:65]
	s_xor_b64 s[62:63], s[64:65], s[62:63]
	s_mov_b64 exec, s[64:65]
	s_cbranch_execz .LBB0_1440
	v_mul_f32_e32 v0, 0xbfb8aa3b, v68
	v_mul_f32_e32 v1, 0xbfb8aa3b, v69
	v_exp_f32_e32 v0, v0
	v_exp_f32_e32 v1, v1
	s_nop 0
	v_pk_add_f32 v[0:1], v[0:1], 1.0 op_sel_hi:[1,0]
	s_nop 0
	s_nop 0
	v_rcp_f32_e32 v2, v1
	s_nop 0
	v_rcp_f32_e32 v3, v0
	v_mul_f32_e32 v0, 0xbfb8aa3b, v70
	v_mul_f32_e32 v1, 0xbfb8aa3b, v71
	v_exp_f32_e32 v0, v0
	v_exp_f32_e32 v1, v1
	s_nop 0
	v_pk_add_f32 v[0:1], v[0:1], 1.0 op_sel_hi:[1,0]
	s_nop 0
	s_nop 0
	v_rcp_f32_e32 v11, v1
	s_nop 0
	v_rcp_f32_e32 v13, v0
	v_mul_f32_e32 v0, 0xbfb8aa3b, v64
	v_mul_f32_e32 v1, 0xbfb8aa3b, v65
	v_exp_f32_e32 v0, v0
	v_exp_f32_e32 v1, v1
	s_nop 0
	v_pk_add_f32 v[0:1], v[0:1], 1.0 op_sel_hi:[1,0]
	s_nop 0
	s_nop 0
	v_rcp_f32_e32 v15, v1
	s_nop 0
	v_rcp_f32_e32 v17, v0
	v_mul_f32_e32 v0, 0xbfb8aa3b, v66
	v_mul_f32_e32 v1, 0xbfb8aa3b, v67
	v_exp_f32_e32 v0, v0
	v_exp_f32_e32 v1, v1
	s_nop 0
	v_pk_add_f32 v[0:1], v[0:1], 1.0 op_sel_hi:[1,0]
	s_nop 0
	s_nop 0
	v_rcp_f32_e32 v18, v1
	s_nop 0
	v_rcp_f32_e32 v19, v0
	v_cvt_pk_bf16_f32 v0, v3, v2
	v_cvt_pk_bf16_f32 v3, v19, v18
	v_mov_b64_e32 v[18:19], s[4:5]
	v_cvt_pk_bf16_f32 v2, v17, v15
	v_mad_i64_i32 v[16:17], s[64:65], v16, s85, v[18:19]
	v_lshl_add_u64 v[16:17], v[4:5], 1, v[16:17]
	v_add_co_u32_e32 v16, vcc, 0x1286e000, v16
	v_cvt_pk_bf16_f32 v1, v13, v11
	s_nop 0
	v_addc_co_u32_e32 v17, vcc, 0, v17, vcc
	global_store_dwordx4 v[16:17], v[0:3], off offset:2560

; __device__ __forceinline__ u32x4 pack8(const float* v) { u32x4 w; w.x = pk2(v[0], v[1]); w.y = pk2(v[2], v[3]); w.z = pk2(v[4], v[5]); w.w = pk2(v[6], v[7]); return w; }
; __device__ __forceinline__ float sigmoidf_(float x) { return 1.f / (1.f + __expf(-x)); }
;     __device__ __forceinline__ void operator()(const f32x4 (&acc)[2][2][4][2], const pg8::Unit& u, int wr, int wc, int fr, int fq) const {
;     ...
;             } else {
; #pragma unroll
;                 for (int e = 0; e < 8; ++e) v[e] = sigmoidf_(v[e]);
;                 *(u32x4*)((bf16_t*)(ws + O_GATES) + (size_t)t * 3072 + (c0 - 2816)) = pack8(v);
.LBB0_1482:
	s_or_b64 exec, exec, s[0:1]
	s_and_saveexec_b64 s[0:1], s[96:97]
	s_xor_b64 s[36:37], exec, s[0:1]
	s_cbranch_execz .LBB0_1527
	s_and_saveexec_b64 s[0:1], s[94:95]
	s_xor_b64 s[24:25], exec, s[0:1]
	s_cbranch_execz .LBB0_1524
	s_and_saveexec_b64 s[0:1], s[92:93]
	s_xor_b64 s[26:27], exec, s[0:1]
	s_cbranch_execz .LBB0_1513
	s_and_saveexec_b64 s[0:1], s[90:91]
	s_xor_b64 s[0:1], exec, s[0:1]
	s_cbranch_execz .LBB0_1508
	s_mov_b64 s[18:19], exec
	v_readlane_b32 s46, v252, 17
	v_readlane_b32 s47, v252, 18
	s_and_b64 s[46:47], s[18:19], s[46:47]
	s_xor_b64 s[18:19], s[46:47], s[18:19]
	s_mov_b64 exec, s[46:47]
	s_cbranch_execz .LBB0_1505
	s_mov_b64 s[46:47], exec
	v_readlane_b32 s50, v252, 23
	v_readlane_b32 s51, v252, 24
	s_and_b64 s[50:51], s[46:47], s[50:51]
	s_mov_b64 exec, s[50:51]
	s_cbranch_execz .LBB0_1504
	s_mov_b64 s[50:51], exec
	v_readlane_b32 s52, v252, 25
	v_readlane_b32 s53, v252, 26
	s_and_b64 s[52:53], s[50:51], s[52:53]
	s_xor_b64 s[50:51], s[52:53], s[50:51]
	s_mov_b64 exec, s[52:53]
	s_cbranch_execz .LBB0_1502
	s_mov_b64 s[52:53], exec
	v_readlane_b32 s56, v252, 27
	v_readlane_b32 s57, v252, 28
	s_and_b64 s[56:57], s[52:53], s[56:57]
	s_xor_b64 s[52:53], s[56:57], s[52:53]
	s_mov_b64 exec, s[56:57]
	s_cbranch_execz .LBB0_1499
	s_mov_b64 s[56:57], exec
	v_readlane_b32 s58, v252, 29
	v_readlane_b32 s59, v252, 30
	s_and_b64 s[58:59], s[56:57], s[58:59]
	s_xor_b64 s[56:57], s[58:59], s[56:57]
	s_mov_b64 exec, s[58:59]
	s_cbranch_execz .LBB0_1496
	s_mov_b64 s[58:59], exec
	v_readlane_b32 s60, v252, 31
	v_readlane_b32 s61, v252, 32
	s_and_b64 s[60:61], s[58:59], s[60:61]
	s_xor_b64 s[58:59], s[60:61], s[58:59]
	s_mov_b64 exec, s[60:61]
	s_cbranch_execz .LBB0_1493
	v_mul_f32_e32 v0, 0xbfb8aa3b, v60
	v_mul_f32_e32 v1, 0xbfb8aa3b, v61
	v_exp_f32_e32 v0, v0
	v_exp_f32_e32 v1, v1
	s_nop 0
	v_pk_add_f32 v[0:1], v[0:1], 1.0 op_sel_hi:[1,0]
	s_nop 0
	s_nop 0
	v_rcp_f32_e32 v2, v1
	s_nop 0
	v_rcp_f32_e32 v3, v0
	v_mul_f32_e32 v0, 0xbfb8aa3b, v62
	v_mul_f32_e32 v1, 0xbfb8aa3b, v63
	v_exp_f32_e32 v0, v0
	v_exp_f32_e32 v1, v1
	s_nop 0
	v_pk_add_f32 v[0:1], v[0:1], 1.0 op_sel_hi:[1,0]
	s_nop 0
	s_nop 0
	v_rcp_f32_e32 v11, v1
	s_nop 0
	v_rcp_f32_e32 v13, v0
	v_mul_f32_e32 v0, 0xbfb8aa3b, v56
	v_mul_f32_e32 v1, 0xbfb8aa3b, v57
	v_exp_f32_e32 v0, v0
	v_exp_f32_e32 v1, v1
	s_nop 0
	v_pk_add_f32 v[0:1], v[0:1], 1.0 op_sel_hi:[1,0]
	s_nop 0
	s_nop 0
	v_rcp_f32_e32 v14, v1
	s_nop 0
	v_rcp_f32_e32 v15, v0
	v_mul_f32_e32 v0, 0xbfb8aa3b, v58
	v_mul_f32_e32 v1, 0xbfb8aa3b, v59
	v_exp_f32_e32 v0, v0
	v_exp_f32_e32 v1, v1
	s_nop 0
	v_pk_add_f32 v[0:1], v[0:1], 1.0 op_sel_hi:[1,0]
	s_nop 0
	s_nop 0
	v_rcp_f32_e32 v16, v1
	s_nop 0
	v_rcp_f32_e32 v17, v0
	v_cvt_pk_bf16_f32 v0, v3, v2
	v_cvt_pk_bf16_f32 v2, v15, v14
	v_mov_b64_e32 v[14:15], s[4:5]
	v_cvt_pk_bf16_f32 v1, v13, v11
	v_mad_i64_i32 v[12:13], s[60:61], v12, s85, v[14:15]
	v_lshl_add_u64 v[12:13], v[4:5], 1, v[12:13]
	v_add_co_u32_e32 v12, vcc, 0x1286e000, v12
	v_cvt_pk_bf16_f32 v3, v17, v16
	s_nop 0
	v_addc_co_u32_e32 v13, vcc, 0, v13, vcc
	global_store_dwordx4 v[12:13], v[0:3], off offset:2560

; __device__ __forceinline__ u32x4 pack8(const float* v) { u32x4 w; w.x = pk2(v[0], v[1]); w.y = pk2(v[2], v[3]); w.z = pk2(v[4], v[5]); w.w = pk2(v[6], v[7]); return w; }
; __device__ __forceinline__ float sigmoidf_(float x) { return 1.f / (1.f + __expf(-x)); }
;     __device__ __forceinline__ void operator()(const f32x4 (&acc)[2][2][4][2], const pg8::Unit& u, int wr, int wc, int fr, int fq) const {
;     ...
;             } else {
; #pragma unroll
;                 for (int e = 0; e < 8; ++e) v[e] = sigmoidf_(v[e]);
;                 *(u32x4*)((bf16_t*)(ws + O_GATES) + (size_t)t * 3072 + (c0 - 2816)) = pack8(v);
.LBB0_1535:
	s_or_b64 exec, exec, s[0:1]
	s_and_saveexec_b64 s[0:1], s[96:97]
	s_xor_b64 s[44:45], exec, s[0:1]
	v_readlane_b32 s63, v254, 19
	s_movk_i32 s96, 0x100
	v_readlane_b32 s97, v254, 41
	s_cbranch_execz .LBB0_1580
	s_and_saveexec_b64 s[0:1], s[94:95]
	s_xor_b64 s[36:37], exec, s[0:1]
	s_cbranch_execz .LBB0_1577
	s_and_saveexec_b64 s[0:1], s[92:93]
	s_xor_b64 s[24:25], exec, s[0:1]
	s_cbranch_execz .LBB0_1566
	s_and_saveexec_b64 s[0:1], s[90:91]
	s_xor_b64 s[26:27], exec, s[0:1]
	s_cbranch_execz .LBB0_1561
	s_mov_b64 s[0:1], exec
	v_readlane_b32 s18, v252, 17
	v_readlane_b32 s19, v252, 18
	s_and_b64 s[18:19], s[0:1], s[18:19]
	s_xor_b64 s[0:1], s[18:19], s[0:1]
	s_mov_b64 exec, s[18:19]
	s_cbranch_execz .LBB0_1558
	s_mov_b64 s[46:47], exec
	v_readlane_b32 s18, v252, 23
	v_readlane_b32 s19, v252, 24
	s_and_b64 s[18:19], s[46:47], s[18:19]
	s_mov_b64 exec, s[18:19]
	s_cbranch_execz .LBB0_1557
	s_mov_b64 s[18:19], exec
	v_readlane_b32 s50, v252, 25
	v_readlane_b32 s51, v252, 26
	s_and_b64 s[50:51], s[18:19], s[50:51]
	s_xor_b64 s[18:19], s[50:51], s[18:19]
	s_mov_b64 exec, s[50:51]
	s_cbranch_execz .LBB0_1555
	s_mov_b64 s[50:51], exec
	v_readlane_b32 s52, v252, 27
	v_readlane_b32 s53, v252, 28
	s_and_b64 s[52:53], s[50:51], s[52:53]
	s_xor_b64 s[50:51], s[52:53], s[50:51]
	s_mov_b64 exec, s[52:53]
	s_cbranch_execz .LBB0_1552
	s_mov_b64 s[52:53], exec
	v_readlane_b32 s54, v252, 29
	v_readlane_b32 s55, v252, 30
	s_and_b64 s[54:55], s[52:53], s[54:55]
	s_xor_b64 s[52:53], s[54:55], s[52:53]
	s_mov_b64 exec, s[54:55]
	s_cbranch_execz .LBB0_1549
	s_mov_b64 s[54:55], exec
	v_readlane_b32 s56, v252, 31
	v_readlane_b32 s57, v252, 32
	s_and_b64 s[56:57], s[54:55], s[56:57]
	s_xor_b64 s[54:55], s[56:57], s[54:55]
	s_mov_b64 exec, s[56:57]
	s_cbranch_execz .LBB0_1546
	v_mul_f32_e32 v0, 0xbfb8aa3b, v52
	v_mul_f32_e32 v1, 0xbfb8aa3b, v53
	v_exp_f32_e32 v0, v0
	v_exp_f32_e32 v1, v1
	s_nop 0
	v_pk_add_f32 v[0:1], v[0:1], 1.0 op_sel_hi:[1,0]
	s_nop 0
	s_nop 0
	v_rcp_f32_e32 v2, v1
	s_nop 0
	v_rcp_f32_e32 v3, v0
	v_mul_f32_e32 v0, 0xbfb8aa3b, v54
	v_mul_f32_e32 v1, 0xbfb8aa3b, v55
	v_exp_f32_e32 v0, v0
	v_exp_f32_e32 v1, v1
	s_nop 0
	v_pk_add_f32 v[0:1], v[0:1], 1.0 op_sel_hi:[1,0]
	s_nop 0
	s_nop 0
	v_rcp_f32_e32 v6, v1
	s_nop 0
	v_rcp_f32_e32 v7, v0
	v_mul_f32_e32 v0, 0xbfb8aa3b, v48
	v_mul_f32_e32 v1, 0xbfb8aa3b, v49
	v_exp_f32_e32 v0, v0
	v_exp_f32_e32 v1, v1
	s_nop 0
	v_pk_add_f32 v[0:1], v[0:1], 1.0 op_sel_hi:[1,0]
	s_nop 0
	s_nop 0
	v_rcp_f32_e32 v9, v1
	s_nop 0
	v_rcp_f32_e32 v10, v0
	v_mul_f32_e32 v0, 0xbfb8aa3b, v50
	v_mul_f32_e32 v1, 0xbfb8aa3b, v51
	v_exp_f32_e32 v0, v0
	v_exp_f32_e32 v1, v1
	s_nop 0
	v_pk_add_f32 v[0:1], v[0:1], 1.0 op_sel_hi:[1,0]
	s_nop 0
	s_nop 0
	v_rcp_f32_e32 v11, v1
	s_nop 0
	v_rcp_f32_e32 v12, v0
	v_cvt_pk_bf16_f32 v1, v7, v6
	v_mov_b64_e32 v[6:7], s[4:5]
	v_mad_i64_i32 v[6:7], s[56:57], v8, s85, v[6:7]
	v_lshl_add_u64 v[4:5], v[4:5], 1, v[6:7]
	v_add_co_u32_e32 v4, vcc, 0x1286e000, v4
	v_cvt_pk_bf16_f32 v0, v3, v2
	v_cvt_pk_bf16_f32 v2, v10, v9
	v_cvt_pk_bf16_f32 v3, v12, v11
	v_addc_co_u32_e32 v5, vcc, 0, v5, vcc
	global_store_dwordx4 v[4:5], v[0:3], off offset:2560
